# v27: v23 without the lgkmcnt(8) wait that closed the first load segment of each K-step (the MMA block behind the barrier waits lgkmcnt(0) itself)
# baseline (speedup 1.0000x reference)
; #define PG8_STAGE(bufoff, gbase, voff) do { _Pragma("unroll") for (int _i = 0; _i < 2; ++_i) \
;         __builtin_amdgcn_global_load_lds((const unsigned*)((const char*)(gbase) + (voff)[_i]), (LAS unsigned*)(lds + (bufoff) + ldsw + _i * 8192), 16, 0, 0); } while (0)
; #define PG8_WAIT_V(n) asm volatile("s_waitcnt vmcnt(" #n ")" ::: "memory")
; #define PG8_BAR __builtin_amdgcn_s_barrier()
; template <class Epi, class Ptrs>
; __device__ __forceinline__ void gemm_phase(LAS unsigned char* lds, const int K, const StaticOrder& S, const Ptrs& P, const Epi& E) {
;     ...
;     for (int i = 0; i < 2; ++i) { int R, C; stage_rc(tid * 16 + i * 8192, R, C); const int Rb = (R & ~31) + perm32(R & 31);
;         voffA[i] = (unsigned)(R * K + C) * 2u; voffB[i] = (unsigned)(Rb * K + C) * 2u; }
;     const size_t kstep = (size_t)(BK * 2);
;     const size_t hstep = (size_t)HALF * K * 2;
;     const unsigned ldsw = (unsigned)wid * 1024u;
;     const int aoff = lds_byte(wr * 64 + fr, fq * 8), boff = lds_byte(wc * 32 + fr, fq * 8);
;     ...
;     PG8_STAGE(PG8_SB(0, 0), cB, voffB); PG8_STAGE(PG8_SA(0, 0), cA, voffA); PG8_STAGE(PG8_SB(0, 1), cB + hstep, voffB); PG8_STAGE(PG8_SA(0, 1), cA + hstep, voffA);
;     if (wr == 1) PG8_BAR;
;     PG8_WAIT_V(4); PG8_BAR;
;     PG8_STAGE(PG8_SB(1, 0), cB + kstep, voffB); PG8_STAGE(PG8_SA(1, 0), cA + kstep, voffA); PG8_STAGE(PG8_SB(1, 1), cB + hstep + kstep, voffB);
;     PG8_WAIT_V(6); PG8_BAR;
.LBB0_120:
	s_add_u32 s4, s28, 0x35000000
	s_addc_u32 s5, s29, 0
	s_mov_b64 s[58:59], 0x80
	v_writelane_b32 v254, s4, 0
	v_lshl_add_u64 v[6:7], v[6:7], 0, s[58:59]
	s_waitcnt vmcnt(4)
	s_barrier
	v_writelane_b32 v254, s5, 1
	s_add_u32 s4, s28, 0x26000000
	s_addc_u32 s5, s29, 0
	s_add_u32 s42, s28, 0x32000000
	s_addc_u32 s43, s29, 0
	s_add_u32 s44, s28, 0x2000000
	s_addc_u32 s45, s29, 0
	s_add_u32 s48, s26, 0xc000000
	s_addc_u32 s49, s27, 0
	s_add_u32 s54, s28, 0x3e000000
	s_addc_u32 s55, s29, 0
	s_add_u32 s56, s28, 0xe000000
	s_addc_u32 s57, s29, 0
	s_lshl_b32 s1, s1, 5
	s_and_b32 s88, s1, 0x60
	s_add_i32 m0, s67, 0x18000
	v_writelane_b32 v254, s4, 2
	s_ashr_i32 s86, s3, 31
	s_ashr_i32 s87, s2, 31
	s_lshl_b32 s20, s0, 13
	s_lshl_b32 s1, s88, 7
	global_load_lds_dwordx4 v[6:7], off
	v_lshl_add_u64 v[4:5], v[4:5], 0, s[58:59]
	s_add_i32 m0, s67, 0x1a000
	s_add_i32 s89, s67, 0x8000
	s_add_i32 s90, s67, 0xa000
	v_writelane_b32 v254, s5, 3
	global_load_lds_dwordx4 v[4:5], off
	v_lshl_add_u64 v[2:3], v[2:3], 0, s[58:59]
	s_mov_b32 m0, s89
	s_add_u32 s4, s78, 0x40080
	global_load_lds_dwordx4 v[2:3], off
	v_lshl_add_u64 v[0:1], v[0:1], 0, s[58:59]
	s_mov_b32 m0, s90
	s_addc_u32 s5, s79, 0
	global_load_lds_dwordx4 v[0:1], off
	s_add_i32 m0, s67, 0x1c000
	v_lshl_add_u64 v[0:1], s[4:5], 0, v[134:135]
	global_load_lds_dwordx4 v[0:1], off
	v_lshl_add_u64 v[0:1], s[4:5], 0, v[138:139]
	s_add_i32 m0, s67, 0x1e000
	v_lshlrev_b32_e32 v2, 6, v208
	global_load_lds_dwordx4 v[0:1], off
	v_and_b32_e32 v0, 15, v208
	v_lshlrev_b32_e32 v1, 1, v130
	s_movk_i32 s4, 0x3c0
	v_lshlrev_b32_e32 v3, 2, v208
	v_and_or_b32 v2, v2, s4, v1
	v_and_b32_e32 v3, 32, v3
	v_cmp_eq_u32_e64 s[10:11], 0, v0
	v_lshl_or_b32 v129, s0, 6, v0
	v_lshl_or_b32 v0, v0, 6, v1
	v_lshlrev_b32_e32 v1, 8, v208
	v_bitop3_b32 v131, s1, v2, v3 bitop3:0xf6
	v_and_b32_e32 v1, 0x38000, v1
	v_lshlrev_b32_e32 v2, 11, v10
	v_or3_b32 v1, v8, v1, v2
	v_add_u32_e32 v142, v1, v9
	v_lshlrev_b32_e32 v1, 4, v11
	s_waitcnt vmcnt(6)
	v_and_b32_e32 v1, 0x78000, v1
	v_bitop3_b32 v0, v0, s20, v3 bitop3:0xde
	v_or3_b32 v1, v8, v1, v2
	s_add_i32 s91, 0, 0x10000
	s_add_i32 s92, 0, 0x14000
	v_or_b32_e32 v204, s88, v130
	v_mov_b32_e32 v143, v141
	v_add_u32_e32 v144, v1, v9
	v_mov_b32_e32 v145, v141
	v_mov_b64_e32 v[146:147], 0x2100
	v_mov_b64_e32 v[148:149], 0x20ff
	v_add_u32_e32 v205, s91, v131
	v_add_u32_e32 v206, 0, v0
	v_add_u32_e32 v207, s92, v131
	s_mov_b32 s60, 0xbfb8aa3b
	s_lshl_b32 s62, s0, 2
	s_mov_b32 s64, 0x3dd2d3e7
	s_mov_b32 s66, 0xc0135761
	s_mov_b32 s93, 0x600000
	s_mov_b32 s94, 0x900000
	s_mov_b32 s95, 0x1800000
	s_mov_b32 s96, 0x1b00000
	s_mov_b32 s97, 0x1e00000
	s_mov_b32 s98, 0x2100000
	s_mov_b32 s99, 0x40000
	s_mov_b32 s22, 0x48000
	s_mov_b32 s23, 0x50000
	s_nop 0
	s_mov_b32 s24, 0
	s_cmpk_lt_u32 s61, 0x100
	s_cbranch_scc1 .Lsprio_0
	s_setprio 1

; #define PG8_STAGE(bufoff, gbase, voff) do { _Pragma("unroll") for (int _i = 0; _i < 2; ++_i) \
;         __builtin_amdgcn_global_load_lds((const unsigned*)((const char*)(gbase) + (voff)[_i]), (LAS unsigned*)(lds + (bufoff) + ldsw + _i * 8192), 16, 0, 0); } while (0)
; #define PG8_LDA(dst, b, h) do { _Pragma("unroll") for (int m = 0; m < 4; ++m) _Pragma("unroll") for (int k = 0; k < 2; ++k) dst[m][k] = *(const LAS bf16x8*)(lds + PG8_SA(b, h) + aoff + m * 2048 + k * 1024); } while (0)
; #define PG8_LDB(dst, b, h) do { _Pragma("unroll") for (int n = 0; n < 2; ++n) _Pragma("unroll") for (int k = 0; k < 2; ++k) dst[n][k] = *(const LAS bf16x8*)(lds + PG8_SB(b, h) + boff + n * 2048 + k * 1024); } while (0)
; #define PG8_MMA(ai, bj, At, Bt) do { __builtin_amdgcn_s_setprio(1); _Pragma("unroll") for (int m = 0; m < 4; ++m) _Pragma("unroll") for (int n = 0; n < 2; ++n) _Pragma("unroll") for (int k = 0; k < 2; ++k) \
;         acc[ai][bj][m][n] = __builtin_amdgcn_mfma_f32_16x16x32_bf16(Bt[n][k], At[m][k], acc[ai][bj][m][n], 0, 0, 0); __builtin_amdgcn_s_setprio(0); } while (0)
; #define PG8_WAIT_V(n) asm volatile("s_waitcnt vmcnt(" #n ")" ::: "memory")
; #define PG8_WAIT_L(n) asm volatile("s_waitcnt lgkmcnt(" #n ")" ::: "memory")
; template <class Epi, class Ptrs>
; __device__ __forceinline__ void gemm_phase(LAS unsigned char* lds, const int K, const StaticOrder& S, const Ptrs& P, const Epi& E) {
;     ...
;         for (int t = 0; t < nt; t += 2) {
;             const bool last = (t == nt - 2);
;             const char* a1 = cA + (size_t)(t + 1) * kstep;
;             const char* a2 = last ? nA : cA + (size_t)(t + 2) * kstep; const char* b2 = last ? nB : cB + (size_t)(t + 2) * kstep;
;             const char* a3 = a2 + kstep; const char* b3 = b2 + kstep;
;             PG8_LDB(B0, 0, 0); PG8_SCHED; PG8_LDA(At, 0, 0); PG8_STAGE(PG8_SA(1, 1), a1 + hstep, voffA);
;             PG8_WAIT_L(8); PG8_BAR; PG8_WAIT_L(0); PG8_MMA(0, 0, At, B0); PG8_BAR; PG8_SCHED;
;             PG8_LDB(B1, 0, 1); PG8_STAGE(PG8_SB(0, 0), b2, voffB);
;             PG8_BAR; PG8_WAIT_L(0); PG8_MMA(0, 1, At, B1); PG8_BAR;
;             PG8_LDA(At, 0, 1); PG8_STAGE(PG8_SA(0, 0), a2, voffA);
;             PG8_BAR; PG8_WAIT_L(0); PG8_MMA(1, 0, At, B0); PG8_BAR; PG8_SCHED;
;             PG8_STAGE(PG8_SB(0, 1), b2 + hstep, voffB);
;             PG8_WAIT_V(6); PG8_BAR; PG8_MMA(1, 1, At, B1); PG8_BAR;
.LBB0_126:
	s_add_u32 s6, s6, 0x40080
	s_addc_u32 s7, s7, 0
	s_add_u32 s20, s78, 0x100
	s_addc_u32 s25, s79, 0
	s_mov_b32 s63, -2
	v_add_u32_e32 v252, 0x18000, v131
	v_add_u32_e32 v253, 0x1c000, v131
	ds_read_b128 v[150:153], v205
	ds_read_b128 v[154:157], v205 offset:1024
	ds_read_b128 v[158:161], v205 offset:2048
	ds_read_b128 v[162:165], v205 offset:3072
	s_add_u32 s69, s6, 0xfffc0080
	s_addc_u32 s71, s7, -1
	s_cmp_eq_u32 s63, 12
	s_cselect_b32 s81, s1, s71
	s_cselect_b32 s80, s0, s69
	s_cselect_b32 s79, s73, s25
	s_cselect_b32 s78, s72, s20
	s_add_i32 m0, s67, 0xc000
	ds_read_b128 v[166:169], v206
	ds_read_b128 v[170:173], v206 offset:1024
	ds_read_b128 v[174:177], v206 offset:2048
	ds_read_b128 v[178:181], v206 offset:3072
	ds_read_b128 v[182:185], v206 offset:4096
	ds_read_b128 v[186:189], v206 offset:5120
	ds_read_b128 v[190:193], v206 offset:6144
	ds_read_b128 v[194:197], v206 offset:7168
	global_load_lds_dwordx4 v142, s[6:7]
	s_add_i32 m0, s67, 0xe000
	s_nop 0
	global_load_lds_dwordx4 v144, s[6:7]
	s_barrier
	s_waitcnt lgkmcnt(0)
	v_mfma_f32_16x16x32_bf16 v[120:123], v[150:153], v[166:169], 0
	v_mfma_f32_16x16x32_bf16 v[120:123], v[154:157], v[170:173], v[120:123]
	v_mfma_f32_16x16x32_bf16 v[116:119], v[162:165], v[170:173], 0
	v_mfma_f32_16x16x32_bf16 v[116:119], v[158:161], v[166:169], v[116:119]
	v_mfma_f32_16x16x32_bf16 v[100:103], v[158:161], v[174:177], 0
	v_mfma_f32_16x16x32_bf16 v[100:103], v[162:165], v[178:181], v[100:103]
	v_mfma_f32_16x16x32_bf16 v[104:107], v[154:157], v[178:181], 0
	v_mfma_f32_16x16x32_bf16 v[104:107], v[150:153], v[174:177], v[104:107]
	v_mfma_f32_16x16x32_bf16 v[88:91], v[150:153], v[182:185], 0
	v_mfma_f32_16x16x32_bf16 v[88:91], v[154:157], v[186:189], v[88:91]
	v_mfma_f32_16x16x32_bf16 v[84:87], v[162:165], v[186:189], 0
	v_mfma_f32_16x16x32_bf16 v[84:87], v[158:161], v[182:185], v[84:87]
	v_mfma_f32_16x16x32_bf16 v[68:71], v[158:161], v[190:193], 0
	v_mfma_f32_16x16x32_bf16 v[68:71], v[162:165], v[194:197], v[68:71]
	v_mfma_f32_16x16x32_bf16 v[72:75], v[154:157], v[194:197], 0
	v_mfma_f32_16x16x32_bf16 v[72:75], v[150:153], v[190:193], v[72:75]
	s_barrier
	s_add_i32 s69, s91, s65
	s_add_u32 s100, s78, 0x80
	s_addc_u32 s101, s79, 0
	s_mov_b32 m0, s69
	ds_read_b128 v[198:201], v207
	ds_read_b128 v[210:213], v207 offset:1024
	ds_read_b128 v[214:217], v207 offset:2048
	ds_read_b128 v[218:221], v207 offset:3072
	global_load_lds_dwordx4 v134, s[78:79]
	s_add_i32 m0, s69, 0x2000
	s_nop 0
	global_load_lds_dwordx4 v138, s[78:79]
	s_barrier
	s_waitcnt lgkmcnt(0)
	v_mfma_f32_16x16x32_bf16 v[124:127], v[198:201], v[166:169], 0
	v_mfma_f32_16x16x32_bf16 v[124:127], v[210:213], v[170:173], v[124:127]
	v_mfma_f32_16x16x32_bf16 v[112:115], v[218:221], v[170:173], 0
	v_mfma_f32_16x16x32_bf16 v[112:115], v[214:217], v[166:169], v[112:115]
	v_mfma_f32_16x16x32_bf16 v[96:99], v[214:217], v[174:177], 0
	v_mfma_f32_16x16x32_bf16 v[96:99], v[218:221], v[178:181], v[96:99]
	v_mfma_f32_16x16x32_bf16 v[108:111], v[210:213], v[178:181], 0
	v_mfma_f32_16x16x32_bf16 v[108:111], v[198:201], v[174:177], v[108:111]
	v_mfma_f32_16x16x32_bf16 v[92:95], v[198:201], v[182:185], 0
	v_mfma_f32_16x16x32_bf16 v[92:95], v[210:213], v[186:189], v[92:95]
	v_mfma_f32_16x16x32_bf16 v[80:83], v[218:221], v[186:189], 0
	v_mfma_f32_16x16x32_bf16 v[80:83], v[214:217], v[182:185], v[80:83]
	v_mfma_f32_16x16x32_bf16 v[64:67], v[214:217], v[190:193], 0
	v_mfma_f32_16x16x32_bf16 v[64:67], v[218:221], v[194:197], v[64:67]
	v_mfma_f32_16x16x32_bf16 v[76:79], v[210:213], v[194:197], 0
	v_mfma_f32_16x16x32_bf16 v[76:79], v[198:201], v[190:193], v[76:79]
	s_barrier
	s_mov_b32 m0, s67
	ds_read_b128 v[166:169], v206 offset:16384
	ds_read_b128 v[170:173], v206 offset:17408
	ds_read_b128 v[174:177], v206 offset:18432
	ds_read_b128 v[178:181], v206 offset:19456
	ds_read_b128 v[182:185], v206 offset:20480
	ds_read_b128 v[186:189], v206 offset:21504
	ds_read_b128 v[190:193], v206 offset:22528
	ds_read_b128 v[194:197], v206 offset:23552
	global_load_lds_dwordx4 v132, s[80:81]
	s_mov_b32 m0, s75
	s_nop 0
	global_load_lds_dwordx4 v136, s[80:81]
	s_barrier
	s_waitcnt lgkmcnt(0)
	v_mfma_f32_16x16x32_bf16 v[56:59], v[150:153], v[166:169], 0
	v_mfma_f32_16x16x32_bf16 v[56:59], v[154:157], v[170:173], v[56:59]
	v_mfma_f32_16x16x32_bf16 v[52:55], v[162:165], v[170:173], 0
	v_mfma_f32_16x16x32_bf16 v[52:55], v[158:161], v[166:169], v[52:55]
	v_mfma_f32_16x16x32_bf16 v[36:39], v[158:161], v[174:177], 0
	v_mfma_f32_16x16x32_bf16 v[36:39], v[162:165], v[178:181], v[36:39]
	v_mfma_f32_16x16x32_bf16 v[40:43], v[154:157], v[178:181], 0
	v_mfma_f32_16x16x32_bf16 v[40:43], v[150:153], v[174:177], v[40:43]
	v_mfma_f32_16x16x32_bf16 v[24:27], v[150:153], v[182:185], 0
	v_mfma_f32_16x16x32_bf16 v[24:27], v[154:157], v[186:189], v[24:27]
	v_mfma_f32_16x16x32_bf16 v[20:23], v[162:165], v[186:189], 0
	v_mfma_f32_16x16x32_bf16 v[20:23], v[158:161], v[182:185], v[20:23]
	v_mfma_f32_16x16x32_bf16 v[4:7], v[158:161], v[190:193], 0
	v_mfma_f32_16x16x32_bf16 v[4:7], v[162:165], v[194:197], v[4:7]
	v_mfma_f32_16x16x32_bf16 v[8:11], v[154:157], v[194:197], 0
	v_mfma_f32_16x16x32_bf16 v[8:11], v[150:153], v[190:193], v[8:11]
	s_barrier
	s_add_u32 s82, s78, 0x40000
	s_addc_u32 s83, s79, 0
	s_add_i32 s69, s92, s65
	s_mov_b32 m0, s69
	s_nop 0
	global_load_lds_dwordx4 v134, s[82:83]
	s_add_i32 m0, s69, 0x2000
	s_nop 0
	global_load_lds_dwordx4 v138, s[82:83]
	s_waitcnt vmcnt(6)
	s_barrier
; #define PG8_STAGE(bufoff, gbase, voff) do { _Pragma("unroll") for (int _i = 0; _i < 2; ++_i) \
;         __builtin_amdgcn_global_load_lds((const unsigned*)((const char*)(gbase) + (voff)[_i]), (LAS unsigned*)(lds + (bufoff) + ldsw + _i * 8192), 16, 0, 0); } while (0)
; #define PG8_LDA(dst, b, h) do { _Pragma("unroll") for (int m = 0; m < 4; ++m) _Pragma("unroll") for (int k = 0; k < 2; ++k) dst[m][k] = *(const LAS bf16x8*)(lds + PG8_SA(b, h) + aoff + m * 2048 + k * 1024); } while (0)
; #define PG8_LDB(dst, b, h) do { _Pragma("unroll") for (int n = 0; n < 2; ++n) _Pragma("unroll") for (int k = 0; k < 2; ++k) dst[n][k] = *(const LAS bf16x8*)(lds + PG8_SB(b, h) + boff + n * 2048 + k * 1024); } while (0)
; #define PG8_MMA(ai, bj, At, Bt) do { __builtin_amdgcn_s_setprio(1); _Pragma("unroll") for (int m = 0; m < 4; ++m) _Pragma("unroll") for (int n = 0; n < 2; ++n) _Pragma("unroll") for (int k = 0; k < 2; ++k) \
;         acc[ai][bj][m][n] = __builtin_amdgcn_mfma_f32_16x16x32_bf16(Bt[n][k], At[m][k], acc[ai][bj][m][n], 0, 0, 0); __builtin_amdgcn_s_setprio(0); } while (0)
; #define PG8_WAIT_V(n) asm volatile("s_waitcnt vmcnt(" #n ")" ::: "memory")
; #define PG8_WAIT_L(n) asm volatile("s_waitcnt lgkmcnt(" #n ")" ::: "memory")
; #define PG8_BAR __builtin_amdgcn_s_barrier()
; #define PG8_SCHED __builtin_amdgcn_sched_barrier(0)
; template <class Epi, class Ptrs>
; __device__ __forceinline__ void gemm_phase(LAS unsigned char* lds, const int K, const StaticOrder& S, const Ptrs& P, const Epi& E) {
;     ...
;             PG8_WAIT_V(6); PG8_BAR; PG8_MMA(1, 1, At, B1); PG8_BAR;
;             PG8_LDB(B0, 1, 0); PG8_SCHED; PG8_LDA(At, 1, 0); PG8_STAGE(PG8_SA(0, 1), a2 + hstep, voffA);
;             PG8_WAIT_L(8); PG8_BAR; PG8_WAIT_L(0); PG8_MMA(0, 0, At, B0); PG8_BAR; PG8_SCHED;
;             PG8_LDB(B1, 1, 1); PG8_STAGE(PG8_SB(1, 0), b3, voffB);
;             PG8_BAR; PG8_WAIT_L(0); PG8_MMA(0, 1, At, B1); PG8_BAR;
;             PG8_LDA(At, 1, 1); PG8_STAGE(PG8_SA(1, 0), a3, voffA);
;             PG8_BAR; PG8_WAIT_L(0); PG8_MMA(1, 0, At, B0); PG8_BAR; PG8_SCHED;
	v_mfma_f32_16x16x32_bf16 v[60:63], v[198:201], v[166:169], 0
	v_mfma_f32_16x16x32_bf16 v[60:63], v[210:213], v[170:173], v[60:63]
	v_mfma_f32_16x16x32_bf16 v[48:51], v[218:221], v[170:173], 0
	v_mfma_f32_16x16x32_bf16 v[48:51], v[214:217], v[166:169], v[48:51]
	v_mfma_f32_16x16x32_bf16 v[32:35], v[214:217], v[174:177], 0
	v_mfma_f32_16x16x32_bf16 v[32:35], v[218:221], v[178:181], v[32:35]
	v_mfma_f32_16x16x32_bf16 v[44:47], v[210:213], v[178:181], 0
	v_mfma_f32_16x16x32_bf16 v[44:47], v[198:201], v[174:177], v[44:47]
	v_mfma_f32_16x16x32_bf16 v[28:31], v[198:201], v[182:185], 0
	v_mfma_f32_16x16x32_bf16 v[28:31], v[210:213], v[186:189], v[28:31]
	v_mfma_f32_16x16x32_bf16 v[16:19], v[218:221], v[186:189], 0
	v_mfma_f32_16x16x32_bf16 v[16:19], v[214:217], v[182:185], v[16:19]
	v_mfma_f32_16x16x32_bf16 v[0:3], v[214:217], v[190:193], 0
	v_mfma_f32_16x16x32_bf16 v[0:3], v[218:221], v[194:197], v[0:3]
	v_mfma_f32_16x16x32_bf16 v[12:15], v[210:213], v[194:197], 0
	v_mfma_f32_16x16x32_bf16 v[12:15], v[198:201], v[190:193], v[12:15]
	s_barrier
	s_add_i32 s69, 0, 0x18000
	ds_read_b128 v[150:153], v252
	ds_read_b128 v[154:157], v252 offset:1024
	ds_read_b128 v[158:161], v252 offset:2048
	ds_read_b128 v[162:165], v252 offset:3072
	s_add_u32 s80, s80, 0x40000
	s_addc_u32 s81, s81, 0
	s_mov_b32 m0, s77
	ds_read_b128 v[166:169], v206 offset:32768
	ds_read_b128 v[170:173], v206 offset:33792
	ds_read_b128 v[174:177], v206 offset:34816
	ds_read_b128 v[178:181], v206 offset:35840
	ds_read_b128 v[182:185], v206 offset:36864
	ds_read_b128 v[186:189], v206 offset:37888
	ds_read_b128 v[190:193], v206 offset:38912
	ds_read_b128 v[194:197], v206 offset:39936
	global_load_lds_dwordx4 v132, s[80:81]
	s_mov_b32 m0, s85
	s_nop 0
	global_load_lds_dwordx4 v136, s[80:81]
	s_barrier
	s_waitcnt lgkmcnt(0)
	v_mfma_f32_16x16x32_bf16 v[120:123], v[150:153], v[166:169], v[120:123]
	v_mfma_f32_16x16x32_bf16 v[120:123], v[154:157], v[170:173], v[120:123]
	v_mfma_f32_16x16x32_bf16 v[116:119], v[162:165], v[170:173], v[116:119]
	v_mfma_f32_16x16x32_bf16 v[116:119], v[158:161], v[166:169], v[116:119]
	v_mfma_f32_16x16x32_bf16 v[100:103], v[158:161], v[174:177], v[100:103]
	v_mfma_f32_16x16x32_bf16 v[100:103], v[162:165], v[178:181], v[100:103]
	v_mfma_f32_16x16x32_bf16 v[104:107], v[154:157], v[178:181], v[104:107]
	v_mfma_f32_16x16x32_bf16 v[104:107], v[150:153], v[174:177], v[104:107]
	v_mfma_f32_16x16x32_bf16 v[88:91], v[150:153], v[182:185], v[88:91]
	v_mfma_f32_16x16x32_bf16 v[88:91], v[154:157], v[186:189], v[88:91]
	v_mfma_f32_16x16x32_bf16 v[84:87], v[162:165], v[186:189], v[84:87]
	v_mfma_f32_16x16x32_bf16 v[84:87], v[158:161], v[182:185], v[84:87]
	v_mfma_f32_16x16x32_bf16 v[68:71], v[158:161], v[190:193], v[68:71]
	v_mfma_f32_16x16x32_bf16 v[68:71], v[162:165], v[194:197], v[68:71]
	v_mfma_f32_16x16x32_bf16 v[72:75], v[154:157], v[194:197], v[72:75]
	v_mfma_f32_16x16x32_bf16 v[72:75], v[150:153], v[190:193], v[72:75]
	s_barrier
	s_add_i32 s71, 0, 0x1c000
	s_add_i32 s69, s69, s65
	s_mov_b32 m0, s69
	ds_read_b128 v[198:201], v253
	ds_read_b128 v[210:213], v253 offset:1024
	ds_read_b128 v[214:217], v253 offset:2048
	ds_read_b128 v[218:221], v253 offset:3072
	global_load_lds_dwordx4 v134, s[100:101]
	s_add_i32 m0, s69, 0x2000
	s_nop 0
	global_load_lds_dwordx4 v138, s[100:101]
	s_barrier
	s_waitcnt lgkmcnt(0)
	v_mfma_f32_16x16x32_bf16 v[124:127], v[198:201], v[166:169], v[124:127]
	v_mfma_f32_16x16x32_bf16 v[124:127], v[210:213], v[170:173], v[124:127]
	v_mfma_f32_16x16x32_bf16 v[112:115], v[218:221], v[170:173], v[112:115]
	v_mfma_f32_16x16x32_bf16 v[112:115], v[214:217], v[166:169], v[112:115]
	v_mfma_f32_16x16x32_bf16 v[96:99], v[214:217], v[174:177], v[96:99]
	v_mfma_f32_16x16x32_bf16 v[96:99], v[218:221], v[178:181], v[96:99]
	v_mfma_f32_16x16x32_bf16 v[108:111], v[210:213], v[178:181], v[108:111]
	v_mfma_f32_16x16x32_bf16 v[108:111], v[198:201], v[174:177], v[108:111]
	v_mfma_f32_16x16x32_bf16 v[92:95], v[198:201], v[182:185], v[92:95]
	v_mfma_f32_16x16x32_bf16 v[92:95], v[210:213], v[186:189], v[92:95]
	v_mfma_f32_16x16x32_bf16 v[80:83], v[218:221], v[186:189], v[80:83]
	v_mfma_f32_16x16x32_bf16 v[80:83], v[214:217], v[182:185], v[80:83]
	v_mfma_f32_16x16x32_bf16 v[64:67], v[214:217], v[190:193], v[64:67]
	v_mfma_f32_16x16x32_bf16 v[64:67], v[218:221], v[194:197], v[64:67]
	v_mfma_f32_16x16x32_bf16 v[76:79], v[210:213], v[194:197], v[76:79]
	v_mfma_f32_16x16x32_bf16 v[76:79], v[198:201], v[190:193], v[76:79]
	s_barrier
	s_mov_b32 m0, s89
	s_add_u32 s100, s80, 0xfffc0080
	s_addc_u32 s101, s81, -1
	ds_read_b128 v[166:169], v206 offset:49152
	ds_read_b128 v[170:173], v206 offset:50176
	ds_read_b128 v[174:177], v206 offset:51200
	ds_read_b128 v[178:181], v206 offset:52224
	ds_read_b128 v[182:185], v206 offset:53248
	ds_read_b128 v[186:189], v206 offset:54272
	ds_read_b128 v[190:193], v206 offset:55296
	ds_read_b128 v[194:197], v206 offset:56320
	global_load_lds_dwordx4 v132, s[100:101]
	s_mov_b32 m0, s90
	s_nop 0
	global_load_lds_dwordx4 v136, s[100:101]
	s_barrier
	s_waitcnt lgkmcnt(0)
	v_mfma_f32_16x16x32_bf16 v[56:59], v[150:153], v[166:169], v[56:59]
	v_mfma_f32_16x16x32_bf16 v[56:59], v[154:157], v[170:173], v[56:59]
	v_mfma_f32_16x16x32_bf16 v[52:55], v[162:165], v[170:173], v[52:55]
	v_mfma_f32_16x16x32_bf16 v[52:55], v[158:161], v[166:169], v[52:55]
	v_mfma_f32_16x16x32_bf16 v[36:39], v[158:161], v[174:177], v[36:39]
	v_mfma_f32_16x16x32_bf16 v[36:39], v[162:165], v[178:181], v[36:39]
	v_mfma_f32_16x16x32_bf16 v[40:43], v[154:157], v[178:181], v[40:43]
	v_mfma_f32_16x16x32_bf16 v[40:43], v[150:153], v[174:177], v[40:43]
	v_mfma_f32_16x16x32_bf16 v[24:27], v[150:153], v[182:185], v[24:27]
	v_mfma_f32_16x16x32_bf16 v[24:27], v[154:157], v[186:189], v[24:27]
	v_mfma_f32_16x16x32_bf16 v[20:23], v[162:165], v[186:189], v[20:23]
	v_mfma_f32_16x16x32_bf16 v[20:23], v[158:161], v[182:185], v[20:23]
	v_mfma_f32_16x16x32_bf16 v[4:7], v[158:161], v[190:193], v[4:7]
	v_mfma_f32_16x16x32_bf16 v[4:7], v[162:165], v[194:197], v[4:7]
	v_mfma_f32_16x16x32_bf16 v[8:11], v[154:157], v[194:197], v[8:11]
	v_mfma_f32_16x16x32_bf16 v[8:11], v[150:153], v[190:193], v[8:11]
	s_barrier
; #define PG8_STAGE(bufoff, gbase, voff) do { _Pragma("unroll") for (int _i = 0; _i < 2; ++_i) \
;         __builtin_amdgcn_global_load_lds((const unsigned*)((const char*)(gbase) + (voff)[_i]), (LAS unsigned*)(lds + (bufoff) + ldsw + _i * 8192), 16, 0, 0); } while (0)
; #define PG8_LDA(dst, b, h) do { _Pragma("unroll") for (int m = 0; m < 4; ++m) _Pragma("unroll") for (int k = 0; k < 2; ++k) dst[m][k] = *(const LAS bf16x8*)(lds + PG8_SA(b, h) + aoff + m * 2048 + k * 1024); } while (0)
; #define PG8_LDB(dst, b, h) do { _Pragma("unroll") for (int n = 0; n < 2; ++n) _Pragma("unroll") for (int k = 0; k < 2; ++k) dst[n][k] = *(const LAS bf16x8*)(lds + PG8_SB(b, h) + boff + n * 2048 + k * 1024); } while (0)
; #define PG8_MMA(ai, bj, At, Bt) do { __builtin_amdgcn_s_setprio(1); _Pragma("unroll") for (int m = 0; m < 4; ++m) _Pragma("unroll") for (int n = 0; n < 2; ++n) _Pragma("unroll") for (int k = 0; k < 2; ++k) \
;         acc[ai][bj][m][n] = __builtin_amdgcn_mfma_f32_16x16x32_bf16(Bt[n][k], At[m][k], acc[ai][bj][m][n], 0, 0, 0); __builtin_amdgcn_s_setprio(0); } while (0)
; #define PG8_WAIT_V(n) asm volatile("s_waitcnt vmcnt(" #n ")" ::: "memory")
; #define PG8_WAIT_L(n) asm volatile("s_waitcnt lgkmcnt(" #n ")" ::: "memory")
; #define PG8_BAR __builtin_amdgcn_s_barrier()
; #define PG8_SCHED __builtin_amdgcn_sched_barrier(0)
; template <class Epi, class Ptrs>
; __device__ __forceinline__ void gemm_phase(LAS unsigned char* lds, const int K, const StaticOrder& S, const Ptrs& P, const Epi& E) {
;     ...
;             PG8_LDB(B0, 0, 0); PG8_SCHED; PG8_LDA(At, 0, 0); PG8_STAGE(PG8_SA(1, 1), a1 + hstep, voffA);
;             PG8_WAIT_L(8); PG8_BAR; PG8_WAIT_L(0); PG8_MMA(0, 0, At, B0); PG8_BAR; PG8_SCHED;
;             PG8_LDB(B1, 0, 1); PG8_STAGE(PG8_SB(0, 0), b2, voffB);
;             PG8_BAR; PG8_WAIT_L(0); PG8_MMA(0, 1, At, B1); PG8_BAR;
;             PG8_LDA(At, 0, 1); PG8_STAGE(PG8_SA(0, 0), a2, voffA);
;     ...
;             PG8_STAGE(PG8_SB(1, 1), b3 + hstep, voffB);
;             PG8_WAIT_V(6); PG8_BAR; PG8_MMA(1, 1, At, B1); PG8_BAR;
	s_add_u32 s78, s78, 0x40080
	s_addc_u32 s79, s79, 0
	s_add_i32 s69, s71, s65
	s_mov_b32 m0, s69
	s_nop 0
	global_load_lds_dwordx4 v134, s[78:79]
	s_add_i32 m0, s69, 0x2000
	s_nop 0
	global_load_lds_dwordx4 v138, s[78:79]
	s_waitcnt vmcnt(6)
	s_barrier
	v_mfma_f32_16x16x32_bf16 v[60:63], v[198:201], v[166:169], v[60:63]
	v_mfma_f32_16x16x32_bf16 v[60:63], v[210:213], v[170:173], v[60:63]
	v_mfma_f32_16x16x32_bf16 v[48:51], v[218:221], v[170:173], v[48:51]
	v_mfma_f32_16x16x32_bf16 v[48:51], v[214:217], v[166:169], v[48:51]
	v_mfma_f32_16x16x32_bf16 v[32:35], v[214:217], v[174:177], v[32:35]
	v_mfma_f32_16x16x32_bf16 v[32:35], v[218:221], v[178:181], v[32:35]
	v_mfma_f32_16x16x32_bf16 v[44:47], v[210:213], v[178:181], v[44:47]
	v_mfma_f32_16x16x32_bf16 v[44:47], v[198:201], v[174:177], v[44:47]
	v_mfma_f32_16x16x32_bf16 v[28:31], v[198:201], v[182:185], v[28:31]
	v_mfma_f32_16x16x32_bf16 v[28:31], v[210:213], v[186:189], v[28:31]
	v_mfma_f32_16x16x32_bf16 v[16:19], v[218:221], v[186:189], v[16:19]
	v_mfma_f32_16x16x32_bf16 v[16:19], v[214:217], v[182:185], v[16:19]
	v_mfma_f32_16x16x32_bf16 v[0:3], v[214:217], v[190:193], v[0:3]
	v_mfma_f32_16x16x32_bf16 v[0:3], v[218:221], v[194:197], v[0:3]
	v_mfma_f32_16x16x32_bf16 v[12:15], v[210:213], v[194:197], v[12:15]
	v_mfma_f32_16x16x32_bf16 v[12:15], v[198:201], v[190:193], v[12:15]
	s_barrier
	s_add_i32 s63, s63, 2
	s_add_u32 s6, s6, 0x100
	s_addc_u32 s7, s7, 0
	s_add_u32 s20, s20, 0x100
	s_addc_u32 s25, s25, 0
	s_cmp_gt_u32 s63, 13
.LBB0_127:
	ds_read_b128 v[150:153], v205
	ds_read_b128 v[154:157], v205 offset:1024
	ds_read_b128 v[158:161], v205 offset:2048
	ds_read_b128 v[162:165], v205 offset:3072
	s_add_u32 s69, s6, 0xfffc0080
	s_addc_u32 s71, s7, -1
	s_cmp_eq_u32 s63, 12
	s_cselect_b32 s81, s1, s71
	s_cselect_b32 s80, s0, s69
	s_cselect_b32 s79, s73, s25
	s_cselect_b32 s78, s72, s20
	s_add_i32 m0, s67, 0xc000
	ds_read_b128 v[166:169], v206
	ds_read_b128 v[170:173], v206 offset:1024
	ds_read_b128 v[174:177], v206 offset:2048
	ds_read_b128 v[178:181], v206 offset:3072
	ds_read_b128 v[182:185], v206 offset:4096
	ds_read_b128 v[186:189], v206 offset:5120
	ds_read_b128 v[190:193], v206 offset:6144
	ds_read_b128 v[194:197], v206 offset:7168
	global_load_lds_dwordx4 v142, s[6:7]
	s_add_i32 m0, s67, 0xe000
	s_nop 0
	global_load_lds_dwordx4 v144, s[6:7]
	s_barrier
	s_waitcnt lgkmcnt(0)
	v_mfma_f32_16x16x32_bf16 v[120:123], v[150:153], v[166:169], v[120:123]
	v_mfma_f32_16x16x32_bf16 v[120:123], v[154:157], v[170:173], v[120:123]
	v_mfma_f32_16x16x32_bf16 v[116:119], v[162:165], v[170:173], v[116:119]
	v_mfma_f32_16x16x32_bf16 v[116:119], v[158:161], v[166:169], v[116:119]
	v_mfma_f32_16x16x32_bf16 v[100:103], v[158:161], v[174:177], v[100:103]
	v_mfma_f32_16x16x32_bf16 v[100:103], v[162:165], v[178:181], v[100:103]
	v_mfma_f32_16x16x32_bf16 v[104:107], v[154:157], v[178:181], v[104:107]
	v_mfma_f32_16x16x32_bf16 v[104:107], v[150:153], v[174:177], v[104:107]
	v_mfma_f32_16x16x32_bf16 v[88:91], v[150:153], v[182:185], v[88:91]
	v_mfma_f32_16x16x32_bf16 v[88:91], v[154:157], v[186:189], v[88:91]
	v_mfma_f32_16x16x32_bf16 v[84:87], v[162:165], v[186:189], v[84:87]
	v_mfma_f32_16x16x32_bf16 v[84:87], v[158:161], v[182:185], v[84:87]
	v_mfma_f32_16x16x32_bf16 v[68:71], v[158:161], v[190:193], v[68:71]
	v_mfma_f32_16x16x32_bf16 v[68:71], v[162:165], v[194:197], v[68:71]
	v_mfma_f32_16x16x32_bf16 v[72:75], v[154:157], v[194:197], v[72:75]
	v_mfma_f32_16x16x32_bf16 v[72:75], v[150:153], v[190:193], v[72:75]
	s_barrier
	s_add_i32 s69, s91, s65
	s_add_u32 s100, s78, 0x80
	s_addc_u32 s101, s79, 0
	s_mov_b32 m0, s69
	ds_read_b128 v[198:201], v207
	ds_read_b128 v[210:213], v207 offset:1024
	ds_read_b128 v[214:217], v207 offset:2048
	ds_read_b128 v[218:221], v207 offset:3072
	global_load_lds_dwordx4 v134, s[78:79]
	s_add_i32 m0, s69, 0x2000
	s_nop 0
	global_load_lds_dwordx4 v138, s[78:79]
	s_barrier
	s_waitcnt lgkmcnt(0)
	v_mfma_f32_16x16x32_bf16 v[124:127], v[198:201], v[166:169], v[124:127]
	v_mfma_f32_16x16x32_bf16 v[124:127], v[210:213], v[170:173], v[124:127]
	v_mfma_f32_16x16x32_bf16 v[112:115], v[218:221], v[170:173], v[112:115]
	v_mfma_f32_16x16x32_bf16 v[112:115], v[214:217], v[166:169], v[112:115]
	v_mfma_f32_16x16x32_bf16 v[96:99], v[214:217], v[174:177], v[96:99]
	v_mfma_f32_16x16x32_bf16 v[96:99], v[218:221], v[178:181], v[96:99]
	v_mfma_f32_16x16x32_bf16 v[108:111], v[210:213], v[178:181], v[108:111]
	v_mfma_f32_16x16x32_bf16 v[108:111], v[198:201], v[174:177], v[108:111]
	v_mfma_f32_16x16x32_bf16 v[92:95], v[198:201], v[182:185], v[92:95]
	v_mfma_f32_16x16x32_bf16 v[92:95], v[210:213], v[186:189], v[92:95]
	v_mfma_f32_16x16x32_bf16 v[80:83], v[218:221], v[186:189], v[80:83]
	v_mfma_f32_16x16x32_bf16 v[80:83], v[214:217], v[182:185], v[80:83]
	v_mfma_f32_16x16x32_bf16 v[64:67], v[214:217], v[190:193], v[64:67]
	v_mfma_f32_16x16x32_bf16 v[64:67], v[218:221], v[194:197], v[64:67]
	v_mfma_f32_16x16x32_bf16 v[76:79], v[210:213], v[194:197], v[76:79]
	v_mfma_f32_16x16x32_bf16 v[76:79], v[198:201], v[190:193], v[76:79]
	s_barrier
	s_mov_b32 m0, s67
	ds_read_b128 v[166:169], v206 offset:16384
	ds_read_b128 v[170:173], v206 offset:17408
	ds_read_b128 v[174:177], v206 offset:18432
	ds_read_b128 v[178:181], v206 offset:19456
	ds_read_b128 v[182:185], v206 offset:20480
	ds_read_b128 v[186:189], v206 offset:21504
	ds_read_b128 v[190:193], v206 offset:22528
	ds_read_b128 v[194:197], v206 offset:23552
	global_load_lds_dwordx4 v132, s[80:81]
	s_mov_b32 m0, s75
	s_nop 0
	global_load_lds_dwordx4 v136, s[80:81]
	s_barrier
; #define PG8_STAGE(bufoff, gbase, voff) do { _Pragma("unroll") for (int _i = 0; _i < 2; ++_i) \
;         __builtin_amdgcn_global_load_lds((const unsigned*)((const char*)(gbase) + (voff)[_i]), (LAS unsigned*)(lds + (bufoff) + ldsw + _i * 8192), 16, 0, 0); } while (0)
; #define PG8_LDA(dst, b, h) do { _Pragma("unroll") for (int m = 0; m < 4; ++m) _Pragma("unroll") for (int k = 0; k < 2; ++k) dst[m][k] = *(const LAS bf16x8*)(lds + PG8_SA(b, h) + aoff + m * 2048 + k * 1024); } while (0)
; #define PG8_LDB(dst, b, h) do { _Pragma("unroll") for (int n = 0; n < 2; ++n) _Pragma("unroll") for (int k = 0; k < 2; ++k) dst[n][k] = *(const LAS bf16x8*)(lds + PG8_SB(b, h) + boff + n * 2048 + k * 1024); } while (0)
; #define PG8_MMA(ai, bj, At, Bt) do { __builtin_amdgcn_s_setprio(1); _Pragma("unroll") for (int m = 0; m < 4; ++m) _Pragma("unroll") for (int n = 0; n < 2; ++n) _Pragma("unroll") for (int k = 0; k < 2; ++k) \
;         acc[ai][bj][m][n] = __builtin_amdgcn_mfma_f32_16x16x32_bf16(Bt[n][k], At[m][k], acc[ai][bj][m][n], 0, 0, 0); __builtin_amdgcn_s_setprio(0); } while (0)
; #define PG8_WAIT_V(n) asm volatile("s_waitcnt vmcnt(" #n ")" ::: "memory")
; #define PG8_WAIT_L(n) asm volatile("s_waitcnt lgkmcnt(" #n ")" ::: "memory")
; #define PG8_BAR __builtin_amdgcn_s_barrier()
; #define PG8_SCHED __builtin_amdgcn_sched_barrier(0)
; template <class Epi, class Ptrs>
; __device__ __forceinline__ void gemm_phase(LAS unsigned char* lds, const int K, const StaticOrder& S, const Ptrs& P, const Epi& E) {
;     ...
;             PG8_BAR; PG8_WAIT_L(0); PG8_MMA(1, 0, At, B0); PG8_BAR; PG8_SCHED;
;             PG8_STAGE(PG8_SB(0, 1), b2 + hstep, voffB);
;             PG8_WAIT_V(6); PG8_BAR; PG8_MMA(1, 1, At, B1); PG8_BAR;
;             PG8_LDB(B0, 1, 0); PG8_SCHED; PG8_LDA(At, 1, 0); PG8_STAGE(PG8_SA(0, 1), a2 + hstep, voffA);
;             PG8_WAIT_L(8); PG8_BAR; PG8_WAIT_L(0); PG8_MMA(0, 0, At, B0); PG8_BAR; PG8_SCHED;
;             PG8_LDB(B1, 1, 1); PG8_STAGE(PG8_SB(1, 0), b3, voffB);
	s_waitcnt lgkmcnt(0)
	v_mfma_f32_16x16x32_bf16 v[56:59], v[150:153], v[166:169], v[56:59]
	v_mfma_f32_16x16x32_bf16 v[56:59], v[154:157], v[170:173], v[56:59]
	v_mfma_f32_16x16x32_bf16 v[52:55], v[162:165], v[170:173], v[52:55]
	v_mfma_f32_16x16x32_bf16 v[52:55], v[158:161], v[166:169], v[52:55]
	v_mfma_f32_16x16x32_bf16 v[36:39], v[158:161], v[174:177], v[36:39]
	v_mfma_f32_16x16x32_bf16 v[36:39], v[162:165], v[178:181], v[36:39]
	v_mfma_f32_16x16x32_bf16 v[40:43], v[154:157], v[178:181], v[40:43]
	v_mfma_f32_16x16x32_bf16 v[40:43], v[150:153], v[174:177], v[40:43]
	v_mfma_f32_16x16x32_bf16 v[24:27], v[150:153], v[182:185], v[24:27]
	v_mfma_f32_16x16x32_bf16 v[24:27], v[154:157], v[186:189], v[24:27]
	v_mfma_f32_16x16x32_bf16 v[20:23], v[162:165], v[186:189], v[20:23]
	v_mfma_f32_16x16x32_bf16 v[20:23], v[158:161], v[182:185], v[20:23]
	v_mfma_f32_16x16x32_bf16 v[4:7], v[158:161], v[190:193], v[4:7]
	v_mfma_f32_16x16x32_bf16 v[4:7], v[162:165], v[194:197], v[4:7]
	v_mfma_f32_16x16x32_bf16 v[8:11], v[154:157], v[194:197], v[8:11]
	v_mfma_f32_16x16x32_bf16 v[8:11], v[150:153], v[190:193], v[8:11]
	s_barrier
	s_add_u32 s82, s78, 0x40000
	s_addc_u32 s83, s79, 0
	s_add_i32 s69, s92, s65
	s_mov_b32 m0, s69
	s_nop 0
	global_load_lds_dwordx4 v134, s[82:83]
	s_add_i32 m0, s69, 0x2000
	s_nop 0
	global_load_lds_dwordx4 v138, s[82:83]
	s_waitcnt vmcnt(6)
	s_barrier
	v_mfma_f32_16x16x32_bf16 v[60:63], v[198:201], v[166:169], v[60:63]
	v_mfma_f32_16x16x32_bf16 v[60:63], v[210:213], v[170:173], v[60:63]
	v_mfma_f32_16x16x32_bf16 v[48:51], v[218:221], v[170:173], v[48:51]
	v_mfma_f32_16x16x32_bf16 v[48:51], v[214:217], v[166:169], v[48:51]
	v_mfma_f32_16x16x32_bf16 v[32:35], v[214:217], v[174:177], v[32:35]
	v_mfma_f32_16x16x32_bf16 v[32:35], v[218:221], v[178:181], v[32:35]
	v_mfma_f32_16x16x32_bf16 v[44:47], v[210:213], v[178:181], v[44:47]
	v_mfma_f32_16x16x32_bf16 v[44:47], v[198:201], v[174:177], v[44:47]
	v_mfma_f32_16x16x32_bf16 v[28:31], v[198:201], v[182:185], v[28:31]
	v_mfma_f32_16x16x32_bf16 v[28:31], v[210:213], v[186:189], v[28:31]
	v_mfma_f32_16x16x32_bf16 v[16:19], v[218:221], v[186:189], v[16:19]
	v_mfma_f32_16x16x32_bf16 v[16:19], v[214:217], v[182:185], v[16:19]
	v_mfma_f32_16x16x32_bf16 v[0:3], v[214:217], v[190:193], v[0:3]
	v_mfma_f32_16x16x32_bf16 v[0:3], v[218:221], v[194:197], v[0:3]
	v_mfma_f32_16x16x32_bf16 v[12:15], v[210:213], v[194:197], v[12:15]
	v_mfma_f32_16x16x32_bf16 v[12:15], v[198:201], v[190:193], v[12:15]
	s_barrier
	s_add_i32 s69, 0, 0x18000
	ds_read_b128 v[150:153], v252
	ds_read_b128 v[154:157], v252 offset:1024
	ds_read_b128 v[158:161], v252 offset:2048
	ds_read_b128 v[162:165], v252 offset:3072
	s_add_u32 s80, s80, 0x40000
	s_addc_u32 s81, s81, 0
	s_mov_b32 m0, s77
	ds_read_b128 v[166:169], v206 offset:32768
	ds_read_b128 v[170:173], v206 offset:33792
	ds_read_b128 v[174:177], v206 offset:34816
	ds_read_b128 v[178:181], v206 offset:35840
	ds_read_b128 v[182:185], v206 offset:36864
	ds_read_b128 v[186:189], v206 offset:37888
	ds_read_b128 v[190:193], v206 offset:38912
	ds_read_b128 v[194:197], v206 offset:39936
	global_load_lds_dwordx4 v132, s[80:81]
	s_mov_b32 m0, s85
	s_nop 0
	global_load_lds_dwordx4 v136, s[80:81]
	s_barrier
	s_waitcnt lgkmcnt(0)
	v_mfma_f32_16x16x32_bf16 v[120:123], v[150:153], v[166:169], v[120:123]
	v_mfma_f32_16x16x32_bf16 v[120:123], v[154:157], v[170:173], v[120:123]
	v_mfma_f32_16x16x32_bf16 v[116:119], v[162:165], v[170:173], v[116:119]
	v_mfma_f32_16x16x32_bf16 v[116:119], v[158:161], v[166:169], v[116:119]
	v_mfma_f32_16x16x32_bf16 v[100:103], v[158:161], v[174:177], v[100:103]
	v_mfma_f32_16x16x32_bf16 v[100:103], v[162:165], v[178:181], v[100:103]
	v_mfma_f32_16x16x32_bf16 v[104:107], v[154:157], v[178:181], v[104:107]
	v_mfma_f32_16x16x32_bf16 v[104:107], v[150:153], v[174:177], v[104:107]
	v_mfma_f32_16x16x32_bf16 v[88:91], v[150:153], v[182:185], v[88:91]
	v_mfma_f32_16x16x32_bf16 v[88:91], v[154:157], v[186:189], v[88:91]
	v_mfma_f32_16x16x32_bf16 v[84:87], v[162:165], v[186:189], v[84:87]
	v_mfma_f32_16x16x32_bf16 v[84:87], v[158:161], v[182:185], v[84:87]
	v_mfma_f32_16x16x32_bf16 v[68:71], v[158:161], v[190:193], v[68:71]
	v_mfma_f32_16x16x32_bf16 v[68:71], v[162:165], v[194:197], v[68:71]
	v_mfma_f32_16x16x32_bf16 v[72:75], v[154:157], v[194:197], v[72:75]
	v_mfma_f32_16x16x32_bf16 v[72:75], v[150:153], v[190:193], v[72:75]
	s_barrier
	s_add_i32 s71, 0, 0x1c000
	s_add_i32 s69, s69, s65
	s_mov_b32 m0, s69
	ds_read_b128 v[198:201], v253
	ds_read_b128 v[210:213], v253 offset:1024
	ds_read_b128 v[214:217], v253 offset:2048
	ds_read_b128 v[218:221], v253 offset:3072
	global_load_lds_dwordx4 v134, s[100:101]
	s_add_i32 m0, s69, 0x2000
	s_nop 0
	global_load_lds_dwordx4 v138, s[100:101]
	s_barrier
; #define PG8_WAIT_V(n) asm volatile("s_waitcnt vmcnt(" #n ")" ::: "memory")
; template <class Epi, class Ptrs>
; __device__ __forceinline__ void gemm_phase(LAS unsigned char* lds, const int K, const StaticOrder& S, const Ptrs& P, const Epi& E) {
;     ...
;             PG8_BAR; PG8_WAIT_L(0); PG8_MMA(0, 1, At, B1); PG8_BAR;
;             PG8_LDA(At, 1, 1); PG8_STAGE(PG8_SA(1, 0), a3, voffA);
;             PG8_BAR; PG8_WAIT_L(0); PG8_MMA(1, 0, At, B0); PG8_BAR; PG8_SCHED;
;             PG8_STAGE(PG8_SB(1, 1), b3 + hstep, voffB);
;             PG8_WAIT_V(6); PG8_BAR; PG8_MMA(1, 1, At, B1); PG8_BAR;
;     __device__ __forceinline__ void operator()(const f32x4 (&acc)[2][2][4][2], const Unit& u, int ui, int wr, int wc, int fr, int fq) const {
;         const int pn = u.pn;
;         if (pn < 8) {
;             bf16_t* base = (bf16_t*)(ws + WS_U) + (size_t)(u.pm * 256 + wr * 64 + fr) * DM + pn * 128 + wc * 32 + 8 * fq;
; #pragma unroll
;             for (int ai = 0; ai < 2; ++ai)
; #pragma unroll
;                 for (int m = 0; m < 4; ++m) {
;                     const f32x4 g0 = g1_4(acc[ai][0][m][0], acc[ai][1][m][0]), g1 = g1_4(acc[ai][0][m][1], acc[ai][1][m][1]);
;                     *(u32x4*)(base + (size_t)(ai * 128 + m * 16) * DM) = pack8(g0, g1); }
;             return; }
;         if (pn >= 17 && pn < 21) {
;             bf16_t* base = (bf16_t*)(dout + DO_GVT) + (size_t)((pn - 17) * 256 + wr * 64 + fr) * MTOK + u.pm * 256 + wc * 32 + 8 * fq;
;             float* pp = (float*)(ws + WS_PART) + (size_t)(u.pm * 256 + wc * 32 + 8 * fq) * 8 + (pn - 17) * 2 + wr;
; #pragma unroll
;             for (int bj = 0; bj < 2; ++bj) { f32x4 sq0 = {0.f, 0.f, 0.f, 0.f}, sq1 = {0.f, 0.f, 0.f, 0.f};
; #pragma unroll
;                 for (int ai = 0; ai < 2; ++ai)
; #pragma unroll
;                     for (int m = 0; m < 4; ++m) { const f32x4 g0 = gelu4(acc[ai][bj][m][0]), g1 = gelu4(acc[ai][bj][m][1]);
;                         sq0 += g0 * g0; sq1 += g1 * g1;
;                         *(u32x4*)(base + (size_t)(ai * 128 + m * 16) * MTOK + bj * 128) = pack8(g0, g1); }
; #pragma unroll
;                 for (int j = 0; j < 4; ++j) { const float t0 = row16_sum(sq0[j]), t1 = row16_sum(sq1[j]); if (fr == 0) { pp[(size_t)(bj * 128 + j) * 8] = t0; pp[(size_t)(bj * 128 + 4 + j) * 8] = t1; } } }
;             return; }
;         bf16_t* base; size_t ld; int row0, col0, act;
	s_waitcnt lgkmcnt(0)
	v_mfma_f32_16x16x32_bf16 v[124:127], v[198:201], v[166:169], v[124:127]
	v_mfma_f32_16x16x32_bf16 v[124:127], v[210:213], v[170:173], v[124:127]
	v_mfma_f32_16x16x32_bf16 v[112:115], v[218:221], v[170:173], v[112:115]
	v_mfma_f32_16x16x32_bf16 v[112:115], v[214:217], v[166:169], v[112:115]
	v_mfma_f32_16x16x32_bf16 v[96:99], v[214:217], v[174:177], v[96:99]
	v_mfma_f32_16x16x32_bf16 v[96:99], v[218:221], v[178:181], v[96:99]
	v_mfma_f32_16x16x32_bf16 v[108:111], v[210:213], v[178:181], v[108:111]
	v_mfma_f32_16x16x32_bf16 v[108:111], v[198:201], v[174:177], v[108:111]
	v_mfma_f32_16x16x32_bf16 v[92:95], v[198:201], v[182:185], v[92:95]
	v_mfma_f32_16x16x32_bf16 v[92:95], v[210:213], v[186:189], v[92:95]
	v_mfma_f32_16x16x32_bf16 v[80:83], v[218:221], v[186:189], v[80:83]
	v_mfma_f32_16x16x32_bf16 v[80:83], v[214:217], v[182:185], v[80:83]
	v_mfma_f32_16x16x32_bf16 v[64:67], v[214:217], v[190:193], v[64:67]
	v_mfma_f32_16x16x32_bf16 v[64:67], v[218:221], v[194:197], v[64:67]
	v_mfma_f32_16x16x32_bf16 v[76:79], v[210:213], v[194:197], v[76:79]
	v_mfma_f32_16x16x32_bf16 v[76:79], v[198:201], v[190:193], v[76:79]
	s_barrier
	s_mov_b32 m0, s89
	s_add_u32 s100, s80, 0xfffc0080
	s_addc_u32 s101, s81, -1
	ds_read_b128 v[166:169], v206 offset:49152
	ds_read_b128 v[170:173], v206 offset:50176
	ds_read_b128 v[174:177], v206 offset:51200
	ds_read_b128 v[178:181], v206 offset:52224
	ds_read_b128 v[182:185], v206 offset:53248
	ds_read_b128 v[186:189], v206 offset:54272
	ds_read_b128 v[190:193], v206 offset:55296
	ds_read_b128 v[194:197], v206 offset:56320
	global_load_lds_dwordx4 v132, s[100:101]
	s_mov_b32 m0, s90
	s_nop 0
	global_load_lds_dwordx4 v136, s[100:101]
	s_barrier
	s_waitcnt lgkmcnt(0)
	v_mfma_f32_16x16x32_bf16 v[56:59], v[150:153], v[166:169], v[56:59]
	v_mfma_f32_16x16x32_bf16 v[56:59], v[154:157], v[170:173], v[56:59]
	v_mfma_f32_16x16x32_bf16 v[52:55], v[162:165], v[170:173], v[52:55]
	v_mfma_f32_16x16x32_bf16 v[52:55], v[158:161], v[166:169], v[52:55]
	v_mfma_f32_16x16x32_bf16 v[36:39], v[158:161], v[174:177], v[36:39]
	v_mfma_f32_16x16x32_bf16 v[36:39], v[162:165], v[178:181], v[36:39]
	v_mfma_f32_16x16x32_bf16 v[40:43], v[154:157], v[178:181], v[40:43]
	v_mfma_f32_16x16x32_bf16 v[40:43], v[150:153], v[174:177], v[40:43]
	v_mfma_f32_16x16x32_bf16 v[24:27], v[150:153], v[182:185], v[24:27]
	v_mfma_f32_16x16x32_bf16 v[24:27], v[154:157], v[186:189], v[24:27]
	v_mfma_f32_16x16x32_bf16 v[20:23], v[162:165], v[186:189], v[20:23]
	v_mfma_f32_16x16x32_bf16 v[20:23], v[158:161], v[182:185], v[20:23]
	v_mfma_f32_16x16x32_bf16 v[4:7], v[158:161], v[190:193], v[4:7]
	v_mfma_f32_16x16x32_bf16 v[4:7], v[162:165], v[194:197], v[4:7]
	v_mfma_f32_16x16x32_bf16 v[8:11], v[154:157], v[194:197], v[8:11]
	v_mfma_f32_16x16x32_bf16 v[8:11], v[150:153], v[190:193], v[8:11]
	s_barrier
	s_add_u32 s78, s78, 0x40080
	s_addc_u32 s79, s79, 0
	s_add_i32 s69, s71, s65
	s_mov_b32 m0, s69
	s_nop 0
	global_load_lds_dwordx4 v134, s[78:79]
	s_add_i32 m0, s69, 0x2000
	s_nop 0
	global_load_lds_dwordx4 v138, s[78:79]
	s_waitcnt vmcnt(6)
	s_barrier
	v_mfma_f32_16x16x32_bf16 v[60:63], v[198:201], v[166:169], v[60:63]
	v_mfma_f32_16x16x32_bf16 v[60:63], v[210:213], v[170:173], v[60:63]
	v_mfma_f32_16x16x32_bf16 v[48:51], v[218:221], v[170:173], v[48:51]
	v_mfma_f32_16x16x32_bf16 v[48:51], v[214:217], v[166:169], v[48:51]
	v_mfma_f32_16x16x32_bf16 v[32:35], v[214:217], v[174:177], v[32:35]
	v_mfma_f32_16x16x32_bf16 v[32:35], v[218:221], v[178:181], v[32:35]
	v_mfma_f32_16x16x32_bf16 v[44:47], v[210:213], v[178:181], v[44:47]
	v_mfma_f32_16x16x32_bf16 v[44:47], v[198:201], v[174:177], v[44:47]
	v_mfma_f32_16x16x32_bf16 v[28:31], v[198:201], v[182:185], v[28:31]
	v_mfma_f32_16x16x32_bf16 v[28:31], v[210:213], v[186:189], v[28:31]
	v_mfma_f32_16x16x32_bf16 v[16:19], v[218:221], v[186:189], v[16:19]
	v_mfma_f32_16x16x32_bf16 v[16:19], v[214:217], v[182:185], v[16:19]
	v_mfma_f32_16x16x32_bf16 v[0:3], v[214:217], v[190:193], v[0:3]
	v_mfma_f32_16x16x32_bf16 v[0:3], v[218:221], v[194:197], v[0:3]
	v_mfma_f32_16x16x32_bf16 v[12:15], v[210:213], v[194:197], v[12:15]
	v_mfma_f32_16x16x32_bf16 v[12:15], v[198:201], v[190:193], v[12:15]
	s_barrier
	s_add_i32 s63, s63, 2
	s_add_u32 s6, s6, 0x100
	s_addc_u32 s7, s7, 0
	s_add_u32 s20, s20, 0x100
	s_addc_u32 s25, s25, 0
	s_cmp_gt_u32 s63, 13
	s_cbranch_scc0 .LBB0_127
	s_cmp_gt_i32 s74, 7
	s_mov_b64 s[6:7], -1
	s_cbranch_scc0 .LBB0_188
	s_sub_i32 s25, s74, 17
	s_cmp_gt_u32 s25, 3
	s_cbranch_scc0 .LBB0_170
	s_lshl_b32 s69, s76, 8
	s_cmp_gt_u32 s74, 11
	s_cbranch_scc0 .LBB0_135
	s_cmp_eq_u32 s74, 12
	s_mov_b64 s[6:7], 0
	s_cbranch_scc1 .LBB0_134
	s_cmp_gt_u32 s74, 16
	s_cbranch_scc1 .LBB0_191
	s_lshl_b32 s20, s74, 8
	v_readlane_b32 s80, v254, 2
	s_addk_i32 s20, 0xf300
	s_mov_b64 s[78:79], 0x400
	s_mov_b64 s[82:83], -1
	s_mov_b32 s63, s69
	v_readlane_b32 s81, v254, 3
	s_andn2_b64 vcc, exec, s[6:7]
	s_cbranch_vccz .LBB0_136
	s_branch .LBB0_137

; __device__ __forceinline__ unsigned xb_ld(unsigned* p)              { return __hip_atomic_load(p, __ATOMIC_RELAXED, __HIP_MEMORY_SCOPE_AGENT); }
; __device__ __forceinline__ unsigned xb_add(unsigned* p, unsigned v) { return __hip_atomic_fetch_add(p, v, __ATOMIC_RELAXED, __HIP_MEMORY_SCOPE_AGENT); }
; __device__ __forceinline__ void xcd_barrier_complete(unsigned* bar, unsigned x, unsigned& nloc, unsigned& nx) {
;     const unsigned G = gridDim.x * gridDim.y * gridDim.z;
;     unsigned sum, cnt, mine, sp = 0u;
;     for (;;) {
;         sum = 0u; cnt = 0u; mine = 0u;
; #pragma unroll
;         for (unsigned j = 0; j < 16; ++j) { const unsigned c = xb_ld(&bar[XB_XCNT(j)]); sum += c; cnt += (c > 0u) ? 1u : 0u; mine = (j == x) ? c : mine; }
; __device__ __forceinline__ void xcd_barrier(const XcdBarrier& b) {
;     asm volatile("s_waitcnt vmcnt(0)" ::: "memory");
;     __syncthreads();
;     if (threadIdx.x == 0) {
;         unsigned* bar = b.bar;
;         __builtin_amdgcn_s_waitcnt(0);
;         unsigned nloc = b.st[0], nx = b.st[1];
;         if (nloc == 0u) { xcd_barrier_complete(bar, b.x, nloc, nx); b.st[0] = nloc; b.st[1] = nx; }
;         const unsigned old = xb_add(&bar[XB_XSUB(b.x)], 1u);
.LBB0_195:
	s_nop 0
	s_nop 0
	s_nop 0
	s_nop 0
	s_nop 0
	s_nop 0
	s_nop 0
	s_nop 0
	s_nop 0
	s_nop 0
	s_nop 0
	s_nop 0
	s_nop 0
	s_nop 0
	s_nop 0
	s_nop 0
	s_nop 0
	s_nop 0
	s_nop 0
	s_nop 0
	s_nop 0
	s_nop 0
	s_nop 0
	s_nop 0
	s_nop 0
	s_nop 0
	s_nop 0
	s_nop 0
	s_nop 0
	s_nop 0
	s_nop 0
	s_nop 0
	s_nop 0
	s_nop 0
	s_nop 0
	s_nop 0
	s_cmp_gt_i32 s31, 2
	s_cselect_b64 s[0:1], -1, 0
	s_and_b64 s[4:5], s[18:19], s[0:1]
	s_andn2_b64 vcc, exec, s[4:5]
	s_cbranch_vccnz .LBB0_245
	s_waitcnt vmcnt(0)
	s_waitcnt vmcnt(0) lgkmcnt(0)
	s_barrier
	s_and_saveexec_b64 s[4:5], s[8:9]
	s_cbranch_execz .LBB0_244
	s_add_i32 s6, 0, 0x25ff0
	v_mov_b32_e32 v0, s6
	s_waitcnt vmcnt(0) expcnt(0) lgkmcnt(0)
	ds_read_b32 v2, v0
	s_add_i32 s6, 0, 0x25ff4
	v_mov_b32_e32 v0, s6
	ds_read_b32 v0, v0
	s_waitcnt lgkmcnt(1)
	v_cmp_ne_u32_e32 vcc, 0, v2
	s_cbranch_vccnz .LBB0_212
	s_load_dwordx2 s[18:19], s[52:53], 0x4
	s_add_u32 s6, s28, 0x3e800200
	s_addc_u32 s7, s29, 0
	s_add_u32 s10, s28, 0x3e800400
	s_addc_u32 s11, s29, 0
	s_waitcnt lgkmcnt(0)
	s_mul_i32 s76, s18, s3
	s_add_u32 s18, s28, 0x3e800500
	s_mul_i32 s76, s76, s19
	s_addc_u32 s19, s29, 0
	s_add_u32 s20, s28, 0x3e800600
	s_addc_u32 s21, s29, 0
	s_add_u32 s22, s28, 0x3e800700
	s_addc_u32 s23, s29, 0
	s_add_u32 s24, s28, 0x3e800800
	s_addc_u32 s25, s29, 0
	s_add_u32 s42, s28, 0x3e800900
	s_addc_u32 s43, s29, 0
	s_add_u32 s44, s28, 0x3e800a00
	s_addc_u32 s45, s29, 0
	s_add_u32 s48, s28, 0x3e800b00
	s_addc_u32 s49, s29, 0
	s_add_u32 s54, s28, 0x3e800c00
	s_addc_u32 s55, s29, 0
	s_add_u32 s56, s28, 0x3e800d00
	s_addc_u32 s57, s29, 0
	s_add_u32 s58, s28, 0x3e800e00
	s_addc_u32 s59, s29, 0
	s_add_u32 s60, s28, 0x3e800f00
	s_addc_u32 s61, s29, 0
	s_add_u32 s62, s28, 0x3e801000
	s_addc_u32 s63, s29, 0
	s_add_u32 s64, s28, 0x3e801100
	s_addc_u32 s65, s29, 0
	s_add_u32 s66, s28, 0x3e801200
	s_addc_u32 s67, s29, 0
	s_add_u32 s68, s28, 0x3e801300
	s_addc_u32 s69, s29, 0
	s_mov_b32 s77, 1
	v_mov_b32_e32 v16, 0
	s_branch .LBB0_200

; #define PG8_STAGE(bufoff, gbase, voff) do { _Pragma("unroll") for (int _i = 0; _i < 2; ++_i) \
;         __builtin_amdgcn_global_load_lds((const unsigned*)((const char*)(gbase) + (voff)[_i]), (LAS unsigned*)(lds + (bufoff) + ldsw + _i * 8192), 16, 0, 0); } while (0)
; #define PG8_LDA(dst, b, h) do { _Pragma("unroll") for (int m = 0; m < 4; ++m) _Pragma("unroll") for (int k = 0; k < 2; ++k) dst[m][k] = *(const LAS bf16x8*)(lds + PG8_SA(b, h) + aoff + m * 2048 + k * 1024); } while (0)
; #define PG8_LDB(dst, b, h) do { _Pragma("unroll") for (int n = 0; n < 2; ++n) _Pragma("unroll") for (int k = 0; k < 2; ++k) dst[n][k] = *(const LAS bf16x8*)(lds + PG8_SB(b, h) + boff + n * 2048 + k * 1024); } while (0)
; #define PG8_MMA(ai, bj, At, Bt) do { __builtin_amdgcn_s_setprio(1); _Pragma("unroll") for (int m = 0; m < 4; ++m) _Pragma("unroll") for (int n = 0; n < 2; ++n) _Pragma("unroll") for (int k = 0; k < 2; ++k) \
;         acc[ai][bj][m][n] = __builtin_amdgcn_mfma_f32_16x16x32_bf16(Bt[n][k], At[m][k], acc[ai][bj][m][n], 0, 0, 0); __builtin_amdgcn_s_setprio(0); } while (0)
; #define PG8_WAIT_V(n) asm volatile("s_waitcnt vmcnt(" #n ")" ::: "memory")
; #define PG8_WAIT_L(n) asm volatile("s_waitcnt lgkmcnt(" #n ")" ::: "memory")
; template <class Epi, class Ptrs>
; __device__ __forceinline__ void gemm_phase(LAS unsigned char* lds, const int K, const StaticOrder& S, const Ptrs& P, const Epi& E) {
;     ...
;         for (int t = 0; t < nt; t += 2) {
;             const bool last = (t == nt - 2);
;             const char* a1 = cA + (size_t)(t + 1) * kstep;
;             const char* a2 = last ? nA : cA + (size_t)(t + 2) * kstep; const char* b2 = last ? nB : cB + (size_t)(t + 2) * kstep;
;             const char* a3 = a2 + kstep; const char* b3 = b2 + kstep;
;             PG8_LDB(B0, 0, 0); PG8_SCHED; PG8_LDA(At, 0, 0); PG8_STAGE(PG8_SA(1, 1), a1 + hstep, voffA);
;             PG8_WAIT_L(8); PG8_BAR; PG8_WAIT_L(0); PG8_MMA(0, 0, At, B0); PG8_BAR; PG8_SCHED;
;             PG8_LDB(B1, 0, 1); PG8_STAGE(PG8_SB(0, 0), b2, voffB);
;             PG8_BAR; PG8_WAIT_L(0); PG8_MMA(0, 1, At, B1); PG8_BAR;
;             PG8_LDA(At, 0, 1); PG8_STAGE(PG8_SA(0, 0), a2, voffA);
;             PG8_BAR; PG8_WAIT_L(0); PG8_MMA(1, 0, At, B0); PG8_BAR; PG8_SCHED;
;             PG8_STAGE(PG8_SB(0, 1), b2 + hstep, voffB);
;             PG8_WAIT_V(6); PG8_BAR; PG8_MMA(1, 1, At, B1); PG8_BAR;
.LBB0_352:
	s_add_u32 s38, s44, 0x40080
	s_addc_u32 s39, s45, 0
	s_add_u32 s21, s42, 0x100
	s_addc_u32 s23, s43, 0
	s_mov_b32 s41, -2
	v_add_u32_e32 v252, 0x18000, v205
	v_add_u32_e32 v253, 0x1c000, v205
	ds_read_b128 v[128:131], v207
	ds_read_b128 v[132:135], v207 offset:1024
	ds_read_b128 v[136:139], v207 offset:2048
	ds_read_b128 v[140:143], v207 offset:3072
	s_add_u32 s42, s38, 0xfffc0080
	s_addc_u32 s43, s39, -1
	s_cmp_eq_u32 s41, 12
	s_cselect_b32 s45, s1, s43
	s_cselect_b32 s44, s0, s42
	s_cselect_b32 s43, s25, s23
	s_cselect_b32 s42, s24, s21
	s_add_i32 m0, s54, 0xc000
	ds_read_b128 v[144:147], v209
	ds_read_b128 v[148:151], v209 offset:1024
	ds_read_b128 v[152:155], v209 offset:2048
	ds_read_b128 v[156:159], v209 offset:3072
	ds_read_b128 v[160:163], v209 offset:4096
	ds_read_b128 v[164:167], v209 offset:5120
	ds_read_b128 v[168:171], v209 offset:6144
	ds_read_b128 v[172:175], v209 offset:7168
	global_load_lds_dwordx4 v184, s[38:39]
	s_add_i32 m0, s54, 0xe000
	s_nop 0
	global_load_lds_dwordx4 v186, s[38:39]
	s_barrier
	s_waitcnt lgkmcnt(0)
	v_mfma_f32_16x16x32_bf16 v[124:127], v[128:131], v[144:147], 0
	v_mfma_f32_16x16x32_bf16 v[124:127], v[132:135], v[148:151], v[124:127]
	v_mfma_f32_16x16x32_bf16 v[120:123], v[140:143], v[148:151], 0
	v_mfma_f32_16x16x32_bf16 v[120:123], v[136:139], v[144:147], v[120:123]
	v_mfma_f32_16x16x32_bf16 v[104:107], v[136:139], v[152:155], 0
	v_mfma_f32_16x16x32_bf16 v[104:107], v[140:143], v[156:159], v[104:107]
	v_mfma_f32_16x16x32_bf16 v[108:111], v[132:135], v[156:159], 0
	v_mfma_f32_16x16x32_bf16 v[108:111], v[128:131], v[152:155], v[108:111]
	v_mfma_f32_16x16x32_bf16 v[92:95], v[128:131], v[160:163], 0
	v_mfma_f32_16x16x32_bf16 v[92:95], v[132:135], v[164:167], v[92:95]
	v_mfma_f32_16x16x32_bf16 v[88:91], v[140:143], v[164:167], 0
	v_mfma_f32_16x16x32_bf16 v[88:91], v[136:139], v[160:163], v[88:91]
	v_mfma_f32_16x16x32_bf16 v[72:75], v[136:139], v[168:171], 0
	v_mfma_f32_16x16x32_bf16 v[72:75], v[140:143], v[172:175], v[72:75]
	v_mfma_f32_16x16x32_bf16 v[76:79], v[132:135], v[172:175], 0
	v_mfma_f32_16x16x32_bf16 v[76:79], v[128:131], v[168:171], v[76:79]
	s_barrier
	s_add_i32 s69, s66, s51
	s_add_u32 s90, s42, 0x80
	s_addc_u32 s91, s43, 0
	s_mov_b32 m0, s69
	ds_read_b128 v[192:195], v210
	ds_read_b128 v[196:199], v210 offset:1024
	ds_read_b128 v[200:203], v210 offset:2048
	ds_read_b128 v[212:215], v210 offset:3072
	global_load_lds_dwordx4 v178, s[42:43]
	s_add_i32 m0, s69, 0x2000
	s_nop 0
	global_load_lds_dwordx4 v182, s[42:43]
	s_barrier
	s_waitcnt lgkmcnt(0)
	v_mfma_f32_16x16x32_bf16 v[116:119], v[192:195], v[144:147], 0
	v_mfma_f32_16x16x32_bf16 v[116:119], v[196:199], v[148:151], v[116:119]
	v_mfma_f32_16x16x32_bf16 v[112:115], v[212:215], v[148:151], 0
	v_mfma_f32_16x16x32_bf16 v[112:115], v[200:203], v[144:147], v[112:115]
	v_mfma_f32_16x16x32_bf16 v[96:99], v[200:203], v[152:155], 0
	v_mfma_f32_16x16x32_bf16 v[96:99], v[212:215], v[156:159], v[96:99]
	v_mfma_f32_16x16x32_bf16 v[100:103], v[196:199], v[156:159], 0
	v_mfma_f32_16x16x32_bf16 v[100:103], v[192:195], v[152:155], v[100:103]
	v_mfma_f32_16x16x32_bf16 v[84:87], v[192:195], v[160:163], 0
	v_mfma_f32_16x16x32_bf16 v[84:87], v[196:199], v[164:167], v[84:87]
	v_mfma_f32_16x16x32_bf16 v[80:83], v[212:215], v[164:167], 0
	v_mfma_f32_16x16x32_bf16 v[80:83], v[200:203], v[160:163], v[80:83]
	v_mfma_f32_16x16x32_bf16 v[64:67], v[200:203], v[168:171], 0
	v_mfma_f32_16x16x32_bf16 v[64:67], v[212:215], v[172:175], v[64:67]
	v_mfma_f32_16x16x32_bf16 v[68:71], v[196:199], v[172:175], 0
	v_mfma_f32_16x16x32_bf16 v[68:71], v[192:195], v[168:171], v[68:71]
	s_barrier
	s_mov_b32 m0, s54
	s_add_u32 s92, s44, 0x80
	s_addc_u32 s93, s45, 0
	ds_read_b128 v[144:147], v209 offset:16384
	ds_read_b128 v[148:151], v209 offset:17408
	ds_read_b128 v[152:155], v209 offset:18432
	ds_read_b128 v[156:159], v209 offset:19456
	ds_read_b128 v[160:163], v209 offset:20480
	ds_read_b128 v[164:167], v209 offset:21504
	ds_read_b128 v[168:171], v209 offset:22528
	ds_read_b128 v[172:175], v209 offset:23552
	global_load_lds_dwordx4 v176, s[44:45]
	s_mov_b32 m0, s55
	s_nop 0
	global_load_lds_dwordx4 v180, s[44:45]
	s_barrier
	s_waitcnt lgkmcnt(0)
	v_mfma_f32_16x16x32_bf16 v[60:63], v[128:131], v[144:147], 0
	v_mfma_f32_16x16x32_bf16 v[60:63], v[132:135], v[148:151], v[60:63]
	v_mfma_f32_16x16x32_bf16 v[56:59], v[140:143], v[148:151], 0
	v_mfma_f32_16x16x32_bf16 v[56:59], v[136:139], v[144:147], v[56:59]
	v_mfma_f32_16x16x32_bf16 v[40:43], v[136:139], v[152:155], 0
	v_mfma_f32_16x16x32_bf16 v[40:43], v[140:143], v[156:159], v[40:43]
	v_mfma_f32_16x16x32_bf16 v[44:47], v[132:135], v[156:159], 0
	v_mfma_f32_16x16x32_bf16 v[44:47], v[128:131], v[152:155], v[44:47]
	v_mfma_f32_16x16x32_bf16 v[28:31], v[128:131], v[160:163], 0
	v_mfma_f32_16x16x32_bf16 v[28:31], v[132:135], v[164:167], v[28:31]
	v_mfma_f32_16x16x32_bf16 v[24:27], v[140:143], v[164:167], 0
	v_mfma_f32_16x16x32_bf16 v[24:27], v[136:139], v[160:163], v[24:27]
	v_mfma_f32_16x16x32_bf16 v[8:11], v[136:139], v[168:171], 0
	v_mfma_f32_16x16x32_bf16 v[8:11], v[140:143], v[172:175], v[8:11]
	v_mfma_f32_16x16x32_bf16 v[12:15], v[132:135], v[172:175], 0
	v_mfma_f32_16x16x32_bf16 v[12:15], v[128:131], v[168:171], v[12:15]
	s_barrier
	s_add_u32 s70, s42, 0x40000
	s_addc_u32 s71, s43, 0
	s_add_i32 s69, s67, s51
	s_mov_b32 m0, s69
	s_nop 0
	global_load_lds_dwordx4 v178, s[70:71]
	s_add_i32 m0, s69, 0x2000
	s_nop 0
	global_load_lds_dwordx4 v182, s[70:71]
	s_waitcnt vmcnt(6)
	s_barrier
; #define PG8_STAGE(bufoff, gbase, voff) do { _Pragma("unroll") for (int _i = 0; _i < 2; ++_i) \
;         __builtin_amdgcn_global_load_lds((const unsigned*)((const char*)(gbase) + (voff)[_i]), (LAS unsigned*)(lds + (bufoff) + ldsw + _i * 8192), 16, 0, 0); } while (0)
; #define PG8_LDA(dst, b, h) do { _Pragma("unroll") for (int m = 0; m < 4; ++m) _Pragma("unroll") for (int k = 0; k < 2; ++k) dst[m][k] = *(const LAS bf16x8*)(lds + PG8_SA(b, h) + aoff + m * 2048 + k * 1024); } while (0)
; #define PG8_LDB(dst, b, h) do { _Pragma("unroll") for (int n = 0; n < 2; ++n) _Pragma("unroll") for (int k = 0; k < 2; ++k) dst[n][k] = *(const LAS bf16x8*)(lds + PG8_SB(b, h) + boff + n * 2048 + k * 1024); } while (0)
; #define PG8_MMA(ai, bj, At, Bt) do { __builtin_amdgcn_s_setprio(1); _Pragma("unroll") for (int m = 0; m < 4; ++m) _Pragma("unroll") for (int n = 0; n < 2; ++n) _Pragma("unroll") for (int k = 0; k < 2; ++k) \
;         acc[ai][bj][m][n] = __builtin_amdgcn_mfma_f32_16x16x32_bf16(Bt[n][k], At[m][k], acc[ai][bj][m][n], 0, 0, 0); __builtin_amdgcn_s_setprio(0); } while (0)
; #define PG8_WAIT_V(n) asm volatile("s_waitcnt vmcnt(" #n ")" ::: "memory")
; #define PG8_WAIT_L(n) asm volatile("s_waitcnt lgkmcnt(" #n ")" ::: "memory")
; #define PG8_BAR __builtin_amdgcn_s_barrier()
; #define PG8_SCHED __builtin_amdgcn_sched_barrier(0)
; template <class Epi, class Ptrs>
; __device__ __forceinline__ void gemm_phase(LAS unsigned char* lds, const int K, const StaticOrder& S, const Ptrs& P, const Epi& E) {
;     ...
;             PG8_WAIT_V(6); PG8_BAR; PG8_MMA(1, 1, At, B1); PG8_BAR;
;             PG8_LDB(B0, 1, 0); PG8_SCHED; PG8_LDA(At, 1, 0); PG8_STAGE(PG8_SA(0, 1), a2 + hstep, voffA);
;             PG8_WAIT_L(8); PG8_BAR; PG8_WAIT_L(0); PG8_MMA(0, 0, At, B0); PG8_BAR; PG8_SCHED;
;             PG8_LDB(B1, 1, 1); PG8_STAGE(PG8_SB(1, 0), b3, voffB);
;             PG8_BAR; PG8_WAIT_L(0); PG8_MMA(0, 1, At, B1); PG8_BAR;
;             PG8_LDA(At, 1, 1); PG8_STAGE(PG8_SA(1, 0), a3, voffA);
;             PG8_BAR; PG8_WAIT_L(0); PG8_MMA(1, 0, At, B0); PG8_BAR; PG8_SCHED;
	v_mfma_f32_16x16x32_bf16 v[52:55], v[192:195], v[144:147], 0
	v_mfma_f32_16x16x32_bf16 v[52:55], v[196:199], v[148:151], v[52:55]
	v_mfma_f32_16x16x32_bf16 v[48:51], v[212:215], v[148:151], 0
	v_mfma_f32_16x16x32_bf16 v[48:51], v[200:203], v[144:147], v[48:51]
	v_mfma_f32_16x16x32_bf16 v[32:35], v[200:203], v[152:155], 0
	v_mfma_f32_16x16x32_bf16 v[32:35], v[212:215], v[156:159], v[32:35]
	v_mfma_f32_16x16x32_bf16 v[36:39], v[196:199], v[156:159], 0
	v_mfma_f32_16x16x32_bf16 v[36:39], v[192:195], v[152:155], v[36:39]
	v_mfma_f32_16x16x32_bf16 v[20:23], v[192:195], v[160:163], 0
	v_mfma_f32_16x16x32_bf16 v[20:23], v[196:199], v[164:167], v[20:23]
	v_mfma_f32_16x16x32_bf16 v[16:19], v[212:215], v[164:167], 0
	v_mfma_f32_16x16x32_bf16 v[16:19], v[200:203], v[160:163], v[16:19]
	v_mfma_f32_16x16x32_bf16 v[0:3], v[200:203], v[168:171], 0
	v_mfma_f32_16x16x32_bf16 v[0:3], v[212:215], v[172:175], v[0:3]
	v_mfma_f32_16x16x32_bf16 v[4:7], v[196:199], v[172:175], 0
	v_mfma_f32_16x16x32_bf16 v[4:7], v[192:195], v[168:171], v[4:7]
	s_barrier
	s_add_i32 s69, 0, 0x18000
	ds_read_b128 v[128:131], v252
	ds_read_b128 v[132:135], v252 offset:1024
	ds_read_b128 v[136:139], v252 offset:2048
	ds_read_b128 v[140:143], v252 offset:3072
	s_add_u32 s44, s44, 0x40000
	s_addc_u32 s45, s45, 0
	s_mov_b32 m0, s56
	ds_read_b128 v[144:147], v209 offset:32768
	ds_read_b128 v[148:151], v209 offset:33792
	ds_read_b128 v[152:155], v209 offset:34816
	ds_read_b128 v[156:159], v209 offset:35840
	ds_read_b128 v[160:163], v209 offset:36864
	ds_read_b128 v[164:167], v209 offset:37888
	ds_read_b128 v[168:171], v209 offset:38912
	ds_read_b128 v[172:175], v209 offset:39936
	global_load_lds_dwordx4 v176, s[44:45]
	s_mov_b32 m0, s57
	s_nop 0
	global_load_lds_dwordx4 v180, s[44:45]
	s_barrier
	s_waitcnt lgkmcnt(0)
	v_mfma_f32_16x16x32_bf16 v[124:127], v[128:131], v[144:147], v[124:127]
	v_mfma_f32_16x16x32_bf16 v[124:127], v[132:135], v[148:151], v[124:127]
	v_mfma_f32_16x16x32_bf16 v[120:123], v[140:143], v[148:151], v[120:123]
	v_mfma_f32_16x16x32_bf16 v[120:123], v[136:139], v[144:147], v[120:123]
	v_mfma_f32_16x16x32_bf16 v[104:107], v[136:139], v[152:155], v[104:107]
	v_mfma_f32_16x16x32_bf16 v[104:107], v[140:143], v[156:159], v[104:107]
	v_mfma_f32_16x16x32_bf16 v[108:111], v[132:135], v[156:159], v[108:111]
	v_mfma_f32_16x16x32_bf16 v[108:111], v[128:131], v[152:155], v[108:111]
	v_mfma_f32_16x16x32_bf16 v[92:95], v[128:131], v[160:163], v[92:95]
	v_mfma_f32_16x16x32_bf16 v[92:95], v[132:135], v[164:167], v[92:95]
	v_mfma_f32_16x16x32_bf16 v[88:91], v[140:143], v[164:167], v[88:91]
	v_mfma_f32_16x16x32_bf16 v[88:91], v[136:139], v[160:163], v[88:91]
	v_mfma_f32_16x16x32_bf16 v[72:75], v[136:139], v[168:171], v[72:75]
	v_mfma_f32_16x16x32_bf16 v[72:75], v[140:143], v[172:175], v[72:75]
	v_mfma_f32_16x16x32_bf16 v[76:79], v[132:135], v[172:175], v[76:79]
	v_mfma_f32_16x16x32_bf16 v[76:79], v[128:131], v[168:171], v[76:79]
	s_barrier
	s_add_i32 s44, 0, 0x1c000
	s_add_i32 s45, s69, s51
	s_mov_b32 m0, s45
	ds_read_b128 v[192:195], v253
	ds_read_b128 v[196:199], v253 offset:1024
	ds_read_b128 v[200:203], v253 offset:2048
	ds_read_b128 v[212:215], v253 offset:3072
	global_load_lds_dwordx4 v178, s[90:91]
	s_add_i32 m0, s45, 0x2000
	s_nop 0
	global_load_lds_dwordx4 v182, s[90:91]
	s_barrier
	s_waitcnt lgkmcnt(0)
	v_mfma_f32_16x16x32_bf16 v[116:119], v[192:195], v[144:147], v[116:119]
	v_mfma_f32_16x16x32_bf16 v[116:119], v[196:199], v[148:151], v[116:119]
	v_mfma_f32_16x16x32_bf16 v[112:115], v[212:215], v[148:151], v[112:115]
	v_mfma_f32_16x16x32_bf16 v[112:115], v[200:203], v[144:147], v[112:115]
	v_mfma_f32_16x16x32_bf16 v[96:99], v[200:203], v[152:155], v[96:99]
	v_mfma_f32_16x16x32_bf16 v[96:99], v[212:215], v[156:159], v[96:99]
	v_mfma_f32_16x16x32_bf16 v[100:103], v[196:199], v[156:159], v[100:103]
	v_mfma_f32_16x16x32_bf16 v[100:103], v[192:195], v[152:155], v[100:103]
	v_mfma_f32_16x16x32_bf16 v[84:87], v[192:195], v[160:163], v[84:87]
	v_mfma_f32_16x16x32_bf16 v[84:87], v[196:199], v[164:167], v[84:87]
	v_mfma_f32_16x16x32_bf16 v[80:83], v[212:215], v[164:167], v[80:83]
	v_mfma_f32_16x16x32_bf16 v[80:83], v[200:203], v[160:163], v[80:83]
	v_mfma_f32_16x16x32_bf16 v[64:67], v[200:203], v[168:171], v[64:67]
	v_mfma_f32_16x16x32_bf16 v[64:67], v[212:215], v[172:175], v[64:67]
	v_mfma_f32_16x16x32_bf16 v[68:71], v[196:199], v[172:175], v[68:71]
	v_mfma_f32_16x16x32_bf16 v[68:71], v[192:195], v[168:171], v[68:71]
	s_barrier
	s_mov_b32 m0, s63
	ds_read_b128 v[144:147], v209 offset:49152
	ds_read_b128 v[148:151], v209 offset:50176
	ds_read_b128 v[152:155], v209 offset:51200
	ds_read_b128 v[156:159], v209 offset:52224
	ds_read_b128 v[160:163], v209 offset:53248
	ds_read_b128 v[164:167], v209 offset:54272
	ds_read_b128 v[168:171], v209 offset:55296
	ds_read_b128 v[172:175], v209 offset:56320
	global_load_lds_dwordx4 v176, s[92:93]
	s_mov_b32 m0, s64
	s_nop 0
	global_load_lds_dwordx4 v180, s[92:93]
	s_barrier
	s_waitcnt lgkmcnt(0)
	v_mfma_f32_16x16x32_bf16 v[60:63], v[128:131], v[144:147], v[60:63]
	v_mfma_f32_16x16x32_bf16 v[60:63], v[132:135], v[148:151], v[60:63]
	v_mfma_f32_16x16x32_bf16 v[56:59], v[140:143], v[148:151], v[56:59]
	v_mfma_f32_16x16x32_bf16 v[56:59], v[136:139], v[144:147], v[56:59]
	v_mfma_f32_16x16x32_bf16 v[40:43], v[136:139], v[152:155], v[40:43]
	v_mfma_f32_16x16x32_bf16 v[40:43], v[140:143], v[156:159], v[40:43]
	v_mfma_f32_16x16x32_bf16 v[44:47], v[132:135], v[156:159], v[44:47]
	v_mfma_f32_16x16x32_bf16 v[44:47], v[128:131], v[152:155], v[44:47]
	v_mfma_f32_16x16x32_bf16 v[28:31], v[128:131], v[160:163], v[28:31]
	v_mfma_f32_16x16x32_bf16 v[28:31], v[132:135], v[164:167], v[28:31]
	v_mfma_f32_16x16x32_bf16 v[24:27], v[140:143], v[164:167], v[24:27]
	v_mfma_f32_16x16x32_bf16 v[24:27], v[136:139], v[160:163], v[24:27]
	v_mfma_f32_16x16x32_bf16 v[8:11], v[136:139], v[168:171], v[8:11]
	v_mfma_f32_16x16x32_bf16 v[8:11], v[140:143], v[172:175], v[8:11]
	v_mfma_f32_16x16x32_bf16 v[12:15], v[132:135], v[172:175], v[12:15]
	v_mfma_f32_16x16x32_bf16 v[12:15], v[128:131], v[168:171], v[12:15]
	s_barrier
; #define PG8_STAGE(bufoff, gbase, voff) do { _Pragma("unroll") for (int _i = 0; _i < 2; ++_i) \
;         __builtin_amdgcn_global_load_lds((const unsigned*)((const char*)(gbase) + (voff)[_i]), (LAS unsigned*)(lds + (bufoff) + ldsw + _i * 8192), 16, 0, 0); } while (0)
; #define PG8_LDA(dst, b, h) do { _Pragma("unroll") for (int m = 0; m < 4; ++m) _Pragma("unroll") for (int k = 0; k < 2; ++k) dst[m][k] = *(const LAS bf16x8*)(lds + PG8_SA(b, h) + aoff + m * 2048 + k * 1024); } while (0)
; #define PG8_LDB(dst, b, h) do { _Pragma("unroll") for (int n = 0; n < 2; ++n) _Pragma("unroll") for (int k = 0; k < 2; ++k) dst[n][k] = *(const LAS bf16x8*)(lds + PG8_SB(b, h) + boff + n * 2048 + k * 1024); } while (0)
; #define PG8_MMA(ai, bj, At, Bt) do { __builtin_amdgcn_s_setprio(1); _Pragma("unroll") for (int m = 0; m < 4; ++m) _Pragma("unroll") for (int n = 0; n < 2; ++n) _Pragma("unroll") for (int k = 0; k < 2; ++k) \
;         acc[ai][bj][m][n] = __builtin_amdgcn_mfma_f32_16x16x32_bf16(Bt[n][k], At[m][k], acc[ai][bj][m][n], 0, 0, 0); __builtin_amdgcn_s_setprio(0); } while (0)
; #define PG8_WAIT_V(n) asm volatile("s_waitcnt vmcnt(" #n ")" ::: "memory")
; #define PG8_WAIT_L(n) asm volatile("s_waitcnt lgkmcnt(" #n ")" ::: "memory")
; #define PG8_BAR __builtin_amdgcn_s_barrier()
; #define PG8_SCHED __builtin_amdgcn_sched_barrier(0)
; template <class Epi, class Ptrs>
; __device__ __forceinline__ void gemm_phase(LAS unsigned char* lds, const int K, const StaticOrder& S, const Ptrs& P, const Epi& E) {
;     ...
;             PG8_LDB(B0, 0, 0); PG8_SCHED; PG8_LDA(At, 0, 0); PG8_STAGE(PG8_SA(1, 1), a1 + hstep, voffA);
;             PG8_WAIT_L(8); PG8_BAR; PG8_WAIT_L(0); PG8_MMA(0, 0, At, B0); PG8_BAR; PG8_SCHED;
;             PG8_LDB(B1, 0, 1); PG8_STAGE(PG8_SB(0, 0), b2, voffB);
;             PG8_BAR; PG8_WAIT_L(0); PG8_MMA(0, 1, At, B1); PG8_BAR;
;             PG8_LDA(At, 0, 1); PG8_STAGE(PG8_SA(0, 0), a2, voffA);
;     ...
;             PG8_STAGE(PG8_SB(1, 1), b3 + hstep, voffB);
;             PG8_WAIT_V(6); PG8_BAR; PG8_MMA(1, 1, At, B1); PG8_BAR;
	s_add_u32 s42, s42, 0x40080
	s_addc_u32 s43, s43, 0
	s_add_i32 s44, s44, s51
	s_mov_b32 m0, s44
	s_nop 0
	global_load_lds_dwordx4 v178, s[42:43]
	s_add_i32 m0, s44, 0x2000
	s_nop 0
	global_load_lds_dwordx4 v182, s[42:43]
	s_waitcnt vmcnt(6)
	s_barrier
	v_mfma_f32_16x16x32_bf16 v[52:55], v[192:195], v[144:147], v[52:55]
	v_mfma_f32_16x16x32_bf16 v[52:55], v[196:199], v[148:151], v[52:55]
	v_mfma_f32_16x16x32_bf16 v[48:51], v[212:215], v[148:151], v[48:51]
	v_mfma_f32_16x16x32_bf16 v[48:51], v[200:203], v[144:147], v[48:51]
	v_mfma_f32_16x16x32_bf16 v[32:35], v[200:203], v[152:155], v[32:35]
	v_mfma_f32_16x16x32_bf16 v[32:35], v[212:215], v[156:159], v[32:35]
	v_mfma_f32_16x16x32_bf16 v[36:39], v[196:199], v[156:159], v[36:39]
	v_mfma_f32_16x16x32_bf16 v[36:39], v[192:195], v[152:155], v[36:39]
	v_mfma_f32_16x16x32_bf16 v[20:23], v[192:195], v[160:163], v[20:23]
	v_mfma_f32_16x16x32_bf16 v[20:23], v[196:199], v[164:167], v[20:23]
	v_mfma_f32_16x16x32_bf16 v[16:19], v[212:215], v[164:167], v[16:19]
	v_mfma_f32_16x16x32_bf16 v[16:19], v[200:203], v[160:163], v[16:19]
	v_mfma_f32_16x16x32_bf16 v[0:3], v[200:203], v[168:171], v[0:3]
	v_mfma_f32_16x16x32_bf16 v[0:3], v[212:215], v[172:175], v[0:3]
	v_mfma_f32_16x16x32_bf16 v[4:7], v[196:199], v[172:175], v[4:7]
	v_mfma_f32_16x16x32_bf16 v[4:7], v[192:195], v[168:171], v[4:7]
	s_barrier
	s_add_i32 s41, s41, 2
	s_add_u32 s38, s38, 0x100
	s_addc_u32 s39, s39, 0
	s_add_u32 s21, s21, 0x100
	s_addc_u32 s23, s23, 0
	s_cmp_gt_u32 s41, 13
.LBB0_353:
	ds_read_b128 v[128:131], v207
	ds_read_b128 v[132:135], v207 offset:1024
	ds_read_b128 v[136:139], v207 offset:2048
	ds_read_b128 v[140:143], v207 offset:3072
	s_add_u32 s42, s38, 0xfffc0080
	s_addc_u32 s43, s39, -1
	s_cmp_eq_u32 s41, 12
	s_cselect_b32 s45, s1, s43
	s_cselect_b32 s44, s0, s42
	s_cselect_b32 s43, s25, s23
	s_cselect_b32 s42, s24, s21
	s_add_i32 m0, s54, 0xc000
	ds_read_b128 v[144:147], v209
	ds_read_b128 v[148:151], v209 offset:1024
	ds_read_b128 v[152:155], v209 offset:2048
	ds_read_b128 v[156:159], v209 offset:3072
	ds_read_b128 v[160:163], v209 offset:4096
	ds_read_b128 v[164:167], v209 offset:5120
	ds_read_b128 v[168:171], v209 offset:6144
	ds_read_b128 v[172:175], v209 offset:7168
	global_load_lds_dwordx4 v184, s[38:39]
	s_add_i32 m0, s54, 0xe000
	s_nop 0
	global_load_lds_dwordx4 v186, s[38:39]
	s_barrier
	s_waitcnt lgkmcnt(0)
	v_mfma_f32_16x16x32_bf16 v[124:127], v[128:131], v[144:147], v[124:127]
	v_mfma_f32_16x16x32_bf16 v[124:127], v[132:135], v[148:151], v[124:127]
	v_mfma_f32_16x16x32_bf16 v[120:123], v[140:143], v[148:151], v[120:123]
	v_mfma_f32_16x16x32_bf16 v[120:123], v[136:139], v[144:147], v[120:123]
	v_mfma_f32_16x16x32_bf16 v[104:107], v[136:139], v[152:155], v[104:107]
	v_mfma_f32_16x16x32_bf16 v[104:107], v[140:143], v[156:159], v[104:107]
	v_mfma_f32_16x16x32_bf16 v[108:111], v[132:135], v[156:159], v[108:111]
	v_mfma_f32_16x16x32_bf16 v[108:111], v[128:131], v[152:155], v[108:111]
	v_mfma_f32_16x16x32_bf16 v[92:95], v[128:131], v[160:163], v[92:95]
	v_mfma_f32_16x16x32_bf16 v[92:95], v[132:135], v[164:167], v[92:95]
	v_mfma_f32_16x16x32_bf16 v[88:91], v[140:143], v[164:167], v[88:91]
	v_mfma_f32_16x16x32_bf16 v[88:91], v[136:139], v[160:163], v[88:91]
	v_mfma_f32_16x16x32_bf16 v[72:75], v[136:139], v[168:171], v[72:75]
	v_mfma_f32_16x16x32_bf16 v[72:75], v[140:143], v[172:175], v[72:75]
	v_mfma_f32_16x16x32_bf16 v[76:79], v[132:135], v[172:175], v[76:79]
	v_mfma_f32_16x16x32_bf16 v[76:79], v[128:131], v[168:171], v[76:79]
	s_barrier
	s_add_i32 s69, s66, s51
	s_add_u32 s90, s42, 0x80
	s_addc_u32 s91, s43, 0
	s_mov_b32 m0, s69
	ds_read_b128 v[192:195], v210
	ds_read_b128 v[196:199], v210 offset:1024
	ds_read_b128 v[200:203], v210 offset:2048
	ds_read_b128 v[212:215], v210 offset:3072
	global_load_lds_dwordx4 v178, s[42:43]
	s_add_i32 m0, s69, 0x2000
	s_nop 0
	global_load_lds_dwordx4 v182, s[42:43]
	s_barrier
	s_waitcnt lgkmcnt(0)
	v_mfma_f32_16x16x32_bf16 v[116:119], v[192:195], v[144:147], v[116:119]
	v_mfma_f32_16x16x32_bf16 v[116:119], v[196:199], v[148:151], v[116:119]
	v_mfma_f32_16x16x32_bf16 v[112:115], v[212:215], v[148:151], v[112:115]
	v_mfma_f32_16x16x32_bf16 v[112:115], v[200:203], v[144:147], v[112:115]
	v_mfma_f32_16x16x32_bf16 v[96:99], v[200:203], v[152:155], v[96:99]
	v_mfma_f32_16x16x32_bf16 v[96:99], v[212:215], v[156:159], v[96:99]
	v_mfma_f32_16x16x32_bf16 v[100:103], v[196:199], v[156:159], v[100:103]
	v_mfma_f32_16x16x32_bf16 v[100:103], v[192:195], v[152:155], v[100:103]
	v_mfma_f32_16x16x32_bf16 v[84:87], v[192:195], v[160:163], v[84:87]
	v_mfma_f32_16x16x32_bf16 v[84:87], v[196:199], v[164:167], v[84:87]
	v_mfma_f32_16x16x32_bf16 v[80:83], v[212:215], v[164:167], v[80:83]
	v_mfma_f32_16x16x32_bf16 v[80:83], v[200:203], v[160:163], v[80:83]
	v_mfma_f32_16x16x32_bf16 v[64:67], v[200:203], v[168:171], v[64:67]
	v_mfma_f32_16x16x32_bf16 v[64:67], v[212:215], v[172:175], v[64:67]
	v_mfma_f32_16x16x32_bf16 v[68:71], v[196:199], v[172:175], v[68:71]
	v_mfma_f32_16x16x32_bf16 v[68:71], v[192:195], v[168:171], v[68:71]
	s_barrier
	s_mov_b32 m0, s54
	s_add_u32 s92, s44, 0x80
	s_addc_u32 s93, s45, 0
	ds_read_b128 v[144:147], v209 offset:16384
	ds_read_b128 v[148:151], v209 offset:17408
	ds_read_b128 v[152:155], v209 offset:18432
	ds_read_b128 v[156:159], v209 offset:19456
	ds_read_b128 v[160:163], v209 offset:20480
	ds_read_b128 v[164:167], v209 offset:21504
	ds_read_b128 v[168:171], v209 offset:22528
	ds_read_b128 v[172:175], v209 offset:23552
	global_load_lds_dwordx4 v176, s[44:45]
	s_mov_b32 m0, s55
	s_nop 0
	global_load_lds_dwordx4 v180, s[44:45]
	s_barrier
; #define PG8_STAGE(bufoff, gbase, voff) do { _Pragma("unroll") for (int _i = 0; _i < 2; ++_i) \
;         __builtin_amdgcn_global_load_lds((const unsigned*)((const char*)(gbase) + (voff)[_i]), (LAS unsigned*)(lds + (bufoff) + ldsw + _i * 8192), 16, 0, 0); } while (0)
; #define PG8_LDA(dst, b, h) do { _Pragma("unroll") for (int m = 0; m < 4; ++m) _Pragma("unroll") for (int k = 0; k < 2; ++k) dst[m][k] = *(const LAS bf16x8*)(lds + PG8_SA(b, h) + aoff + m * 2048 + k * 1024); } while (0)
; #define PG8_LDB(dst, b, h) do { _Pragma("unroll") for (int n = 0; n < 2; ++n) _Pragma("unroll") for (int k = 0; k < 2; ++k) dst[n][k] = *(const LAS bf16x8*)(lds + PG8_SB(b, h) + boff + n * 2048 + k * 1024); } while (0)
; #define PG8_MMA(ai, bj, At, Bt) do { __builtin_amdgcn_s_setprio(1); _Pragma("unroll") for (int m = 0; m < 4; ++m) _Pragma("unroll") for (int n = 0; n < 2; ++n) _Pragma("unroll") for (int k = 0; k < 2; ++k) \
;         acc[ai][bj][m][n] = __builtin_amdgcn_mfma_f32_16x16x32_bf16(Bt[n][k], At[m][k], acc[ai][bj][m][n], 0, 0, 0); __builtin_amdgcn_s_setprio(0); } while (0)
; #define PG8_WAIT_V(n) asm volatile("s_waitcnt vmcnt(" #n ")" ::: "memory")
; #define PG8_WAIT_L(n) asm volatile("s_waitcnt lgkmcnt(" #n ")" ::: "memory")
; #define PG8_BAR __builtin_amdgcn_s_barrier()
; #define PG8_SCHED __builtin_amdgcn_sched_barrier(0)
; template <class Epi, class Ptrs>
; __device__ __forceinline__ void gemm_phase(LAS unsigned char* lds, const int K, const StaticOrder& S, const Ptrs& P, const Epi& E) {
;     ...
;             PG8_BAR; PG8_WAIT_L(0); PG8_MMA(1, 0, At, B0); PG8_BAR; PG8_SCHED;
;             PG8_STAGE(PG8_SB(0, 1), b2 + hstep, voffB);
;             PG8_WAIT_V(6); PG8_BAR; PG8_MMA(1, 1, At, B1); PG8_BAR;
;             PG8_LDB(B0, 1, 0); PG8_SCHED; PG8_LDA(At, 1, 0); PG8_STAGE(PG8_SA(0, 1), a2 + hstep, voffA);
;             PG8_WAIT_L(8); PG8_BAR; PG8_WAIT_L(0); PG8_MMA(0, 0, At, B0); PG8_BAR; PG8_SCHED;
;             PG8_LDB(B1, 1, 1); PG8_STAGE(PG8_SB(1, 0), b3, voffB);
;             PG8_BAR; PG8_WAIT_L(0); PG8_MMA(0, 1, At, B1); PG8_BAR;
;             PG8_LDA(At, 1, 1); PG8_STAGE(PG8_SA(1, 0), a3, voffA);
	s_waitcnt lgkmcnt(0)
	v_mfma_f32_16x16x32_bf16 v[60:63], v[128:131], v[144:147], v[60:63]
	v_mfma_f32_16x16x32_bf16 v[60:63], v[132:135], v[148:151], v[60:63]
	v_mfma_f32_16x16x32_bf16 v[56:59], v[140:143], v[148:151], v[56:59]
	v_mfma_f32_16x16x32_bf16 v[56:59], v[136:139], v[144:147], v[56:59]
	v_mfma_f32_16x16x32_bf16 v[40:43], v[136:139], v[152:155], v[40:43]
	v_mfma_f32_16x16x32_bf16 v[40:43], v[140:143], v[156:159], v[40:43]
	v_mfma_f32_16x16x32_bf16 v[44:47], v[132:135], v[156:159], v[44:47]
	v_mfma_f32_16x16x32_bf16 v[44:47], v[128:131], v[152:155], v[44:47]
	v_mfma_f32_16x16x32_bf16 v[28:31], v[128:131], v[160:163], v[28:31]
	v_mfma_f32_16x16x32_bf16 v[28:31], v[132:135], v[164:167], v[28:31]
	v_mfma_f32_16x16x32_bf16 v[24:27], v[140:143], v[164:167], v[24:27]
	v_mfma_f32_16x16x32_bf16 v[24:27], v[136:139], v[160:163], v[24:27]
	v_mfma_f32_16x16x32_bf16 v[8:11], v[136:139], v[168:171], v[8:11]
	v_mfma_f32_16x16x32_bf16 v[8:11], v[140:143], v[172:175], v[8:11]
	v_mfma_f32_16x16x32_bf16 v[12:15], v[132:135], v[172:175], v[12:15]
	v_mfma_f32_16x16x32_bf16 v[12:15], v[128:131], v[168:171], v[12:15]
	s_barrier
	s_add_u32 s70, s42, 0x40000
	s_addc_u32 s71, s43, 0
	s_add_i32 s69, s67, s51
	s_mov_b32 m0, s69
	s_nop 0
	global_load_lds_dwordx4 v178, s[70:71]
	s_add_i32 m0, s69, 0x2000
	s_nop 0
	global_load_lds_dwordx4 v182, s[70:71]
	s_waitcnt vmcnt(6)
	s_barrier
	v_mfma_f32_16x16x32_bf16 v[52:55], v[192:195], v[144:147], v[52:55]
	v_mfma_f32_16x16x32_bf16 v[52:55], v[196:199], v[148:151], v[52:55]
	v_mfma_f32_16x16x32_bf16 v[48:51], v[212:215], v[148:151], v[48:51]
	v_mfma_f32_16x16x32_bf16 v[48:51], v[200:203], v[144:147], v[48:51]
	v_mfma_f32_16x16x32_bf16 v[32:35], v[200:203], v[152:155], v[32:35]
	v_mfma_f32_16x16x32_bf16 v[32:35], v[212:215], v[156:159], v[32:35]
	v_mfma_f32_16x16x32_bf16 v[36:39], v[196:199], v[156:159], v[36:39]
	v_mfma_f32_16x16x32_bf16 v[36:39], v[192:195], v[152:155], v[36:39]
	v_mfma_f32_16x16x32_bf16 v[20:23], v[192:195], v[160:163], v[20:23]
	v_mfma_f32_16x16x32_bf16 v[20:23], v[196:199], v[164:167], v[20:23]
	v_mfma_f32_16x16x32_bf16 v[16:19], v[212:215], v[164:167], v[16:19]
	v_mfma_f32_16x16x32_bf16 v[16:19], v[200:203], v[160:163], v[16:19]
	v_mfma_f32_16x16x32_bf16 v[0:3], v[200:203], v[168:171], v[0:3]
	v_mfma_f32_16x16x32_bf16 v[0:3], v[212:215], v[172:175], v[0:3]
	v_mfma_f32_16x16x32_bf16 v[4:7], v[196:199], v[172:175], v[4:7]
	v_mfma_f32_16x16x32_bf16 v[4:7], v[192:195], v[168:171], v[4:7]
	s_barrier
	s_add_i32 s69, 0, 0x18000
	ds_read_b128 v[128:131], v252
	ds_read_b128 v[132:135], v252 offset:1024
	ds_read_b128 v[136:139], v252 offset:2048
	ds_read_b128 v[140:143], v252 offset:3072
	s_add_u32 s44, s44, 0x40000
	s_addc_u32 s45, s45, 0
	s_mov_b32 m0, s56
	ds_read_b128 v[144:147], v209 offset:32768
	ds_read_b128 v[148:151], v209 offset:33792
	ds_read_b128 v[152:155], v209 offset:34816
	ds_read_b128 v[156:159], v209 offset:35840
	ds_read_b128 v[160:163], v209 offset:36864
	ds_read_b128 v[164:167], v209 offset:37888
	ds_read_b128 v[168:171], v209 offset:38912
	ds_read_b128 v[172:175], v209 offset:39936
	global_load_lds_dwordx4 v176, s[44:45]
	s_mov_b32 m0, s57
	s_nop 0
	global_load_lds_dwordx4 v180, s[44:45]
	s_barrier
	s_waitcnt lgkmcnt(0)
	v_mfma_f32_16x16x32_bf16 v[124:127], v[128:131], v[144:147], v[124:127]
	v_mfma_f32_16x16x32_bf16 v[124:127], v[132:135], v[148:151], v[124:127]
	v_mfma_f32_16x16x32_bf16 v[120:123], v[140:143], v[148:151], v[120:123]
	v_mfma_f32_16x16x32_bf16 v[120:123], v[136:139], v[144:147], v[120:123]
	v_mfma_f32_16x16x32_bf16 v[104:107], v[136:139], v[152:155], v[104:107]
	v_mfma_f32_16x16x32_bf16 v[104:107], v[140:143], v[156:159], v[104:107]
	v_mfma_f32_16x16x32_bf16 v[108:111], v[132:135], v[156:159], v[108:111]
	v_mfma_f32_16x16x32_bf16 v[108:111], v[128:131], v[152:155], v[108:111]
	v_mfma_f32_16x16x32_bf16 v[92:95], v[128:131], v[160:163], v[92:95]
	v_mfma_f32_16x16x32_bf16 v[92:95], v[132:135], v[164:167], v[92:95]
	v_mfma_f32_16x16x32_bf16 v[88:91], v[140:143], v[164:167], v[88:91]
	v_mfma_f32_16x16x32_bf16 v[88:91], v[136:139], v[160:163], v[88:91]
	v_mfma_f32_16x16x32_bf16 v[72:75], v[136:139], v[168:171], v[72:75]
	v_mfma_f32_16x16x32_bf16 v[72:75], v[140:143], v[172:175], v[72:75]
	v_mfma_f32_16x16x32_bf16 v[76:79], v[132:135], v[172:175], v[76:79]
	v_mfma_f32_16x16x32_bf16 v[76:79], v[128:131], v[168:171], v[76:79]
	s_barrier
	s_add_i32 s44, 0, 0x1c000
	s_add_i32 s45, s69, s51
	s_mov_b32 m0, s45
	ds_read_b128 v[192:195], v253
	ds_read_b128 v[196:199], v253 offset:1024
	ds_read_b128 v[200:203], v253 offset:2048
	ds_read_b128 v[212:215], v253 offset:3072
	global_load_lds_dwordx4 v178, s[90:91]
	s_add_i32 m0, s45, 0x2000
	s_nop 0
	global_load_lds_dwordx4 v182, s[90:91]
	s_barrier
	s_waitcnt lgkmcnt(0)
	v_mfma_f32_16x16x32_bf16 v[116:119], v[192:195], v[144:147], v[116:119]
	v_mfma_f32_16x16x32_bf16 v[116:119], v[196:199], v[148:151], v[116:119]
	v_mfma_f32_16x16x32_bf16 v[112:115], v[212:215], v[148:151], v[112:115]
	v_mfma_f32_16x16x32_bf16 v[112:115], v[200:203], v[144:147], v[112:115]
	v_mfma_f32_16x16x32_bf16 v[96:99], v[200:203], v[152:155], v[96:99]
	v_mfma_f32_16x16x32_bf16 v[96:99], v[212:215], v[156:159], v[96:99]
	v_mfma_f32_16x16x32_bf16 v[100:103], v[196:199], v[156:159], v[100:103]
	v_mfma_f32_16x16x32_bf16 v[100:103], v[192:195], v[152:155], v[100:103]
	v_mfma_f32_16x16x32_bf16 v[84:87], v[192:195], v[160:163], v[84:87]
	v_mfma_f32_16x16x32_bf16 v[84:87], v[196:199], v[164:167], v[84:87]
	v_mfma_f32_16x16x32_bf16 v[80:83], v[212:215], v[164:167], v[80:83]
	v_mfma_f32_16x16x32_bf16 v[80:83], v[200:203], v[160:163], v[80:83]
	v_mfma_f32_16x16x32_bf16 v[64:67], v[200:203], v[168:171], v[64:67]
	v_mfma_f32_16x16x32_bf16 v[64:67], v[212:215], v[172:175], v[64:67]
	v_mfma_f32_16x16x32_bf16 v[68:71], v[196:199], v[172:175], v[68:71]
	v_mfma_f32_16x16x32_bf16 v[68:71], v[192:195], v[168:171], v[68:71]
	s_barrier
; #define PG8_STAGE(bufoff, gbase, voff) do { _Pragma("unroll") for (int _i = 0; _i < 2; ++_i) \
;         __builtin_amdgcn_global_load_lds((const unsigned*)((const char*)(gbase) + (voff)[_i]), (LAS unsigned*)(lds + (bufoff) + ldsw + _i * 8192), 16, 0, 0); } while (0)
; #define PG8_LDA(dst, b, h) do { _Pragma("unroll") for (int m = 0; m < 4; ++m) _Pragma("unroll") for (int k = 0; k < 2; ++k) dst[m][k] = *(const LAS bf16x8*)(lds + PG8_SA(b, h) + aoff + m * 2048 + k * 1024); } while (0)
; #define PG8_MMA(ai, bj, At, Bt) do { __builtin_amdgcn_s_setprio(1); _Pragma("unroll") for (int m = 0; m < 4; ++m) _Pragma("unroll") for (int n = 0; n < 2; ++n) _Pragma("unroll") for (int k = 0; k < 2; ++k) \
;         acc[ai][bj][m][n] = __builtin_amdgcn_mfma_f32_16x16x32_bf16(Bt[n][k], At[m][k], acc[ai][bj][m][n], 0, 0, 0); __builtin_amdgcn_s_setprio(0); } while (0)
; #define PG8_WAIT_V(n) asm volatile("s_waitcnt vmcnt(" #n ")" ::: "memory")
; #define PG8_WAIT_L(n) asm volatile("s_waitcnt lgkmcnt(" #n ")" ::: "memory")
; #define PG8_BAR __builtin_amdgcn_s_barrier()
; #define PG8_SCHED __builtin_amdgcn_sched_barrier(0)
; template <class Epi, class Ptrs>
; __device__ __forceinline__ void gemm_phase(LAS unsigned char* lds, const int K, const StaticOrder& S, const Ptrs& P, const Epi& E) {
;     ...
;             PG8_LDA(At, 1, 1); PG8_STAGE(PG8_SA(1, 0), a3, voffA);
;             PG8_BAR; PG8_WAIT_L(0); PG8_MMA(1, 0, At, B0); PG8_BAR; PG8_SCHED;
;             PG8_STAGE(PG8_SB(1, 1), b3 + hstep, voffB);
;             PG8_WAIT_V(6); PG8_BAR; PG8_MMA(1, 1, At, B1); PG8_BAR;
	s_mov_b32 m0, s63
	ds_read_b128 v[144:147], v209 offset:49152
	ds_read_b128 v[148:151], v209 offset:50176
	ds_read_b128 v[152:155], v209 offset:51200
	ds_read_b128 v[156:159], v209 offset:52224
	ds_read_b128 v[160:163], v209 offset:53248
	ds_read_b128 v[164:167], v209 offset:54272
	ds_read_b128 v[168:171], v209 offset:55296
	ds_read_b128 v[172:175], v209 offset:56320
	global_load_lds_dwordx4 v176, s[92:93]
	s_mov_b32 m0, s64
	s_nop 0
	global_load_lds_dwordx4 v180, s[92:93]
	s_barrier
	s_waitcnt lgkmcnt(0)
	v_mfma_f32_16x16x32_bf16 v[60:63], v[128:131], v[144:147], v[60:63]
	v_mfma_f32_16x16x32_bf16 v[60:63], v[132:135], v[148:151], v[60:63]
	v_mfma_f32_16x16x32_bf16 v[56:59], v[140:143], v[148:151], v[56:59]
	v_mfma_f32_16x16x32_bf16 v[56:59], v[136:139], v[144:147], v[56:59]
	v_mfma_f32_16x16x32_bf16 v[40:43], v[136:139], v[152:155], v[40:43]
	v_mfma_f32_16x16x32_bf16 v[40:43], v[140:143], v[156:159], v[40:43]
	v_mfma_f32_16x16x32_bf16 v[44:47], v[132:135], v[156:159], v[44:47]
	v_mfma_f32_16x16x32_bf16 v[44:47], v[128:131], v[152:155], v[44:47]
	v_mfma_f32_16x16x32_bf16 v[28:31], v[128:131], v[160:163], v[28:31]
	v_mfma_f32_16x16x32_bf16 v[28:31], v[132:135], v[164:167], v[28:31]
	v_mfma_f32_16x16x32_bf16 v[24:27], v[140:143], v[164:167], v[24:27]
	v_mfma_f32_16x16x32_bf16 v[24:27], v[136:139], v[160:163], v[24:27]
	v_mfma_f32_16x16x32_bf16 v[8:11], v[136:139], v[168:171], v[8:11]
	v_mfma_f32_16x16x32_bf16 v[8:11], v[140:143], v[172:175], v[8:11]
	v_mfma_f32_16x16x32_bf16 v[12:15], v[132:135], v[172:175], v[12:15]
	v_mfma_f32_16x16x32_bf16 v[12:15], v[128:131], v[168:171], v[12:15]
	s_barrier
	s_add_u32 s42, s42, 0x40080
	s_addc_u32 s43, s43, 0
	s_add_i32 s44, s44, s51
	s_mov_b32 m0, s44
	s_nop 0
	global_load_lds_dwordx4 v178, s[42:43]
	s_add_i32 m0, s44, 0x2000
	s_nop 0
	global_load_lds_dwordx4 v182, s[42:43]
	s_waitcnt vmcnt(6)
	s_barrier
	v_mfma_f32_16x16x32_bf16 v[52:55], v[192:195], v[144:147], v[52:55]
	v_mfma_f32_16x16x32_bf16 v[52:55], v[196:199], v[148:151], v[52:55]
	v_mfma_f32_16x16x32_bf16 v[48:51], v[212:215], v[148:151], v[48:51]
	v_mfma_f32_16x16x32_bf16 v[48:51], v[200:203], v[144:147], v[48:51]
	v_mfma_f32_16x16x32_bf16 v[32:35], v[200:203], v[152:155], v[32:35]
	v_mfma_f32_16x16x32_bf16 v[32:35], v[212:215], v[156:159], v[32:35]
	v_mfma_f32_16x16x32_bf16 v[36:39], v[196:199], v[156:159], v[36:39]
	v_mfma_f32_16x16x32_bf16 v[36:39], v[192:195], v[152:155], v[36:39]
	v_mfma_f32_16x16x32_bf16 v[20:23], v[192:195], v[160:163], v[20:23]
	v_mfma_f32_16x16x32_bf16 v[20:23], v[196:199], v[164:167], v[20:23]
	v_mfma_f32_16x16x32_bf16 v[16:19], v[212:215], v[164:167], v[16:19]
	v_mfma_f32_16x16x32_bf16 v[16:19], v[200:203], v[160:163], v[16:19]
	v_mfma_f32_16x16x32_bf16 v[0:3], v[200:203], v[168:171], v[0:3]
	v_mfma_f32_16x16x32_bf16 v[0:3], v[212:215], v[172:175], v[0:3]
	v_mfma_f32_16x16x32_bf16 v[4:7], v[196:199], v[172:175], v[4:7]
	v_mfma_f32_16x16x32_bf16 v[4:7], v[192:195], v[168:171], v[4:7]
	s_barrier
	s_add_i32 s41, s41, 2
	s_add_u32 s38, s38, 0x100
	s_addc_u32 s39, s39, 0
	s_add_u32 s21, s21, 0x100
	s_addc_u32 s23, s23, 0
	s_cmp_gt_u32 s41, 13
	s_cbranch_scc0 .LBB0_353
; __device__ __forceinline__ unsigned cvt_pk_bf16(float lo, float hi) { unsigned r; asm volatile("v_cvt_pk_bf16_f32 %0, %1, %2" : "=v"(r) : "v"(lo), "v"(hi)); return r; }
; __device__ __forceinline__ float x16_sum(float x) { auto s = __builtin_amdgcn_permlane16_swap(__float_as_uint(x), __float_as_uint(x), false, false); return __uint_as_float(s[0]) + __uint_as_float(s[1]); }
; __device__ __forceinline__ float x32_sum(float x) { auto s = __builtin_amdgcn_permlane32_swap(__float_as_uint(x), __float_as_uint(x), false, false); return __uint_as_float(s[0]) + __uint_as_float(s[1]); }
;     __device__ __forceinline__ void operator()(const f32x4 (&acc)[2][2][4][2], const Unit& u, int ui, int wr, int wc, int fr, int fq) const {
;         const int row0 = u.pm * 256 + wr * 64 + fr, col0 = u.pn * 256 + wc * 32 + 8 * fq;
;         const float* xb0 = (u.pm * 256 < MP) ? xp : xs - (size_t)MP * DM;
; #pragma unroll
;         for (int ai = 0; ai < 2; ++ai) {
;             f32x4 xv[4][2][2];
; #pragma unroll
;             for (int m = 0; m < 4; ++m)
; #pragma unroll
;                 for (int bj = 0; bj < 2; ++bj) { const float* p = xb0 + (size_t)(row0 + ai * 128 + m * 16) * DM + col0 + bj * 128; xv[m][bj][0] = *(const f32x4*)p; xv[m][bj][1] = *(const f32x4*)(p + 4); }
; #pragma unroll
;             for (int m = 0; m < 4; ++m) { const int row = row0 + ai * 128 + m * 16; const size_t off = (size_t)row * DM + col0; float ss = 0.f;
; #pragma unroll
;                 for (int bj = 0; bj < 2; ++bj) {
;                     const f32x4 v0 = acc[ai][bj][m][0] + xv[m][bj][0], v1 = acc[ai][bj][m][1] + xv[m][bj][1];
;                     u32x4 w; w.x = cvt_pk_bf16(v0[0], v0[1]); w.y = cvt_pk_bf16(v0[2], v0[3]); w.z = cvt_pk_bf16(v1[0], v1[1]); w.w = cvt_pk_bf16(v1[2], v1[3]);
;                     *(u32x4*)(xb + off + bj * 128) = w;
;                     ss += (v0[0] * v0[0] + v0[1] * v0[1]) + (v0[2] * v0[2] + v0[3] * v0[3]) + (v1[0] * v1[0] + v1[1] * v1[1]) + (v1[2] * v1[2] + v1[3] * v1[3]); }
;                 ss = x32_sum(x16_sum(ss));
;                 if (fq == 0) part[(size_t)row * 16 + u.pn * 4 + wc] = ss; }
	s_cmpk_lt_i32 s40, 0x80
	v_lshl_add_u32 v194, s40, 8, v204
	v_lshl_or_b32 v192, s12, 8, v206
	s_cselect_b32 s21, s37, s61
	s_cselect_b32 s23, s36, s60
	v_mov_b32_e32 v128, s23
	v_mov_b32_e32 v129, s21
	v_ashrrev_i32_e32 v193, 31, v192
	v_ashrrev_i32_e32 v195, 31, v194
	v_lshl_add_u64 v[196:197], v[192:193], 2, v[128:129]
	v_lshlrev_b64 v[128:129], 12, v[194:195]
	v_or_b32_e32 v202, 16, v194
	v_or_b32_e32 v200, 32, v194
	v_or_b32_e32 v198, 48, v194
	v_lshl_add_u64 v[128:129], v[196:197], 0, v[128:129]
	v_ashrrev_i32_e32 v203, 31, v202
	v_ashrrev_i32_e32 v201, 31, v200
	v_ashrrev_i32_e32 v199, 31, v198
	global_load_dwordx4 v[212:215], v[128:129], off
	global_load_dwordx4 v[216:219], v[128:129], off offset:16
	global_load_dwordx4 v[220:223], v[128:129], off offset:512
	global_load_dwordx4 v[224:227], v[128:129], off offset:528
	v_lshlrev_b64 v[128:129], 12, v[202:203]
	v_lshlrev_b64 v[130:131], 12, v[200:201]
	v_lshlrev_b64 v[132:133], 12, v[198:199]
	v_lshl_add_u64 v[128:129], v[196:197], 0, v[128:129]
	v_lshl_add_u64 v[130:131], v[196:197], 0, v[130:131]
	v_lshl_add_u64 v[132:133], v[196:197], 0, v[132:133]
	global_load_dwordx4 v[168:171], v[128:129], off offset:16
	global_load_dwordx4 v[172:175], v[128:129], off
	global_load_dwordx4 v[160:163], v[128:129], off offset:528
	global_load_dwordx4 v[164:167], v[128:129], off offset:512
	global_load_dwordx4 v[152:155], v[130:131], off offset:16
	global_load_dwordx4 v[156:159], v[130:131], off
	global_load_dwordx4 v[144:147], v[130:131], off offset:528
	global_load_dwordx4 v[148:151], v[130:131], off offset:512
	global_load_dwordx4 v[136:139], v[132:133], off offset:16
	global_load_dwordx4 v[140:143], v[132:133], off
	s_nop 0
	global_load_dwordx4 v[128:131], v[132:133], off offset:528
	s_nop 0
	global_load_dwordx4 v[132:135], v[132:133], off offset:512
	v_lshlrev_b64 v[228:229], 11, v[194:195]
	v_lshl_add_u64 v[228:229], s[14:15], 0, v[228:229]
	v_lshl_add_u64 v[228:229], v[192:193], 1, v[228:229]
	s_lshl_b32 s38, s12, 2
	s_ashr_i32 s39, s38, 31
	s_waitcnt vmcnt(0)
	v_pk_add_f32 v[126:127], v[126:127], v[214:215]
	v_pk_add_f32 v[124:125], v[124:125], v[212:213]
	v_pk_add_f32 v[118:119], v[118:119], v[222:223]
	v_pk_add_f32 v[116:117], v[116:117], v[220:221]
	v_pk_add_f32 v[120:121], v[120:121], v[216:217]
	v_pk_add_f32 v[214:215], v[112:113], v[224:225]
	v_cvt_pk_bf16_f32 v112, v124, v125
	v_cvt_pk_bf16_f32 v113, v126, v127
	v_mul_f32_e32 v125, v125, v125
	v_mul_f32_e32 v127, v127, v127
	v_mul_f32_e32 v211, v117, v117
	v_mul_f32_e32 v216, v119, v119
	v_pk_add_f32 v[122:123], v[122:123], v[218:219]
	v_pk_add_f32 v[212:213], v[114:115], v[226:227]
	v_cvt_pk_bf16_f32 v114, v120, v121
	v_cvt_pk_bf16_f32 v115, v122, v123
	v_mul_f32_e32 v121, v121, v121
	v_mul_f32_e32 v217, v215, v215
	global_store_dwordx4 v[228:229], v[112:115], off
	v_fmac_f32_e32 v125, v124, v124
	v_fmac_f32_e32 v127, v126, v126
	v_cvt_pk_bf16_f32 v112, v116, v117
	v_fmac_f32_e32 v211, v116, v116
	v_fmac_f32_e32 v216, v118, v118
	v_mul_f32_e32 v123, v123, v123
	v_mul_f32_e32 v218, v213, v213
	v_fmac_f32_e32 v121, v120, v120
	v_cvt_pk_bf16_f32 v113, v118, v119
	v_cvt_pk_bf16_f32 v114, v214, v215
	v_cvt_pk_bf16_f32 v115, v212, v213
	v_fmac_f32_e32 v217, v214, v214
	v_add_f32_e32 v116, v125, v127
	global_store_dwordx4 v[228:229], v[112:115], off offset:256
	v_fmac_f32_e32 v123, v122, v122
	v_fmac_f32_e32 v218, v212, v212
	v_add_f32_e32 v112, v211, v216
	v_add_f32_e32 v113, v116, v121
	v_add_f32_e32 v112, v112, v217
	v_add_f32_e32 v113, v123, v113
	v_add_f32_e32 v112, v218, v112
	v_add_f32_e32 v112, v113, v112
	v_mov_b32_e32 v113, v112
	s_nop 1
	v_permlane16_swap_b32_e32 v112, v113
	v_add_f32_e32 v112, v112, v113
	v_mov_b32_e32 v113, v112
	s_nop 1
	v_permlane32_swap_b32_e32 v112, v113
	s_and_saveexec_b64 s[40:41], s[6:7]
	s_cbranch_execz .LBB0_356
	v_lshlrev_b64 v[114:115], 6, v[194:195]
	v_lshl_add_u64 v[114:115], s[16:17], 0, v[114:115]
	v_lshl_add_u64 v[114:115], s[38:39], 2, v[114:115]
	s_lshl_b32 s12, s62, 2
	v_lshl_add_u64 v[114:115], v[114:115], 0, s[12:13]
	v_add_f32_e32 v112, v112, v113
	global_store_dword v[114:115], v112, off

; __device__ __forceinline__ unsigned xb_ld(unsigned* p)              { return __hip_atomic_load(p, __ATOMIC_RELAXED, __HIP_MEMORY_SCOPE_AGENT); }
; __device__ __forceinline__ unsigned xb_add(unsigned* p, unsigned v) { return __hip_atomic_fetch_add(p, v, __ATOMIC_RELAXED, __HIP_MEMORY_SCOPE_AGENT); }
; __device__ __forceinline__ void xcd_barrier_complete(unsigned* bar, unsigned x, unsigned& nloc, unsigned& nx) {
;     const unsigned G = gridDim.x * gridDim.y * gridDim.z;
;     unsigned sum, cnt, mine, sp = 0u;
;     for (;;) {
;         sum = 0u; cnt = 0u; mine = 0u;
; #pragma unroll
;         for (unsigned j = 0; j < 16; ++j) { const unsigned c = xb_ld(&bar[XB_XCNT(j)]); sum += c; cnt += (c > 0u) ? 1u : 0u; mine = (j == x) ? c : mine; }
; __device__ __forceinline__ void xcd_barrier(const XcdBarrier& b) {
;     asm volatile("s_waitcnt vmcnt(0)" ::: "memory");
;     __syncthreads();
;     if (threadIdx.x == 0) {
;         unsigned* bar = b.bar;
;         __builtin_amdgcn_s_waitcnt(0);
;         unsigned nloc = b.st[0], nx = b.st[1];
;         if (nloc == 0u) { xcd_barrier_complete(bar, b.x, nloc, nx); b.st[0] = nloc; b.st[1] = nx; }
;         const unsigned old = xb_add(&bar[XB_XSUB(b.x)], 1u);
.LBB0_373:
	s_nop 0
	s_nop 0
	s_nop 0
	s_nop 0
	s_nop 0
	s_nop 0
	s_nop 0
	s_nop 0
	s_nop 0
	s_nop 0
	s_nop 0
	s_nop 0
	s_nop 0
	s_nop 0
	s_nop 0
	s_nop 0
	s_nop 0
	s_nop 0
	s_nop 0
	s_nop 0
	s_nop 0
	s_nop 0
	s_nop 0
	s_nop 0
	s_nop 0
	s_nop 0
	s_nop 0
	s_nop 0
	s_nop 0
	s_nop 0
	s_nop 0
	s_nop 0
	s_nop 0
	s_nop 0
	s_nop 0
	s_nop 0
	s_nop 0
	s_nop 0
	s_nop 0
	s_nop 0
	s_nop 0
	s_nop 0
	s_nop 0
	s_nop 0
	s_nop 0
	s_nop 0
	s_nop 0
	s_nop 0
	s_nop 0
	s_nop 0
	s_nop 0
	s_cmp_gt_i32 s31, 4
	s_cselect_b64 s[0:1], -1, 0
	s_and_b64 s[4:5], s[10:11], s[0:1]
	s_andn2_b64 vcc, exec, s[4:5]
	s_cbranch_vccnz .LBB0_423
	s_waitcnt vmcnt(0)
	s_waitcnt vmcnt(0) lgkmcnt(0)
	s_barrier
	s_and_saveexec_b64 s[4:5], s[8:9]
	s_cbranch_execz .LBB0_422
	s_add_i32 s6, 0, 0x25ff0
	v_mov_b32_e32 v0, s6
	s_waitcnt vmcnt(0) expcnt(0) lgkmcnt(0)
	ds_read_b32 v2, v0
	s_add_i32 s6, 0, 0x25ff4
	v_mov_b32_e32 v0, s6
	ds_read_b32 v0, v0
	s_waitcnt lgkmcnt(1)
	v_cmp_ne_u32_e32 vcc, 0, v2
	s_cbranch_vccnz .LBB0_390
	s_load_dwordx2 s[12:13], s[52:53], 0x4
	s_add_u32 s6, s28, 0x3e800200
	s_addc_u32 s7, s29, 0
	s_add_u32 s10, s28, 0x3e800400
	s_addc_u32 s11, s29, 0
	s_waitcnt lgkmcnt(0)
	s_mul_i32 s60, s12, s3
	s_add_u32 s12, s28, 0x3e800500
	s_mul_i32 s60, s60, s13
	s_addc_u32 s13, s29, 0
	s_add_u32 s14, s28, 0x3e800600
	s_addc_u32 s15, s29, 0
	s_add_u32 s16, s28, 0x3e800700
	s_addc_u32 s17, s29, 0
	s_add_u32 s18, s28, 0x3e800800
	s_addc_u32 s19, s29, 0
	s_add_u32 s20, s28, 0x3e800900
	s_addc_u32 s21, s29, 0
	s_add_u32 s22, s28, 0x3e800a00
	s_addc_u32 s23, s29, 0
	s_add_u32 s24, s28, 0x3e800b00
	s_addc_u32 s25, s29, 0
	s_add_u32 s36, s28, 0x3e800c00
	s_addc_u32 s37, s29, 0
	s_add_u32 s38, s28, 0x3e800d00
	s_addc_u32 s39, s29, 0
	s_add_u32 s40, s28, 0x3e800e00
	s_addc_u32 s41, s29, 0
	s_add_u32 s42, s28, 0x3e800f00
	s_addc_u32 s43, s29, 0
	s_add_u32 s44, s28, 0x3e801000
	s_addc_u32 s45, s29, 0
	s_add_u32 s46, s28, 0x3e801100
	s_addc_u32 s47, s29, 0
	s_add_u32 s48, s28, 0x3e801200
	s_addc_u32 s49, s29, 0
	s_add_u32 s50, s28, 0x3e801300
	s_addc_u32 s51, s29, 0
	s_mov_b32 s61, 1
	v_mov_b32_e32 v16, 0
	s_branch .LBB0_378

; #define PG8_STAGE(bufoff, gbase, voff) do { _Pragma("unroll") for (int _i = 0; _i < 2; ++_i) \
;         __builtin_amdgcn_global_load_lds((const unsigned*)((const char*)(gbase) + (voff)[_i]), (LAS unsigned*)(lds + (bufoff) + ldsw + _i * 8192), 16, 0, 0); } while (0)
; #define PG8_WAIT_V(n) asm volatile("s_waitcnt vmcnt(" #n ")" ::: "memory")
; #define PG8_BAR __builtin_amdgcn_s_barrier()
; template <class Epi, class Ptrs>
; __device__ __forceinline__ void gemm_phase(LAS unsigned char* lds, const int K, const StaticOrder& S, const Ptrs& P, const Epi& E) {
;     ...
;     for (int i = 0; i < 2; ++i) { int R, C; stage_rc(tid * 16 + i * 8192, R, C); const int Rb = (R & ~31) + perm32(R & 31);
;         voffA[i] = (unsigned)(R * K + C) * 2u; voffB[i] = (unsigned)(Rb * K + C) * 2u; }
;     const size_t kstep = (size_t)(BK * 2);
;     const size_t hstep = (size_t)HALF * K * 2;
;     const unsigned ldsw = (unsigned)wid * 1024u;
;     const int aoff = lds_byte(wr * 64 + fr, fq * 8), boff = lds_byte(wc * 32 + fr, fq * 8);
;     ...
;     Unit cur, nxt; int ui = 0;
;     if (!S.next(0, cur)) return;
;     f32x4 acc[2][2][4][2];
; #pragma unroll
;     for (int a = 0; a < 2; ++a)
; #pragma unroll
;         for (int b = 0; b < 2; ++b)
; #pragma unroll
;             for (int m = 0; m < 4; ++m)
; #pragma unroll
;                 for (int n = 0; n < 2; ++n) acc[a][b][m][n] = (f32x4){0.f, 0.f, 0.f, 0.f};
;     bf16x8 At[4][2], B0[2][2], B1[2][2];
;     const char* cA; const char* cB; P.get(cur, cA, cB);
;     PG8_STAGE(PG8_SB(0, 0), cB, voffB); PG8_STAGE(PG8_SA(0, 0), cA, voffA); PG8_STAGE(PG8_SB(0, 1), cB + hstep, voffB); PG8_STAGE(PG8_SA(0, 1), cA + hstep, voffA);
;     if (wr == 1) PG8_BAR;
;     PG8_WAIT_V(4); PG8_BAR;
;     PG8_STAGE(PG8_SB(1, 0), cB + kstep, voffB); PG8_STAGE(PG8_SA(1, 0), cA + kstep, voffA); PG8_STAGE(PG8_SB(1, 1), cB + hstep + kstep, voffB);
;     PG8_WAIT_V(6); PG8_BAR;
.LBB0_427:
	s_nop 0
	s_nop 0
	s_nop 0
	s_nop 0
	s_nop 0
	s_nop 0
	s_nop 0
	s_nop 0
	s_nop 0
	s_nop 0
	s_nop 0
	s_nop 0
	s_nop 0
	s_nop 0
	s_nop 0
	s_nop 0
	s_nop 0
	s_nop 0
	s_nop 0
	s_nop 0
	s_nop 0
	s_nop 0
	s_nop 0
	s_nop 0
	s_nop 0
	s_nop 0
	s_nop 0
	s_nop 0
	s_nop 0
	s_nop 0
	s_nop 0
	s_nop 0
	s_nop 0
	s_nop 0
	s_nop 0
	s_nop 0
	s_nop 0
	s_nop 0
	s_nop 0
	s_nop 0
	s_nop 0
	s_nop 0
	s_nop 0
	s_nop 0
	s_nop 0
	s_nop 0
	s_nop 0
	s_nop 0
	s_nop 0
	s_nop 0
	s_nop 0
	s_nop 0
	s_nop 0
	s_nop 0
	s_nop 0
	s_nop 0
	s_nop 0
	s_add_u32 s10, s28, 0xe000000
	s_addc_u32 s11, s29, 0
	s_lshl_b32 s4, s4, 5
	s_mov_b64 s[12:13], 0x80
	s_and_b32 s15, s4, 0x60
	s_add_i32 m0, s39, 0x18000
	v_lshl_add_u64 v[6:7], v[6:7], 0, s[12:13]
	s_ashr_i32 s60, s3, 31
	s_lshl_b32 s14, s1, 13
	s_lshl_b32 s16, s15, 7
	s_waitcnt vmcnt(4)
	s_barrier
	global_load_lds_dwordx4 v[6:7], off
	v_lshl_add_u64 v[4:5], v[4:5], 0, s[12:13]
	s_add_i32 m0, s39, 0x1a000
	s_add_i32 s61, s39, 0x8000
	s_add_i32 s62, s39, 0xa000
	global_load_lds_dwordx4 v[4:5], off
	v_lshl_add_u64 v[2:3], v[2:3], 0, s[12:13]
	s_mov_b32 m0, s61
	s_add_u32 s4, s42, 0x40080
	global_load_lds_dwordx4 v[2:3], off
	v_lshl_add_u64 v[0:1], v[0:1], 0, s[12:13]
	s_mov_b32 m0, s62
	s_addc_u32 s5, s43, 0
	global_load_lds_dwordx4 v[0:1], off
	s_add_i32 m0, s39, 0x1c000
	v_lshl_add_u64 v[0:1], s[4:5], 0, v[130:131]
	global_load_lds_dwordx4 v[0:1], off
	v_lshl_add_u64 v[0:1], s[4:5], 0, v[134:135]
	s_add_i32 m0, s39, 0x1e000
	s_sext_i32_i8 s69, s0
	global_load_lds_dwordx4 v[0:1], off
	v_and_b32_e32 v0, 15, v208
	v_lshlrev_b32_e32 v1, 1, v11
	v_lshlrev_b32_e32 v2, 6, v208
	s_movk_i32 s0, 0x3c0
	v_lshlrev_b32_e32 v3, 2, v208
	v_and_or_b32 v2, v2, s0, v1
	v_and_b32_e32 v3, 32, v3
	v_lshl_or_b32 v146, s1, 6, v0
	v_lshl_or_b32 v0, v0, 6, v1
	v_lshlrev_b32_e32 v1, 8, v208
	v_bitop3_b32 v147, s16, v2, v3 bitop3:0xf6
	v_and_b32_e32 v1, 0x38000, v1
	v_lshlrev_b32_e32 v2, 11, v10
	v_or3_b32 v1, v8, v1, v2
	v_add_u32_e32 v136, v1, v9
	v_lshlrev_b32_e32 v1, 4, v12
	s_waitcnt vmcnt(6)
	v_and_b32_e32 v1, 0x78000, v1
	v_bitop3_b32 v0, v0, s14, v3 bitop3:0xde
	v_or3_b32 v1, v8, v1, v2
	s_add_i32 s63, 0, 0x10000
	s_add_i32 s64, 0, 0x14000
	v_or_b32_e32 v148, s15, v11
	v_mov_b32_e32 v137, v131
	v_add_u32_e32 v138, v1, v9
	v_mov_b32_e32 v139, v131
	v_mov_b64_e32 v[140:141], 0x1800
	v_mov_b64_e32 v[142:143], 0x17ff
	v_add_u32_e32 v149, s63, v147
	v_add_u32_e32 v150, 0, v0
	v_add_u32_e32 v151, s64, v147
	s_mov_b64 s[14:15], 0x100000
	s_mov_b32 s65, 0x100000
	s_mov_b64 s[16:17], 0x120000
	s_mov_b32 s66, 0x120000
	s_mov_b64 s[18:19], 0x140000
	s_mov_b32 s67, 0x140000
	s_mov_b64 s[20:21], 0x160000
	s_mov_b32 s68, 0x160000
	s_cmpk_lt_u32 s46, 0x100
	s_cbranch_scc1 .Lsprio_2
	s_setprio 1

; #define PG8_STAGE(bufoff, gbase, voff) do { _Pragma("unroll") for (int _i = 0; _i < 2; ++_i) \
;         __builtin_amdgcn_global_load_lds((const unsigned*)((const char*)(gbase) + (voff)[_i]), (LAS unsigned*)(lds + (bufoff) + ldsw + _i * 8192), 16, 0, 0); } while (0)
; #define PG8_LDA(dst, b, h) do { _Pragma("unroll") for (int m = 0; m < 4; ++m) _Pragma("unroll") for (int k = 0; k < 2; ++k) dst[m][k] = *(const LAS bf16x8*)(lds + PG8_SA(b, h) + aoff + m * 2048 + k * 1024); } while (0)
; #define PG8_LDB(dst, b, h) do { _Pragma("unroll") for (int n = 0; n < 2; ++n) _Pragma("unroll") for (int k = 0; k < 2; ++k) dst[n][k] = *(const LAS bf16x8*)(lds + PG8_SB(b, h) + boff + n * 2048 + k * 1024); } while (0)
; #define PG8_MMA(ai, bj, At, Bt) do { __builtin_amdgcn_s_setprio(1); _Pragma("unroll") for (int m = 0; m < 4; ++m) _Pragma("unroll") for (int n = 0; n < 2; ++n) _Pragma("unroll") for (int k = 0; k < 2; ++k) \
;         acc[ai][bj][m][n] = __builtin_amdgcn_mfma_f32_16x16x32_bf16(Bt[n][k], At[m][k], acc[ai][bj][m][n], 0, 0, 0); __builtin_amdgcn_s_setprio(0); } while (0)
; #define PG8_WAIT_V(n) asm volatile("s_waitcnt vmcnt(" #n ")" ::: "memory")
; #define PG8_WAIT_L(n) asm volatile("s_waitcnt lgkmcnt(" #n ")" ::: "memory")
; template <class Epi, class Ptrs>
; __device__ __forceinline__ void gemm_phase(LAS unsigned char* lds, const int K, const StaticOrder& S, const Ptrs& P, const Epi& E) {
;     ...
;         for (int t = 0; t < nt; t += 2) {
;             const bool last = (t == nt - 2);
;             const char* a1 = cA + (size_t)(t + 1) * kstep;
;             const char* a2 = last ? nA : cA + (size_t)(t + 2) * kstep; const char* b2 = last ? nB : cB + (size_t)(t + 2) * kstep;
;             const char* a3 = a2 + kstep; const char* b3 = b2 + kstep;
;             PG8_LDB(B0, 0, 0); PG8_SCHED; PG8_LDA(At, 0, 0); PG8_STAGE(PG8_SA(1, 1), a1 + hstep, voffA);
;             PG8_WAIT_L(8); PG8_BAR; PG8_WAIT_L(0); PG8_MMA(0, 0, At, B0); PG8_BAR; PG8_SCHED;
;             PG8_LDB(B1, 0, 1); PG8_STAGE(PG8_SB(0, 0), b2, voffB);
;             PG8_BAR; PG8_WAIT_L(0); PG8_MMA(0, 1, At, B1); PG8_BAR;
;             PG8_LDA(At, 0, 1); PG8_STAGE(PG8_SA(0, 0), a2, voffA);
;             PG8_BAR; PG8_WAIT_L(0); PG8_MMA(1, 0, At, B0); PG8_BAR; PG8_SCHED;
;             PG8_STAGE(PG8_SB(0, 1), b2 + hstep, voffB);
;             PG8_WAIT_V(6); PG8_BAR; PG8_MMA(1, 1, At, B1); PG8_BAR;
.LBB0_432:
	s_add_u32 s40, s40, 0x40080
	s_addc_u32 s41, s41, 0
	s_add_u32 s23, s42, 0x100
	s_addc_u32 s25, s43, 0
	s_mov_b32 s70, -2
	v_add_u32_e32 v252, 0x18000, v147
	v_add_u32_e32 v253, 0x1c000, v147
	ds_read_b128 v[152:155], v149
	ds_read_b128 v[156:159], v149 offset:1024
	ds_read_b128 v[160:163], v149 offset:2048
	ds_read_b128 v[164:167], v149 offset:3072
	s_add_u32 s42, s40, 0xfffc0080
	s_addc_u32 s43, s41, -1
	s_cmp_eq_u32 s70, 12
	s_cselect_b32 s45, s1, s43
	s_cselect_b32 s44, s0, s42
	s_cselect_b32 s43, s37, s25
	s_cselect_b32 s42, s36, s23
	s_add_i32 m0, s39, 0xc000
	ds_read_b128 v[168:171], v150
	ds_read_b128 v[172:175], v150 offset:1024
	ds_read_b128 v[176:179], v150 offset:2048
	ds_read_b128 v[180:183], v150 offset:3072
	ds_read_b128 v[184:187], v150 offset:4096
	ds_read_b128 v[188:191], v150 offset:5120
	ds_read_b128 v[192:195], v150 offset:6144
	ds_read_b128 v[196:199], v150 offset:7168
	global_load_lds_dwordx4 v136, s[40:41]
	s_add_i32 m0, s39, 0xe000
	s_nop 0
	global_load_lds_dwordx4 v138, s[40:41]
	s_barrier
	s_waitcnt lgkmcnt(0)
	v_mfma_f32_16x16x32_bf16 v[124:127], v[152:155], v[168:171], 0
	v_mfma_f32_16x16x32_bf16 v[124:127], v[156:159], v[172:175], v[124:127]
	v_mfma_f32_16x16x32_bf16 v[120:123], v[164:167], v[172:175], 0
	v_mfma_f32_16x16x32_bf16 v[120:123], v[160:163], v[168:171], v[120:123]
	v_mfma_f32_16x16x32_bf16 v[104:107], v[160:163], v[176:179], 0
	v_mfma_f32_16x16x32_bf16 v[104:107], v[164:167], v[180:183], v[104:107]
	v_mfma_f32_16x16x32_bf16 v[108:111], v[156:159], v[180:183], 0
	v_mfma_f32_16x16x32_bf16 v[108:111], v[152:155], v[176:179], v[108:111]
	v_mfma_f32_16x16x32_bf16 v[92:95], v[152:155], v[184:187], 0
	v_mfma_f32_16x16x32_bf16 v[92:95], v[156:159], v[188:191], v[92:95]
	v_mfma_f32_16x16x32_bf16 v[88:91], v[164:167], v[188:191], 0
	v_mfma_f32_16x16x32_bf16 v[88:91], v[160:163], v[184:187], v[88:91]
	v_mfma_f32_16x16x32_bf16 v[72:75], v[160:163], v[192:195], 0
	v_mfma_f32_16x16x32_bf16 v[72:75], v[164:167], v[196:199], v[72:75]
	v_mfma_f32_16x16x32_bf16 v[76:79], v[156:159], v[196:199], 0
	v_mfma_f32_16x16x32_bf16 v[76:79], v[152:155], v[192:195], v[76:79]
	s_barrier
	s_add_i32 s71, s63, s51
	s_add_u32 s76, s42, 0x80
	s_addc_u32 s77, s43, 0
	s_mov_b32 m0, s71
	ds_read_b128 v[200:203], v151
	ds_read_b128 v[204:207], v151 offset:1024
	ds_read_b128 v[210:213], v151 offset:2048
	ds_read_b128 v[214:217], v151 offset:3072
	global_load_lds_dwordx4 v130, s[42:43]
	s_add_i32 m0, s71, 0x2000
	s_nop 0
	global_load_lds_dwordx4 v134, s[42:43]
	s_barrier
	s_waitcnt lgkmcnt(0)
	v_mfma_f32_16x16x32_bf16 v[116:119], v[200:203], v[168:171], 0
	v_mfma_f32_16x16x32_bf16 v[116:119], v[204:207], v[172:175], v[116:119]
	v_mfma_f32_16x16x32_bf16 v[112:115], v[214:217], v[172:175], 0
	v_mfma_f32_16x16x32_bf16 v[112:115], v[210:213], v[168:171], v[112:115]
	v_mfma_f32_16x16x32_bf16 v[96:99], v[210:213], v[176:179], 0
	v_mfma_f32_16x16x32_bf16 v[96:99], v[214:217], v[180:183], v[96:99]
	v_mfma_f32_16x16x32_bf16 v[100:103], v[204:207], v[180:183], 0
	v_mfma_f32_16x16x32_bf16 v[100:103], v[200:203], v[176:179], v[100:103]
	v_mfma_f32_16x16x32_bf16 v[84:87], v[200:203], v[184:187], 0
	v_mfma_f32_16x16x32_bf16 v[84:87], v[204:207], v[188:191], v[84:87]
	v_mfma_f32_16x16x32_bf16 v[80:83], v[214:217], v[188:191], 0
	v_mfma_f32_16x16x32_bf16 v[80:83], v[210:213], v[184:187], v[80:83]
	v_mfma_f32_16x16x32_bf16 v[64:67], v[210:213], v[192:195], 0
	v_mfma_f32_16x16x32_bf16 v[64:67], v[214:217], v[196:199], v[64:67]
	v_mfma_f32_16x16x32_bf16 v[68:71], v[204:207], v[196:199], 0
	v_mfma_f32_16x16x32_bf16 v[68:71], v[200:203], v[192:195], v[68:71]
	s_barrier
	s_mov_b32 m0, s39
	s_add_u32 s78, s44, 0x80
	s_addc_u32 s79, s45, 0
	ds_read_b128 v[168:171], v150 offset:16384
	ds_read_b128 v[172:175], v150 offset:17408
	ds_read_b128 v[176:179], v150 offset:18432
	ds_read_b128 v[180:183], v150 offset:19456
	ds_read_b128 v[184:187], v150 offset:20480
	ds_read_b128 v[188:191], v150 offset:21504
	ds_read_b128 v[192:195], v150 offset:22528
	ds_read_b128 v[196:199], v150 offset:23552
	global_load_lds_dwordx4 v128, s[44:45]
	s_mov_b32 m0, s56
	s_nop 0
	global_load_lds_dwordx4 v132, s[44:45]
	s_barrier
	s_waitcnt lgkmcnt(0)
	v_mfma_f32_16x16x32_bf16 v[60:63], v[152:155], v[168:171], 0
	v_mfma_f32_16x16x32_bf16 v[60:63], v[156:159], v[172:175], v[60:63]
	v_mfma_f32_16x16x32_bf16 v[56:59], v[164:167], v[172:175], 0
	v_mfma_f32_16x16x32_bf16 v[56:59], v[160:163], v[168:171], v[56:59]
	v_mfma_f32_16x16x32_bf16 v[40:43], v[160:163], v[176:179], 0
	v_mfma_f32_16x16x32_bf16 v[40:43], v[164:167], v[180:183], v[40:43]
	v_mfma_f32_16x16x32_bf16 v[44:47], v[156:159], v[180:183], 0
	v_mfma_f32_16x16x32_bf16 v[44:47], v[152:155], v[176:179], v[44:47]
	v_mfma_f32_16x16x32_bf16 v[28:31], v[152:155], v[184:187], 0
	v_mfma_f32_16x16x32_bf16 v[28:31], v[156:159], v[188:191], v[28:31]
	v_mfma_f32_16x16x32_bf16 v[24:27], v[164:167], v[188:191], 0
	v_mfma_f32_16x16x32_bf16 v[24:27], v[160:163], v[184:187], v[24:27]
	v_mfma_f32_16x16x32_bf16 v[8:11], v[160:163], v[192:195], 0
	v_mfma_f32_16x16x32_bf16 v[8:11], v[164:167], v[196:199], v[8:11]
	v_mfma_f32_16x16x32_bf16 v[12:15], v[156:159], v[196:199], 0
	v_mfma_f32_16x16x32_bf16 v[12:15], v[152:155], v[192:195], v[12:15]
	s_barrier
	s_add_u32 s72, s42, 0x40000
	s_addc_u32 s73, s43, 0
	s_add_i32 s71, s64, s51
	s_mov_b32 m0, s71
	s_nop 0
	global_load_lds_dwordx4 v130, s[72:73]
	s_add_i32 m0, s71, 0x2000
	s_nop 0
	global_load_lds_dwordx4 v134, s[72:73]
	s_waitcnt vmcnt(6)
	s_barrier
; #define PG8_STAGE(bufoff, gbase, voff) do { _Pragma("unroll") for (int _i = 0; _i < 2; ++_i) \
;         __builtin_amdgcn_global_load_lds((const unsigned*)((const char*)(gbase) + (voff)[_i]), (LAS unsigned*)(lds + (bufoff) + ldsw + _i * 8192), 16, 0, 0); } while (0)
; #define PG8_LDA(dst, b, h) do { _Pragma("unroll") for (int m = 0; m < 4; ++m) _Pragma("unroll") for (int k = 0; k < 2; ++k) dst[m][k] = *(const LAS bf16x8*)(lds + PG8_SA(b, h) + aoff + m * 2048 + k * 1024); } while (0)
; #define PG8_LDB(dst, b, h) do { _Pragma("unroll") for (int n = 0; n < 2; ++n) _Pragma("unroll") for (int k = 0; k < 2; ++k) dst[n][k] = *(const LAS bf16x8*)(lds + PG8_SB(b, h) + boff + n * 2048 + k * 1024); } while (0)
; #define PG8_MMA(ai, bj, At, Bt) do { __builtin_amdgcn_s_setprio(1); _Pragma("unroll") for (int m = 0; m < 4; ++m) _Pragma("unroll") for (int n = 0; n < 2; ++n) _Pragma("unroll") for (int k = 0; k < 2; ++k) \
;         acc[ai][bj][m][n] = __builtin_amdgcn_mfma_f32_16x16x32_bf16(Bt[n][k], At[m][k], acc[ai][bj][m][n], 0, 0, 0); __builtin_amdgcn_s_setprio(0); } while (0)
; #define PG8_WAIT_V(n) asm volatile("s_waitcnt vmcnt(" #n ")" ::: "memory")
; #define PG8_WAIT_L(n) asm volatile("s_waitcnt lgkmcnt(" #n ")" ::: "memory")
; #define PG8_BAR __builtin_amdgcn_s_barrier()
; #define PG8_SCHED __builtin_amdgcn_sched_barrier(0)
; template <class Epi, class Ptrs>
; __device__ __forceinline__ void gemm_phase(LAS unsigned char* lds, const int K, const StaticOrder& S, const Ptrs& P, const Epi& E) {
;     ...
;             PG8_WAIT_V(6); PG8_BAR; PG8_MMA(1, 1, At, B1); PG8_BAR;
;             PG8_LDB(B0, 1, 0); PG8_SCHED; PG8_LDA(At, 1, 0); PG8_STAGE(PG8_SA(0, 1), a2 + hstep, voffA);
;             PG8_WAIT_L(8); PG8_BAR; PG8_WAIT_L(0); PG8_MMA(0, 0, At, B0); PG8_BAR; PG8_SCHED;
;             PG8_LDB(B1, 1, 1); PG8_STAGE(PG8_SB(1, 0), b3, voffB);
;             PG8_BAR; PG8_WAIT_L(0); PG8_MMA(0, 1, At, B1); PG8_BAR;
;             PG8_LDA(At, 1, 1); PG8_STAGE(PG8_SA(1, 0), a3, voffA);
;             PG8_BAR; PG8_WAIT_L(0); PG8_MMA(1, 0, At, B0); PG8_BAR; PG8_SCHED;
;             PG8_STAGE(PG8_SB(1, 1), b3 + hstep, voffB);
;             PG8_WAIT_V(6); PG8_BAR; PG8_MMA(1, 1, At, B1); PG8_BAR;
	v_mfma_f32_16x16x32_bf16 v[52:55], v[200:203], v[168:171], 0
	v_mfma_f32_16x16x32_bf16 v[52:55], v[204:207], v[172:175], v[52:55]
	v_mfma_f32_16x16x32_bf16 v[48:51], v[214:217], v[172:175], 0
	v_mfma_f32_16x16x32_bf16 v[48:51], v[210:213], v[168:171], v[48:51]
	v_mfma_f32_16x16x32_bf16 v[32:35], v[210:213], v[176:179], 0
	v_mfma_f32_16x16x32_bf16 v[32:35], v[214:217], v[180:183], v[32:35]
	v_mfma_f32_16x16x32_bf16 v[36:39], v[204:207], v[180:183], 0
	v_mfma_f32_16x16x32_bf16 v[36:39], v[200:203], v[176:179], v[36:39]
	v_mfma_f32_16x16x32_bf16 v[20:23], v[200:203], v[184:187], 0
	v_mfma_f32_16x16x32_bf16 v[20:23], v[204:207], v[188:191], v[20:23]
	v_mfma_f32_16x16x32_bf16 v[16:19], v[214:217], v[188:191], 0
	v_mfma_f32_16x16x32_bf16 v[16:19], v[210:213], v[184:187], v[16:19]
	v_mfma_f32_16x16x32_bf16 v[0:3], v[210:213], v[192:195], 0
	v_mfma_f32_16x16x32_bf16 v[0:3], v[214:217], v[196:199], v[0:3]
	v_mfma_f32_16x16x32_bf16 v[4:7], v[204:207], v[196:199], 0
	v_mfma_f32_16x16x32_bf16 v[4:7], v[200:203], v[192:195], v[4:7]
	s_barrier
	s_add_i32 s71, 0, 0x18000
	ds_read_b128 v[152:155], v252
	ds_read_b128 v[156:159], v252 offset:1024
	ds_read_b128 v[160:163], v252 offset:2048
	ds_read_b128 v[164:167], v252 offset:3072
	s_add_u32 s44, s44, 0x40000
	s_addc_u32 s45, s45, 0
	s_mov_b32 m0, s57
	ds_read_b128 v[168:171], v150 offset:32768
	ds_read_b128 v[172:175], v150 offset:33792
	ds_read_b128 v[176:179], v150 offset:34816
	ds_read_b128 v[180:183], v150 offset:35840
	ds_read_b128 v[184:187], v150 offset:36864
	ds_read_b128 v[188:191], v150 offset:37888
	ds_read_b128 v[192:195], v150 offset:38912
	ds_read_b128 v[196:199], v150 offset:39936
	global_load_lds_dwordx4 v128, s[44:45]
	s_mov_b32 m0, s58
	s_nop 0
	global_load_lds_dwordx4 v132, s[44:45]
	s_barrier
	s_waitcnt lgkmcnt(0)
	v_mfma_f32_16x16x32_bf16 v[124:127], v[152:155], v[168:171], v[124:127]
	v_mfma_f32_16x16x32_bf16 v[124:127], v[156:159], v[172:175], v[124:127]
	v_mfma_f32_16x16x32_bf16 v[120:123], v[164:167], v[172:175], v[120:123]
	v_mfma_f32_16x16x32_bf16 v[120:123], v[160:163], v[168:171], v[120:123]
	v_mfma_f32_16x16x32_bf16 v[104:107], v[160:163], v[176:179], v[104:107]
	v_mfma_f32_16x16x32_bf16 v[104:107], v[164:167], v[180:183], v[104:107]
	v_mfma_f32_16x16x32_bf16 v[108:111], v[156:159], v[180:183], v[108:111]
	v_mfma_f32_16x16x32_bf16 v[108:111], v[152:155], v[176:179], v[108:111]
	v_mfma_f32_16x16x32_bf16 v[92:95], v[152:155], v[184:187], v[92:95]
	v_mfma_f32_16x16x32_bf16 v[92:95], v[156:159], v[188:191], v[92:95]
	v_mfma_f32_16x16x32_bf16 v[88:91], v[164:167], v[188:191], v[88:91]
	v_mfma_f32_16x16x32_bf16 v[88:91], v[160:163], v[184:187], v[88:91]
	v_mfma_f32_16x16x32_bf16 v[72:75], v[160:163], v[192:195], v[72:75]
	v_mfma_f32_16x16x32_bf16 v[72:75], v[164:167], v[196:199], v[72:75]
	v_mfma_f32_16x16x32_bf16 v[76:79], v[156:159], v[196:199], v[76:79]
	v_mfma_f32_16x16x32_bf16 v[76:79], v[152:155], v[192:195], v[76:79]
	s_barrier
	s_add_i32 s44, 0, 0x1c000
	s_add_i32 s45, s71, s51
	s_mov_b32 m0, s45
	ds_read_b128 v[200:203], v253
	ds_read_b128 v[204:207], v253 offset:1024
	ds_read_b128 v[210:213], v253 offset:2048
	ds_read_b128 v[214:217], v253 offset:3072
	global_load_lds_dwordx4 v130, s[76:77]
	s_add_i32 m0, s45, 0x2000
	s_nop 0
	global_load_lds_dwordx4 v134, s[76:77]
	s_barrier
	s_waitcnt lgkmcnt(0)
	v_mfma_f32_16x16x32_bf16 v[116:119], v[200:203], v[168:171], v[116:119]
	v_mfma_f32_16x16x32_bf16 v[116:119], v[204:207], v[172:175], v[116:119]
	v_mfma_f32_16x16x32_bf16 v[112:115], v[214:217], v[172:175], v[112:115]
	v_mfma_f32_16x16x32_bf16 v[112:115], v[210:213], v[168:171], v[112:115]
	v_mfma_f32_16x16x32_bf16 v[96:99], v[210:213], v[176:179], v[96:99]
	v_mfma_f32_16x16x32_bf16 v[96:99], v[214:217], v[180:183], v[96:99]
	v_mfma_f32_16x16x32_bf16 v[100:103], v[204:207], v[180:183], v[100:103]
	v_mfma_f32_16x16x32_bf16 v[100:103], v[200:203], v[176:179], v[100:103]
	v_mfma_f32_16x16x32_bf16 v[84:87], v[200:203], v[184:187], v[84:87]
	v_mfma_f32_16x16x32_bf16 v[84:87], v[204:207], v[188:191], v[84:87]
	v_mfma_f32_16x16x32_bf16 v[80:83], v[214:217], v[188:191], v[80:83]
	v_mfma_f32_16x16x32_bf16 v[80:83], v[210:213], v[184:187], v[80:83]
	v_mfma_f32_16x16x32_bf16 v[64:67], v[210:213], v[192:195], v[64:67]
	v_mfma_f32_16x16x32_bf16 v[64:67], v[214:217], v[196:199], v[64:67]
	v_mfma_f32_16x16x32_bf16 v[68:71], v[204:207], v[196:199], v[68:71]
	v_mfma_f32_16x16x32_bf16 v[68:71], v[200:203], v[192:195], v[68:71]
	s_barrier
	s_mov_b32 m0, s61
	ds_read_b128 v[168:171], v150 offset:49152
	ds_read_b128 v[172:175], v150 offset:50176
	ds_read_b128 v[176:179], v150 offset:51200
	ds_read_b128 v[180:183], v150 offset:52224
	ds_read_b128 v[184:187], v150 offset:53248
	ds_read_b128 v[188:191], v150 offset:54272
	ds_read_b128 v[192:195], v150 offset:55296
	ds_read_b128 v[196:199], v150 offset:56320
	global_load_lds_dwordx4 v128, s[78:79]
	s_mov_b32 m0, s62
	s_nop 0
	global_load_lds_dwordx4 v132, s[78:79]
	s_barrier
	s_waitcnt lgkmcnt(0)
	v_mfma_f32_16x16x32_bf16 v[60:63], v[152:155], v[168:171], v[60:63]
	v_mfma_f32_16x16x32_bf16 v[60:63], v[156:159], v[172:175], v[60:63]
	v_mfma_f32_16x16x32_bf16 v[56:59], v[164:167], v[172:175], v[56:59]
	v_mfma_f32_16x16x32_bf16 v[56:59], v[160:163], v[168:171], v[56:59]
	v_mfma_f32_16x16x32_bf16 v[40:43], v[160:163], v[176:179], v[40:43]
	v_mfma_f32_16x16x32_bf16 v[40:43], v[164:167], v[180:183], v[40:43]
	v_mfma_f32_16x16x32_bf16 v[44:47], v[156:159], v[180:183], v[44:47]
	v_mfma_f32_16x16x32_bf16 v[44:47], v[152:155], v[176:179], v[44:47]
	v_mfma_f32_16x16x32_bf16 v[28:31], v[152:155], v[184:187], v[28:31]
	v_mfma_f32_16x16x32_bf16 v[28:31], v[156:159], v[188:191], v[28:31]
	v_mfma_f32_16x16x32_bf16 v[24:27], v[164:167], v[188:191], v[24:27]
	v_mfma_f32_16x16x32_bf16 v[24:27], v[160:163], v[184:187], v[24:27]
	v_mfma_f32_16x16x32_bf16 v[8:11], v[160:163], v[192:195], v[8:11]
	v_mfma_f32_16x16x32_bf16 v[8:11], v[164:167], v[196:199], v[8:11]
	v_mfma_f32_16x16x32_bf16 v[12:15], v[156:159], v[196:199], v[12:15]
	v_mfma_f32_16x16x32_bf16 v[12:15], v[152:155], v[192:195], v[12:15]
	s_barrier
; #define PG8_STAGE(bufoff, gbase, voff) do { _Pragma("unroll") for (int _i = 0; _i < 2; ++_i) \
;         __builtin_amdgcn_global_load_lds((const unsigned*)((const char*)(gbase) + (voff)[_i]), (LAS unsigned*)(lds + (bufoff) + ldsw + _i * 8192), 16, 0, 0); } while (0)
; #define PG8_LDA(dst, b, h) do { _Pragma("unroll") for (int m = 0; m < 4; ++m) _Pragma("unroll") for (int k = 0; k < 2; ++k) dst[m][k] = *(const LAS bf16x8*)(lds + PG8_SA(b, h) + aoff + m * 2048 + k * 1024); } while (0)
; #define PG8_LDB(dst, b, h) do { _Pragma("unroll") for (int n = 0; n < 2; ++n) _Pragma("unroll") for (int k = 0; k < 2; ++k) dst[n][k] = *(const LAS bf16x8*)(lds + PG8_SB(b, h) + boff + n * 2048 + k * 1024); } while (0)
; #define PG8_MMA(ai, bj, At, Bt) do { __builtin_amdgcn_s_setprio(1); _Pragma("unroll") for (int m = 0; m < 4; ++m) _Pragma("unroll") for (int n = 0; n < 2; ++n) _Pragma("unroll") for (int k = 0; k < 2; ++k) \
;         acc[ai][bj][m][n] = __builtin_amdgcn_mfma_f32_16x16x32_bf16(Bt[n][k], At[m][k], acc[ai][bj][m][n], 0, 0, 0); __builtin_amdgcn_s_setprio(0); } while (0)
; #define PG8_WAIT_V(n) asm volatile("s_waitcnt vmcnt(" #n ")" ::: "memory")
; #define PG8_WAIT_L(n) asm volatile("s_waitcnt lgkmcnt(" #n ")" ::: "memory")
; #define PG8_BAR __builtin_amdgcn_s_barrier()
; #define PG8_SCHED __builtin_amdgcn_sched_barrier(0)
; template <class Epi, class Ptrs>
; __device__ __forceinline__ void gemm_phase(LAS unsigned char* lds, const int K, const StaticOrder& S, const Ptrs& P, const Epi& E) {
;     ...
;             PG8_LDB(B0, 0, 0); PG8_SCHED; PG8_LDA(At, 0, 0); PG8_STAGE(PG8_SA(1, 1), a1 + hstep, voffA);
;             PG8_WAIT_L(8); PG8_BAR; PG8_WAIT_L(0); PG8_MMA(0, 0, At, B0); PG8_BAR; PG8_SCHED;
;             PG8_LDB(B1, 0, 1); PG8_STAGE(PG8_SB(0, 0), b2, voffB);
;             PG8_BAR; PG8_WAIT_L(0); PG8_MMA(0, 1, At, B1); PG8_BAR;
;             PG8_LDA(At, 0, 1); PG8_STAGE(PG8_SA(0, 0), a2, voffA);
;             PG8_BAR; PG8_WAIT_L(0); PG8_MMA(1, 0, At, B0); PG8_BAR; PG8_SCHED;
;     ...
;             PG8_STAGE(PG8_SB(1, 1), b3 + hstep, voffB);
;             PG8_WAIT_V(6); PG8_BAR; PG8_MMA(1, 1, At, B1); PG8_BAR;
	s_add_u32 s42, s42, 0x40080
	s_addc_u32 s43, s43, 0
	s_add_i32 s44, s44, s51
	s_mov_b32 m0, s44
	s_nop 0
	global_load_lds_dwordx4 v130, s[42:43]
	s_add_i32 m0, s44, 0x2000
	s_nop 0
	global_load_lds_dwordx4 v134, s[42:43]
	s_waitcnt vmcnt(6)
	s_barrier
	v_mfma_f32_16x16x32_bf16 v[52:55], v[200:203], v[168:171], v[52:55]
	v_mfma_f32_16x16x32_bf16 v[52:55], v[204:207], v[172:175], v[52:55]
	v_mfma_f32_16x16x32_bf16 v[48:51], v[214:217], v[172:175], v[48:51]
	v_mfma_f32_16x16x32_bf16 v[48:51], v[210:213], v[168:171], v[48:51]
	v_mfma_f32_16x16x32_bf16 v[32:35], v[210:213], v[176:179], v[32:35]
	v_mfma_f32_16x16x32_bf16 v[32:35], v[214:217], v[180:183], v[32:35]
	v_mfma_f32_16x16x32_bf16 v[36:39], v[204:207], v[180:183], v[36:39]
	v_mfma_f32_16x16x32_bf16 v[36:39], v[200:203], v[176:179], v[36:39]
	v_mfma_f32_16x16x32_bf16 v[20:23], v[200:203], v[184:187], v[20:23]
	v_mfma_f32_16x16x32_bf16 v[20:23], v[204:207], v[188:191], v[20:23]
	v_mfma_f32_16x16x32_bf16 v[16:19], v[214:217], v[188:191], v[16:19]
	v_mfma_f32_16x16x32_bf16 v[16:19], v[210:213], v[184:187], v[16:19]
	v_mfma_f32_16x16x32_bf16 v[0:3], v[210:213], v[192:195], v[0:3]
	v_mfma_f32_16x16x32_bf16 v[0:3], v[214:217], v[196:199], v[0:3]
	v_mfma_f32_16x16x32_bf16 v[4:7], v[204:207], v[196:199], v[4:7]
	v_mfma_f32_16x16x32_bf16 v[4:7], v[200:203], v[192:195], v[4:7]
	s_barrier
	s_add_i32 s70, s70, 2
	s_add_u32 s40, s40, 0x100
	s_addc_u32 s41, s41, 0
	s_add_u32 s23, s23, 0x100
	s_addc_u32 s25, s25, 0
	s_cmp_gt_u32 s70, 13
.LBB0_433:
	ds_read_b128 v[152:155], v149
	ds_read_b128 v[156:159], v149 offset:1024
	ds_read_b128 v[160:163], v149 offset:2048
	ds_read_b128 v[164:167], v149 offset:3072
	s_add_u32 s42, s40, 0xfffc0080
	s_addc_u32 s43, s41, -1
	s_cmp_eq_u32 s70, 12
	s_cselect_b32 s45, s1, s43
	s_cselect_b32 s44, s0, s42
	s_cselect_b32 s43, s37, s25
	s_cselect_b32 s42, s36, s23
	s_add_i32 m0, s39, 0xc000
	ds_read_b128 v[168:171], v150
	ds_read_b128 v[172:175], v150 offset:1024
	ds_read_b128 v[176:179], v150 offset:2048
	ds_read_b128 v[180:183], v150 offset:3072
	ds_read_b128 v[184:187], v150 offset:4096
	ds_read_b128 v[188:191], v150 offset:5120
	ds_read_b128 v[192:195], v150 offset:6144
	ds_read_b128 v[196:199], v150 offset:7168
	global_load_lds_dwordx4 v136, s[40:41]
	s_add_i32 m0, s39, 0xe000
	s_nop 0
	global_load_lds_dwordx4 v138, s[40:41]
	s_barrier
	s_waitcnt lgkmcnt(0)
	v_mfma_f32_16x16x32_bf16 v[124:127], v[152:155], v[168:171], v[124:127]
	v_mfma_f32_16x16x32_bf16 v[124:127], v[156:159], v[172:175], v[124:127]
	v_mfma_f32_16x16x32_bf16 v[120:123], v[164:167], v[172:175], v[120:123]
	v_mfma_f32_16x16x32_bf16 v[120:123], v[160:163], v[168:171], v[120:123]
	v_mfma_f32_16x16x32_bf16 v[104:107], v[160:163], v[176:179], v[104:107]
	v_mfma_f32_16x16x32_bf16 v[104:107], v[164:167], v[180:183], v[104:107]
	v_mfma_f32_16x16x32_bf16 v[108:111], v[156:159], v[180:183], v[108:111]
	v_mfma_f32_16x16x32_bf16 v[108:111], v[152:155], v[176:179], v[108:111]
	v_mfma_f32_16x16x32_bf16 v[92:95], v[152:155], v[184:187], v[92:95]
	v_mfma_f32_16x16x32_bf16 v[92:95], v[156:159], v[188:191], v[92:95]
	v_mfma_f32_16x16x32_bf16 v[88:91], v[164:167], v[188:191], v[88:91]
	v_mfma_f32_16x16x32_bf16 v[88:91], v[160:163], v[184:187], v[88:91]
	v_mfma_f32_16x16x32_bf16 v[72:75], v[160:163], v[192:195], v[72:75]
	v_mfma_f32_16x16x32_bf16 v[72:75], v[164:167], v[196:199], v[72:75]
	v_mfma_f32_16x16x32_bf16 v[76:79], v[156:159], v[196:199], v[76:79]
	v_mfma_f32_16x16x32_bf16 v[76:79], v[152:155], v[192:195], v[76:79]
	s_barrier
	s_add_i32 s71, s63, s51
	s_add_u32 s76, s42, 0x80
	s_addc_u32 s77, s43, 0
	s_mov_b32 m0, s71
	ds_read_b128 v[200:203], v151
	ds_read_b128 v[204:207], v151 offset:1024
	ds_read_b128 v[210:213], v151 offset:2048
	ds_read_b128 v[214:217], v151 offset:3072
	global_load_lds_dwordx4 v130, s[42:43]
	s_add_i32 m0, s71, 0x2000
	s_nop 0
	global_load_lds_dwordx4 v134, s[42:43]
	s_barrier
	s_waitcnt lgkmcnt(0)
	v_mfma_f32_16x16x32_bf16 v[116:119], v[200:203], v[168:171], v[116:119]
	v_mfma_f32_16x16x32_bf16 v[116:119], v[204:207], v[172:175], v[116:119]
	v_mfma_f32_16x16x32_bf16 v[112:115], v[214:217], v[172:175], v[112:115]
	v_mfma_f32_16x16x32_bf16 v[112:115], v[210:213], v[168:171], v[112:115]
	v_mfma_f32_16x16x32_bf16 v[96:99], v[210:213], v[176:179], v[96:99]
	v_mfma_f32_16x16x32_bf16 v[96:99], v[214:217], v[180:183], v[96:99]
	v_mfma_f32_16x16x32_bf16 v[100:103], v[204:207], v[180:183], v[100:103]
	v_mfma_f32_16x16x32_bf16 v[100:103], v[200:203], v[176:179], v[100:103]
	v_mfma_f32_16x16x32_bf16 v[84:87], v[200:203], v[184:187], v[84:87]
	v_mfma_f32_16x16x32_bf16 v[84:87], v[204:207], v[188:191], v[84:87]
	v_mfma_f32_16x16x32_bf16 v[80:83], v[214:217], v[188:191], v[80:83]
	v_mfma_f32_16x16x32_bf16 v[80:83], v[210:213], v[184:187], v[80:83]
	v_mfma_f32_16x16x32_bf16 v[64:67], v[210:213], v[192:195], v[64:67]
	v_mfma_f32_16x16x32_bf16 v[64:67], v[214:217], v[196:199], v[64:67]
	v_mfma_f32_16x16x32_bf16 v[68:71], v[204:207], v[196:199], v[68:71]
	v_mfma_f32_16x16x32_bf16 v[68:71], v[200:203], v[192:195], v[68:71]
	s_barrier
	s_mov_b32 m0, s39
	s_add_u32 s78, s44, 0x80
	s_addc_u32 s79, s45, 0
	ds_read_b128 v[168:171], v150 offset:16384
	ds_read_b128 v[172:175], v150 offset:17408
	ds_read_b128 v[176:179], v150 offset:18432
	ds_read_b128 v[180:183], v150 offset:19456
	ds_read_b128 v[184:187], v150 offset:20480
	ds_read_b128 v[188:191], v150 offset:21504
	ds_read_b128 v[192:195], v150 offset:22528
	ds_read_b128 v[196:199], v150 offset:23552
	global_load_lds_dwordx4 v128, s[44:45]
	s_mov_b32 m0, s56
	s_nop 0
	global_load_lds_dwordx4 v132, s[44:45]
	s_barrier
; #define PG8_STAGE(bufoff, gbase, voff) do { _Pragma("unroll") for (int _i = 0; _i < 2; ++_i) \
;         __builtin_amdgcn_global_load_lds((const unsigned*)((const char*)(gbase) + (voff)[_i]), (LAS unsigned*)(lds + (bufoff) + ldsw + _i * 8192), 16, 0, 0); } while (0)
; #define PG8_LDA(dst, b, h) do { _Pragma("unroll") for (int m = 0; m < 4; ++m) _Pragma("unroll") for (int k = 0; k < 2; ++k) dst[m][k] = *(const LAS bf16x8*)(lds + PG8_SA(b, h) + aoff + m * 2048 + k * 1024); } while (0)
; #define PG8_LDB(dst, b, h) do { _Pragma("unroll") for (int n = 0; n < 2; ++n) _Pragma("unroll") for (int k = 0; k < 2; ++k) dst[n][k] = *(const LAS bf16x8*)(lds + PG8_SB(b, h) + boff + n * 2048 + k * 1024); } while (0)
; #define PG8_MMA(ai, bj, At, Bt) do { __builtin_amdgcn_s_setprio(1); _Pragma("unroll") for (int m = 0; m < 4; ++m) _Pragma("unroll") for (int n = 0; n < 2; ++n) _Pragma("unroll") for (int k = 0; k < 2; ++k) \
;         acc[ai][bj][m][n] = __builtin_amdgcn_mfma_f32_16x16x32_bf16(Bt[n][k], At[m][k], acc[ai][bj][m][n], 0, 0, 0); __builtin_amdgcn_s_setprio(0); } while (0)
; #define PG8_WAIT_V(n) asm volatile("s_waitcnt vmcnt(" #n ")" ::: "memory")
; #define PG8_WAIT_L(n) asm volatile("s_waitcnt lgkmcnt(" #n ")" ::: "memory")
; #define PG8_BAR __builtin_amdgcn_s_barrier()
; #define PG8_SCHED __builtin_amdgcn_sched_barrier(0)
; template <class Epi, class Ptrs>
; __device__ __forceinline__ void gemm_phase(LAS unsigned char* lds, const int K, const StaticOrder& S, const Ptrs& P, const Epi& E) {
;     ...
;             PG8_BAR; PG8_WAIT_L(0); PG8_MMA(1, 0, At, B0); PG8_BAR; PG8_SCHED;
;             PG8_STAGE(PG8_SB(0, 1), b2 + hstep, voffB);
;             PG8_WAIT_V(6); PG8_BAR; PG8_MMA(1, 1, At, B1); PG8_BAR;
;             PG8_LDB(B0, 1, 0); PG8_SCHED; PG8_LDA(At, 1, 0); PG8_STAGE(PG8_SA(0, 1), a2 + hstep, voffA);
;             PG8_WAIT_L(8); PG8_BAR; PG8_WAIT_L(0); PG8_MMA(0, 0, At, B0); PG8_BAR; PG8_SCHED;
;             PG8_LDB(B1, 1, 1); PG8_STAGE(PG8_SB(1, 0), b3, voffB);
;             PG8_BAR; PG8_WAIT_L(0); PG8_MMA(0, 1, At, B1); PG8_BAR;
;             PG8_LDA(At, 1, 1); PG8_STAGE(PG8_SA(1, 0), a3, voffA);
;             PG8_BAR; PG8_WAIT_L(0); PG8_MMA(1, 0, At, B0); PG8_BAR; PG8_SCHED;
	s_waitcnt lgkmcnt(0)
	v_mfma_f32_16x16x32_bf16 v[60:63], v[152:155], v[168:171], v[60:63]
	v_mfma_f32_16x16x32_bf16 v[60:63], v[156:159], v[172:175], v[60:63]
	v_mfma_f32_16x16x32_bf16 v[56:59], v[164:167], v[172:175], v[56:59]
	v_mfma_f32_16x16x32_bf16 v[56:59], v[160:163], v[168:171], v[56:59]
	v_mfma_f32_16x16x32_bf16 v[40:43], v[160:163], v[176:179], v[40:43]
	v_mfma_f32_16x16x32_bf16 v[40:43], v[164:167], v[180:183], v[40:43]
	v_mfma_f32_16x16x32_bf16 v[44:47], v[156:159], v[180:183], v[44:47]
	v_mfma_f32_16x16x32_bf16 v[44:47], v[152:155], v[176:179], v[44:47]
	v_mfma_f32_16x16x32_bf16 v[28:31], v[152:155], v[184:187], v[28:31]
	v_mfma_f32_16x16x32_bf16 v[28:31], v[156:159], v[188:191], v[28:31]
	v_mfma_f32_16x16x32_bf16 v[24:27], v[164:167], v[188:191], v[24:27]
	v_mfma_f32_16x16x32_bf16 v[24:27], v[160:163], v[184:187], v[24:27]
	v_mfma_f32_16x16x32_bf16 v[8:11], v[160:163], v[192:195], v[8:11]
	v_mfma_f32_16x16x32_bf16 v[8:11], v[164:167], v[196:199], v[8:11]
	v_mfma_f32_16x16x32_bf16 v[12:15], v[156:159], v[196:199], v[12:15]
	v_mfma_f32_16x16x32_bf16 v[12:15], v[152:155], v[192:195], v[12:15]
	s_barrier
	s_add_u32 s72, s42, 0x40000
	s_addc_u32 s73, s43, 0
	s_add_i32 s71, s64, s51
	s_mov_b32 m0, s71
	s_nop 0
	global_load_lds_dwordx4 v130, s[72:73]
	s_add_i32 m0, s71, 0x2000
	s_nop 0
	global_load_lds_dwordx4 v134, s[72:73]
	s_waitcnt vmcnt(6)
	s_barrier
	v_mfma_f32_16x16x32_bf16 v[52:55], v[200:203], v[168:171], v[52:55]
	v_mfma_f32_16x16x32_bf16 v[52:55], v[204:207], v[172:175], v[52:55]
	v_mfma_f32_16x16x32_bf16 v[48:51], v[214:217], v[172:175], v[48:51]
	v_mfma_f32_16x16x32_bf16 v[48:51], v[210:213], v[168:171], v[48:51]
	v_mfma_f32_16x16x32_bf16 v[32:35], v[210:213], v[176:179], v[32:35]
	v_mfma_f32_16x16x32_bf16 v[32:35], v[214:217], v[180:183], v[32:35]
	v_mfma_f32_16x16x32_bf16 v[36:39], v[204:207], v[180:183], v[36:39]
	v_mfma_f32_16x16x32_bf16 v[36:39], v[200:203], v[176:179], v[36:39]
	v_mfma_f32_16x16x32_bf16 v[20:23], v[200:203], v[184:187], v[20:23]
	v_mfma_f32_16x16x32_bf16 v[20:23], v[204:207], v[188:191], v[20:23]
	v_mfma_f32_16x16x32_bf16 v[16:19], v[214:217], v[188:191], v[16:19]
	v_mfma_f32_16x16x32_bf16 v[16:19], v[210:213], v[184:187], v[16:19]
	v_mfma_f32_16x16x32_bf16 v[0:3], v[210:213], v[192:195], v[0:3]
	v_mfma_f32_16x16x32_bf16 v[0:3], v[214:217], v[196:199], v[0:3]
	v_mfma_f32_16x16x32_bf16 v[4:7], v[204:207], v[196:199], v[4:7]
	v_mfma_f32_16x16x32_bf16 v[4:7], v[200:203], v[192:195], v[4:7]
	s_barrier
	s_add_i32 s71, 0, 0x18000
	ds_read_b128 v[152:155], v252
	ds_read_b128 v[156:159], v252 offset:1024
	ds_read_b128 v[160:163], v252 offset:2048
	ds_read_b128 v[164:167], v252 offset:3072
	s_add_u32 s44, s44, 0x40000
	s_addc_u32 s45, s45, 0
	s_mov_b32 m0, s57
	ds_read_b128 v[168:171], v150 offset:32768
	ds_read_b128 v[172:175], v150 offset:33792
	ds_read_b128 v[176:179], v150 offset:34816
	ds_read_b128 v[180:183], v150 offset:35840
	ds_read_b128 v[184:187], v150 offset:36864
	ds_read_b128 v[188:191], v150 offset:37888
	ds_read_b128 v[192:195], v150 offset:38912
	ds_read_b128 v[196:199], v150 offset:39936
	global_load_lds_dwordx4 v128, s[44:45]
	s_mov_b32 m0, s58
	s_nop 0
	global_load_lds_dwordx4 v132, s[44:45]
	s_barrier
	s_waitcnt lgkmcnt(0)
	v_mfma_f32_16x16x32_bf16 v[124:127], v[152:155], v[168:171], v[124:127]
	v_mfma_f32_16x16x32_bf16 v[124:127], v[156:159], v[172:175], v[124:127]
	v_mfma_f32_16x16x32_bf16 v[120:123], v[164:167], v[172:175], v[120:123]
	v_mfma_f32_16x16x32_bf16 v[120:123], v[160:163], v[168:171], v[120:123]
	v_mfma_f32_16x16x32_bf16 v[104:107], v[160:163], v[176:179], v[104:107]
	v_mfma_f32_16x16x32_bf16 v[104:107], v[164:167], v[180:183], v[104:107]
	v_mfma_f32_16x16x32_bf16 v[108:111], v[156:159], v[180:183], v[108:111]
	v_mfma_f32_16x16x32_bf16 v[108:111], v[152:155], v[176:179], v[108:111]
	v_mfma_f32_16x16x32_bf16 v[92:95], v[152:155], v[184:187], v[92:95]
	v_mfma_f32_16x16x32_bf16 v[92:95], v[156:159], v[188:191], v[92:95]
	v_mfma_f32_16x16x32_bf16 v[88:91], v[164:167], v[188:191], v[88:91]
	v_mfma_f32_16x16x32_bf16 v[88:91], v[160:163], v[184:187], v[88:91]
	v_mfma_f32_16x16x32_bf16 v[72:75], v[160:163], v[192:195], v[72:75]
	v_mfma_f32_16x16x32_bf16 v[72:75], v[164:167], v[196:199], v[72:75]
	v_mfma_f32_16x16x32_bf16 v[76:79], v[156:159], v[196:199], v[76:79]
	v_mfma_f32_16x16x32_bf16 v[76:79], v[152:155], v[192:195], v[76:79]
	s_barrier
	s_add_i32 s44, 0, 0x1c000
	s_add_i32 s45, s71, s51
	s_mov_b32 m0, s45
	ds_read_b128 v[200:203], v253
	ds_read_b128 v[204:207], v253 offset:1024
	ds_read_b128 v[210:213], v253 offset:2048
	ds_read_b128 v[214:217], v253 offset:3072
	global_load_lds_dwordx4 v130, s[76:77]
	s_add_i32 m0, s45, 0x2000
	s_nop 0
	global_load_lds_dwordx4 v134, s[76:77]
	s_barrier
	s_waitcnt lgkmcnt(0)
	v_mfma_f32_16x16x32_bf16 v[116:119], v[200:203], v[168:171], v[116:119]
	v_mfma_f32_16x16x32_bf16 v[116:119], v[204:207], v[172:175], v[116:119]
	v_mfma_f32_16x16x32_bf16 v[112:115], v[214:217], v[172:175], v[112:115]
	v_mfma_f32_16x16x32_bf16 v[112:115], v[210:213], v[168:171], v[112:115]
	v_mfma_f32_16x16x32_bf16 v[96:99], v[210:213], v[176:179], v[96:99]
	v_mfma_f32_16x16x32_bf16 v[96:99], v[214:217], v[180:183], v[96:99]
	v_mfma_f32_16x16x32_bf16 v[100:103], v[204:207], v[180:183], v[100:103]
	v_mfma_f32_16x16x32_bf16 v[100:103], v[200:203], v[176:179], v[100:103]
	v_mfma_f32_16x16x32_bf16 v[84:87], v[200:203], v[184:187], v[84:87]
	v_mfma_f32_16x16x32_bf16 v[84:87], v[204:207], v[188:191], v[84:87]
	v_mfma_f32_16x16x32_bf16 v[80:83], v[214:217], v[188:191], v[80:83]
	v_mfma_f32_16x16x32_bf16 v[80:83], v[210:213], v[184:187], v[80:83]
	v_mfma_f32_16x16x32_bf16 v[64:67], v[210:213], v[192:195], v[64:67]
	v_mfma_f32_16x16x32_bf16 v[64:67], v[214:217], v[196:199], v[64:67]
	v_mfma_f32_16x16x32_bf16 v[68:71], v[204:207], v[196:199], v[68:71]
	v_mfma_f32_16x16x32_bf16 v[68:71], v[200:203], v[192:195], v[68:71]
	s_barrier
; __device__ __forceinline__ unsigned cvt_pk_bf16(float lo, float hi) { unsigned r; asm volatile("v_cvt_pk_bf16_f32 %0, %1, %2" : "=v"(r) : "v"(lo), "v"(hi)); return r; }
; #define PG8_STAGE(bufoff, gbase, voff) do { _Pragma("unroll") for (int _i = 0; _i < 2; ++_i) \
;         __builtin_amdgcn_global_load_lds((const unsigned*)((const char*)(gbase) + (voff)[_i]), (LAS unsigned*)(lds + (bufoff) + ldsw + _i * 8192), 16, 0, 0); } while (0)
; #define PG8_LDA(dst, b, h) do { _Pragma("unroll") for (int m = 0; m < 4; ++m) _Pragma("unroll") for (int k = 0; k < 2; ++k) dst[m][k] = *(const LAS bf16x8*)(lds + PG8_SA(b, h) + aoff + m * 2048 + k * 1024); } while (0)
; #define PG8_MMA(ai, bj, At, Bt) do { __builtin_amdgcn_s_setprio(1); _Pragma("unroll") for (int m = 0; m < 4; ++m) _Pragma("unroll") for (int n = 0; n < 2; ++n) _Pragma("unroll") for (int k = 0; k < 2; ++k) \
;         acc[ai][bj][m][n] = __builtin_amdgcn_mfma_f32_16x16x32_bf16(Bt[n][k], At[m][k], acc[ai][bj][m][n], 0, 0, 0); __builtin_amdgcn_s_setprio(0); } while (0)
; #define PG8_WAIT_V(n) asm volatile("s_waitcnt vmcnt(" #n ")" ::: "memory")
; template <class Epi, class Ptrs>
; __device__ __forceinline__ void gemm_phase(LAS unsigned char* lds, const int K, const StaticOrder& S, const Ptrs& P, const Epi& E) {
;     ...
;             PG8_LDA(At, 1, 1); PG8_STAGE(PG8_SA(1, 0), a3, voffA);
;             PG8_BAR; PG8_WAIT_L(0); PG8_MMA(1, 0, At, B0); PG8_BAR; PG8_SCHED;
;             PG8_STAGE(PG8_SB(1, 1), b3 + hstep, voffB);
;             PG8_WAIT_V(6); PG8_BAR; PG8_MMA(1, 1, At, B1); PG8_BAR;
;     __device__ __forceinline__ void operator()(const f32x4 (&acc)[2][2][4][2], const Unit& u, int ui, int wr, int wc, int fr, int fq) const {
;     ...
;         for (int ai = 0; ai < 2; ++ai)
; #pragma unroll
;             for (int m = 0; m < 4; ++m) { bf16_t* rowp = hid + (size_t)(row0 + ai * 128 + m * 16) * DFF + col0;
; #pragma unroll
;                 for (int bj = 0; bj < 2; ++bj) { f32x4 v0 = acc[ai][bj][m][0], v1 = acc[ai][bj][m][1];
; #pragma unroll
;                     for (int j = 0; j < 4; ++j) { const float a = fmaxf(v0[j], 0.f), b = fmaxf(v1[j], 0.f); v0[j] = a * a; v1[j] = b * b; }
;                     u32x4 w; w.x = cvt_pk_bf16(v0[0], v0[1]); w.y = cvt_pk_bf16(v0[2], v0[3]); w.z = cvt_pk_bf16(v1[0], v1[1]); w.w = cvt_pk_bf16(v1[2], v1[3]);
;                     *(u32x4*)(rowp + bj * 128) = w; } }
	s_mov_b32 m0, s61
	ds_read_b128 v[168:171], v150 offset:49152
	ds_read_b128 v[172:175], v150 offset:50176
	ds_read_b128 v[176:179], v150 offset:51200
	ds_read_b128 v[180:183], v150 offset:52224
	ds_read_b128 v[184:187], v150 offset:53248
	ds_read_b128 v[188:191], v150 offset:54272
	ds_read_b128 v[192:195], v150 offset:55296
	ds_read_b128 v[196:199], v150 offset:56320
	global_load_lds_dwordx4 v128, s[78:79]
	s_mov_b32 m0, s62
	s_nop 0
	global_load_lds_dwordx4 v132, s[78:79]
	s_barrier
	s_waitcnt lgkmcnt(0)
	v_mfma_f32_16x16x32_bf16 v[60:63], v[152:155], v[168:171], v[60:63]
	v_mfma_f32_16x16x32_bf16 v[60:63], v[156:159], v[172:175], v[60:63]
	v_mfma_f32_16x16x32_bf16 v[56:59], v[164:167], v[172:175], v[56:59]
	v_mfma_f32_16x16x32_bf16 v[56:59], v[160:163], v[168:171], v[56:59]
	v_mfma_f32_16x16x32_bf16 v[40:43], v[160:163], v[176:179], v[40:43]
	v_mfma_f32_16x16x32_bf16 v[40:43], v[164:167], v[180:183], v[40:43]
	v_mfma_f32_16x16x32_bf16 v[44:47], v[156:159], v[180:183], v[44:47]
	v_mfma_f32_16x16x32_bf16 v[44:47], v[152:155], v[176:179], v[44:47]
	v_mfma_f32_16x16x32_bf16 v[28:31], v[152:155], v[184:187], v[28:31]
	v_mfma_f32_16x16x32_bf16 v[28:31], v[156:159], v[188:191], v[28:31]
	v_mfma_f32_16x16x32_bf16 v[24:27], v[164:167], v[188:191], v[24:27]
	v_mfma_f32_16x16x32_bf16 v[24:27], v[160:163], v[184:187], v[24:27]
	v_mfma_f32_16x16x32_bf16 v[8:11], v[160:163], v[192:195], v[8:11]
	v_mfma_f32_16x16x32_bf16 v[8:11], v[164:167], v[196:199], v[8:11]
	v_mfma_f32_16x16x32_bf16 v[12:15], v[156:159], v[196:199], v[12:15]
	v_mfma_f32_16x16x32_bf16 v[12:15], v[152:155], v[192:195], v[12:15]
	s_barrier
	s_add_u32 s42, s42, 0x40080
	s_addc_u32 s43, s43, 0
	s_add_i32 s44, s44, s51
	s_mov_b32 m0, s44
	s_nop 0
	global_load_lds_dwordx4 v130, s[42:43]
	s_add_i32 m0, s44, 0x2000
	s_nop 0
	global_load_lds_dwordx4 v134, s[42:43]
	s_waitcnt vmcnt(6)
	s_barrier
	v_mfma_f32_16x16x32_bf16 v[52:55], v[200:203], v[168:171], v[52:55]
	v_mfma_f32_16x16x32_bf16 v[52:55], v[204:207], v[172:175], v[52:55]
	v_mfma_f32_16x16x32_bf16 v[48:51], v[214:217], v[172:175], v[48:51]
	v_mfma_f32_16x16x32_bf16 v[48:51], v[210:213], v[168:171], v[48:51]
	v_mfma_f32_16x16x32_bf16 v[32:35], v[210:213], v[176:179], v[32:35]
	v_mfma_f32_16x16x32_bf16 v[32:35], v[214:217], v[180:183], v[32:35]
	v_mfma_f32_16x16x32_bf16 v[36:39], v[204:207], v[180:183], v[36:39]
	v_mfma_f32_16x16x32_bf16 v[36:39], v[200:203], v[176:179], v[36:39]
	v_mfma_f32_16x16x32_bf16 v[20:23], v[200:203], v[184:187], v[20:23]
	v_mfma_f32_16x16x32_bf16 v[20:23], v[204:207], v[188:191], v[20:23]
	v_mfma_f32_16x16x32_bf16 v[16:19], v[214:217], v[188:191], v[16:19]
	v_mfma_f32_16x16x32_bf16 v[16:19], v[210:213], v[184:187], v[16:19]
	v_mfma_f32_16x16x32_bf16 v[0:3], v[210:213], v[192:195], v[0:3]
	v_mfma_f32_16x16x32_bf16 v[0:3], v[214:217], v[196:199], v[0:3]
	v_mfma_f32_16x16x32_bf16 v[4:7], v[204:207], v[196:199], v[4:7]
	v_mfma_f32_16x16x32_bf16 v[4:7], v[200:203], v[192:195], v[4:7]
	s_barrier
	s_add_i32 s70, s70, 2
	s_add_u32 s40, s40, 0x100
	s_addc_u32 s41, s41, 0
	s_add_u32 s23, s23, 0x100
	s_addc_u32 s25, s25, 0
	s_cmp_gt_u32 s70, 13
	s_cbranch_scc0 .LBB0_433
	v_lshl_add_u32 v152, s38, 8, v146
	v_max_f32_e32 v120, 0, v120
	v_ashrrev_i32_e32 v153, 31, v152
	v_max_f32_e32 v121, 0, v121
	v_max_f32_e32 v122, 0, v122
	v_lshl_or_b32 v144, s69, 8, v148
	v_lshlrev_b64 v[154:155], 13, v[152:153]
	v_mul_f32_e32 v153, v120, v120
	v_max_f32_e32 v120, 0, v125
	v_ashrrev_i32_e32 v145, 31, v144
	v_max_f32_e32 v124, 0, v124
	v_mul_f32_e32 v125, v121, v121
	v_max_f32_e32 v121, 0, v126
	v_mul_f32_e32 v126, v122, v122
	v_max_f32_e32 v122, 0, v127
	v_max_f32_e32 v123, 0, v123
	v_lshl_add_u64 v[154:155], s[10:11], 0, v[154:155]
	v_lshlrev_b64 v[156:157], 1, v[144:145]
	v_mul_f32_e32 v120, v120, v120
	v_max_f32_e32 v112, 0, v112
	v_lshl_add_u64 v[144:145], v[154:155], 0, v[156:157]
	v_mul_f32_e32 v124, v124, v124
	v_mul_f32_e32 v121, v121, v121
	v_mul_f32_e32 v122, v122, v122
	v_mul_f32_e32 v123, v123, v123
	v_cvt_pk_bf16_f32 v120, v124, v120
	v_max_f32_e32 v113, 0, v113
	v_max_f32_e32 v114, 0, v114
	v_cvt_pk_bf16_f32 v121, v121, v122
	v_cvt_pk_bf16_f32 v122, v153, v125
	v_cvt_pk_bf16_f32 v123, v126, v123
	global_store_dwordx4 v[144:145], v[120:123], off
	s_nop 1
	v_mul_f32_e32 v120, v112, v112
	v_max_f32_e32 v112, 0, v117
	v_max_f32_e32 v116, 0, v116
	v_mul_f32_e32 v117, v113, v113
	v_max_f32_e32 v113, 0, v118
	v_mul_f32_e32 v118, v114, v114
	v_max_f32_e32 v114, 0, v119
	v_max_f32_e32 v115, 0, v115
	v_mul_f32_e32 v112, v112, v112
	v_mul_f32_e32 v116, v116, v116
	v_mul_f32_e32 v113, v113, v113
	v_mul_f32_e32 v114, v114, v114
	v_mul_f32_e32 v115, v115, v115
	v_cvt_pk_bf16_f32 v112, v116, v112
	v_max_f32_e32 v104, 0, v104
	v_cvt_pk_bf16_f32 v113, v113, v114
	v_cvt_pk_bf16_f32 v114, v120, v117
	v_cvt_pk_bf16_f32 v115, v118, v115
	global_store_dwordx4 v[144:145], v[112:115], off offset:256
	s_nop 0
	v_max_f32_e32 v105, 0, v105
	v_or_b32_e32 v112, 16, v152
	v_max_f32_e32 v106, 0, v106
	v_ashrrev_i32_e32 v113, 31, v112
	v_mul_f32_e32 v114, v104, v104
	v_max_f32_e32 v104, 0, v109
	v_lshlrev_b64 v[112:113], 13, v[112:113]
	v_max_f32_e32 v108, 0, v108
	v_mul_f32_e32 v109, v105, v105
	v_max_f32_e32 v105, 0, v110
	v_mul_f32_e32 v110, v106, v106
	v_max_f32_e32 v106, 0, v111
	v_max_f32_e32 v107, 0, v107
	v_lshl_add_u64 v[112:113], s[10:11], 0, v[112:113]
	v_mul_f32_e32 v104, v104, v104
	v_max_f32_e32 v96, 0, v96
	v_lshl_add_u64 v[112:113], v[112:113], 0, v[156:157]
	v_mul_f32_e32 v108, v108, v108
	v_mul_f32_e32 v105, v105, v105
	v_mul_f32_e32 v106, v106, v106
	v_mul_f32_e32 v107, v107, v107
	v_cvt_pk_bf16_f32 v104, v108, v104
; __device__ __forceinline__ unsigned cvt_pk_bf16(float lo, float hi) { unsigned r; asm volatile("v_cvt_pk_bf16_f32 %0, %1, %2" : "=v"(r) : "v"(lo), "v"(hi)); return r; }
;     __device__ __forceinline__ void operator()(const f32x4 (&acc)[2][2][4][2], const Unit& u, int ui, int wr, int wc, int fr, int fq) const {
;     ...
;         for (int ai = 0; ai < 2; ++ai)
; #pragma unroll
;             for (int m = 0; m < 4; ++m) { bf16_t* rowp = hid + (size_t)(row0 + ai * 128 + m * 16) * DFF + col0;
; #pragma unroll
;                 for (int bj = 0; bj < 2; ++bj) { f32x4 v0 = acc[ai][bj][m][0], v1 = acc[ai][bj][m][1];
; #pragma unroll
;                     for (int j = 0; j < 4; ++j) { const float a = fmaxf(v0[j], 0.f), b = fmaxf(v1[j], 0.f); v0[j] = a * a; v1[j] = b * b; }
;                     u32x4 w; w.x = cvt_pk_bf16(v0[0], v0[1]); w.y = cvt_pk_bf16(v0[2], v0[3]); w.z = cvt_pk_bf16(v1[0], v1[1]); w.w = cvt_pk_bf16(v1[2], v1[3]);
;                     *(u32x4*)(rowp + bj * 128) = w; } }
	v_max_f32_e32 v97, 0, v97
	v_max_f32_e32 v98, 0, v98
	v_cvt_pk_bf16_f32 v105, v105, v106
	v_cvt_pk_bf16_f32 v106, v114, v109
	v_cvt_pk_bf16_f32 v107, v110, v107
	global_store_dwordx4 v[112:113], v[104:107], off
	s_nop 1
	v_mul_f32_e32 v104, v96, v96
	v_max_f32_e32 v96, 0, v101
	v_max_f32_e32 v100, 0, v100
	v_mul_f32_e32 v101, v97, v97
	v_max_f32_e32 v97, 0, v102
	v_mul_f32_e32 v102, v98, v98
	v_max_f32_e32 v98, 0, v103
	v_max_f32_e32 v99, 0, v99
	v_mul_f32_e32 v96, v96, v96
	v_mul_f32_e32 v100, v100, v100
	v_mul_f32_e32 v97, v97, v97
	v_mul_f32_e32 v98, v98, v98
	v_mul_f32_e32 v99, v99, v99
	v_cvt_pk_bf16_f32 v96, v100, v96
	v_max_f32_e32 v88, 0, v88
	v_cvt_pk_bf16_f32 v97, v97, v98
	v_cvt_pk_bf16_f32 v98, v104, v101
	v_cvt_pk_bf16_f32 v99, v102, v99
	global_store_dwordx4 v[112:113], v[96:99], off offset:256
	s_nop 0
	v_max_f32_e32 v89, 0, v89
	v_or_b32_e32 v96, 32, v152
	v_max_f32_e32 v90, 0, v90
	v_ashrrev_i32_e32 v97, 31, v96
	v_mul_f32_e32 v98, v88, v88
	v_max_f32_e32 v88, 0, v93
	v_lshlrev_b64 v[96:97], 13, v[96:97]
	v_max_f32_e32 v92, 0, v92
	v_mul_f32_e32 v93, v89, v89
	v_max_f32_e32 v89, 0, v94
	v_mul_f32_e32 v94, v90, v90
	v_max_f32_e32 v90, 0, v95
	v_max_f32_e32 v91, 0, v91
	v_lshl_add_u64 v[96:97], s[10:11], 0, v[96:97]
	v_mul_f32_e32 v88, v88, v88
	v_max_f32_e32 v80, 0, v80
	v_lshl_add_u64 v[96:97], v[96:97], 0, v[156:157]
	v_mul_f32_e32 v92, v92, v92
	v_mul_f32_e32 v89, v89, v89
	v_mul_f32_e32 v90, v90, v90
	v_mul_f32_e32 v91, v91, v91
	v_cvt_pk_bf16_f32 v88, v92, v88
	v_max_f32_e32 v81, 0, v81
	v_max_f32_e32 v82, 0, v82
	v_cvt_pk_bf16_f32 v89, v89, v90
	v_cvt_pk_bf16_f32 v90, v98, v93
	v_cvt_pk_bf16_f32 v91, v94, v91
	global_store_dwordx4 v[96:97], v[88:91], off
	s_nop 1
	v_mul_f32_e32 v88, v80, v80
	v_max_f32_e32 v80, 0, v85
	v_max_f32_e32 v84, 0, v84
	v_mul_f32_e32 v85, v81, v81
	v_max_f32_e32 v81, 0, v86
	v_mul_f32_e32 v86, v82, v82
	v_max_f32_e32 v82, 0, v87
	v_max_f32_e32 v83, 0, v83
	v_mul_f32_e32 v80, v80, v80
	v_mul_f32_e32 v84, v84, v84
	v_mul_f32_e32 v81, v81, v81
	v_mul_f32_e32 v82, v82, v82
	v_mul_f32_e32 v83, v83, v83
	v_cvt_pk_bf16_f32 v80, v84, v80
	v_max_f32_e32 v72, 0, v72
	v_cvt_pk_bf16_f32 v81, v81, v82
	v_cvt_pk_bf16_f32 v82, v88, v85
	v_cvt_pk_bf16_f32 v83, v86, v83
	global_store_dwordx4 v[96:97], v[80:83], off offset:256
	s_nop 0
	v_max_f32_e32 v73, 0, v73
	v_or_b32_e32 v80, 48, v152
	v_max_f32_e32 v74, 0, v74
	v_ashrrev_i32_e32 v81, 31, v80
	v_mul_f32_e32 v82, v72, v72
	v_max_f32_e32 v72, 0, v77
	v_lshlrev_b64 v[80:81], 13, v[80:81]
	v_max_f32_e32 v76, 0, v76
	v_mul_f32_e32 v77, v73, v73
	v_max_f32_e32 v73, 0, v78
	v_mul_f32_e32 v78, v74, v74
	v_max_f32_e32 v74, 0, v79
	v_max_f32_e32 v75, 0, v75
	v_lshl_add_u64 v[80:81], s[10:11], 0, v[80:81]
	v_mul_f32_e32 v72, v72, v72
	v_max_f32_e32 v64, 0, v64
	v_max_f32_e32 v65, 0, v65
	v_max_f32_e32 v66, 0, v66
	v_lshl_add_u64 v[80:81], v[80:81], 0, v[156:157]
	v_mul_f32_e32 v76, v76, v76
	v_mul_f32_e32 v73, v73, v73
	v_mul_f32_e32 v74, v74, v74
	v_mul_f32_e32 v75, v75, v75
	v_cvt_pk_bf16_f32 v72, v76, v72
	v_cvt_pk_bf16_f32 v73, v73, v74
	v_cvt_pk_bf16_f32 v74, v82, v77
	v_cvt_pk_bf16_f32 v75, v78, v75
	global_store_dwordx4 v[80:81], v[72:75], off
	v_max_f32_e32 v68, 0, v68
	v_max_f32_e32 v67, 0, v67
	v_mul_f32_e32 v72, v64, v64
	v_max_f32_e32 v64, 0, v69
	v_mul_f32_e32 v69, v65, v65
	v_max_f32_e32 v65, 0, v70
	v_mul_f32_e32 v70, v66, v66
	v_max_f32_e32 v66, 0, v71
	v_mul_f32_e32 v64, v64, v64
	v_mul_f32_e32 v65, v65, v65
	v_mul_f32_e32 v66, v66, v66
	v_max_f32_e32 v56, 0, v56
	v_mul_f32_e32 v68, v68, v68
	v_mul_f32_e32 v67, v67, v67
	v_cvt_pk_bf16_f32 v64, v68, v64
	v_cvt_pk_bf16_f32 v65, v65, v66
	v_cvt_pk_bf16_f32 v66, v72, v69
	v_max_f32_e32 v57, 0, v57
	v_max_f32_e32 v58, 0, v58
	v_cvt_pk_bf16_f32 v67, v70, v67
	global_store_dwordx4 v[80:81], v[64:67], off offset:256
	s_nop 0
	v_max_f32_e32 v60, 0, v60
	v_mul_f32_e32 v66, v56, v56
	v_max_f32_e32 v56, 0, v61
	v_mul_f32_e32 v61, v57, v57
	v_max_f32_e32 v57, 0, v62
	v_mul_f32_e32 v62, v58, v58
	v_max_f32_e32 v58, 0, v63
	v_mul_f32_e32 v60, v60, v60
	v_mul_f32_e32 v56, v56, v56
	v_max_f32_e32 v59, 0, v59
	v_mul_f32_e32 v57, v57, v57
	v_mul_f32_e32 v58, v58, v58
	v_cvt_pk_bf16_f32 v56, v60, v56
	v_add_co_u32_e32 v60, vcc, s65, v144
	v_max_f32_e32 v48, 0, v48
	v_max_f32_e32 v49, 0, v49
	v_max_f32_e32 v50, 0, v50
	v_mul_f32_e32 v59, v59, v59
	v_cvt_pk_bf16_f32 v57, v57, v58
	v_cvt_pk_bf16_f32 v58, v66, v61
	v_addc_co_u32_e32 v61, vcc, 0, v145, vcc
	v_cvt_pk_bf16_f32 v59, v62, v59
	global_store_dwordx4 v[60:61], v[56:59], off
	v_max_f32_e32 v52, 0, v52
	v_max_f32_e32 v51, 0, v51
	v_mul_f32_e32 v56, v48, v48
	v_max_f32_e32 v48, 0, v53
	v_mul_f32_e32 v53, v49, v49
	v_max_f32_e32 v49, 0, v54
	v_mul_f32_e32 v54, v50, v50
	v_max_f32_e32 v50, 0, v55
; __device__ __forceinline__ unsigned cvt_pk_bf16(float lo, float hi) { unsigned r; asm volatile("v_cvt_pk_bf16_f32 %0, %1, %2" : "=v"(r) : "v"(lo), "v"(hi)); return r; }
; #define PG8_WAIT_V(n) asm volatile("s_waitcnt vmcnt(" #n ")" ::: "memory")
; #define PG8_BAR __builtin_amdgcn_s_barrier()
; template <class Epi, class Ptrs>
; __device__ __forceinline__ void gemm_phase(LAS unsigned char* lds, const int K, const StaticOrder& S, const Ptrs& P, const Epi& E) {
;     ...
;         cur = nxt; cA = nA; cB = nB; ++ui;
;     }
;     PG8_WAIT_V(0);
;     if (wr == 0) PG8_BAR;
;     PG8_BAR;
;     __device__ __forceinline__ void operator()(const f32x4 (&acc)[2][2][4][2], const Unit& u, int ui, int wr, int wc, int fr, int fq) const {
;     ...
;         for (int ai = 0; ai < 2; ++ai)
; #pragma unroll
;             for (int m = 0; m < 4; ++m) { bf16_t* rowp = hid + (size_t)(row0 + ai * 128 + m * 16) * DFF + col0;
; #pragma unroll
;                 for (int bj = 0; bj < 2; ++bj) { f32x4 v0 = acc[ai][bj][m][0], v1 = acc[ai][bj][m][1];
; #pragma unroll
;                     for (int j = 0; j < 4; ++j) { const float a = fmaxf(v0[j], 0.f), b = fmaxf(v1[j], 0.f); v0[j] = a * a; v1[j] = b * b; }
;                     u32x4 w; w.x = cvt_pk_bf16(v0[0], v0[1]); w.y = cvt_pk_bf16(v0[2], v0[3]); w.z = cvt_pk_bf16(v1[0], v1[1]); w.w = cvt_pk_bf16(v1[2], v1[3]);
;                     *(u32x4*)(rowp + bj * 128) = w; } }
	v_mul_f32_e32 v48, v48, v48
	v_mul_f32_e32 v49, v49, v49
	v_mul_f32_e32 v50, v50, v50
	v_max_f32_e32 v40, 0, v40
	v_lshl_add_u64 v[64:65], v[144:145], 0, s[14:15]
	v_mul_f32_e32 v52, v52, v52
	v_mul_f32_e32 v51, v51, v51
	v_cvt_pk_bf16_f32 v48, v52, v48
	v_cvt_pk_bf16_f32 v49, v49, v50
	v_cvt_pk_bf16_f32 v50, v56, v53
	v_max_f32_e32 v41, 0, v41
	v_max_f32_e32 v42, 0, v42
	v_cvt_pk_bf16_f32 v51, v54, v51
	global_store_dwordx4 v[64:65], v[48:51], off offset:256
	s_nop 0
	v_max_f32_e32 v44, 0, v44
	v_mul_f32_e32 v50, v40, v40
	v_max_f32_e32 v40, 0, v45
	v_mul_f32_e32 v45, v41, v41
	v_max_f32_e32 v41, 0, v46
	v_mul_f32_e32 v46, v42, v42
	v_max_f32_e32 v42, 0, v47
	v_mul_f32_e32 v44, v44, v44
	v_mul_f32_e32 v40, v40, v40
	v_max_f32_e32 v43, 0, v43
	v_mul_f32_e32 v41, v41, v41
	v_mul_f32_e32 v42, v42, v42
	v_cvt_pk_bf16_f32 v40, v44, v40
	v_add_co_u32_e32 v44, vcc, s66, v144
	v_max_f32_e32 v32, 0, v32
	v_max_f32_e32 v33, 0, v33
	v_max_f32_e32 v34, 0, v34
	v_mul_f32_e32 v43, v43, v43
	v_cvt_pk_bf16_f32 v41, v41, v42
	v_cvt_pk_bf16_f32 v42, v50, v45
	v_addc_co_u32_e32 v45, vcc, 0, v145, vcc
	v_cvt_pk_bf16_f32 v43, v46, v43
	global_store_dwordx4 v[44:45], v[40:43], off
	v_max_f32_e32 v36, 0, v36
	v_max_f32_e32 v35, 0, v35
	v_mul_f32_e32 v40, v32, v32
	v_max_f32_e32 v32, 0, v37
	v_mul_f32_e32 v37, v33, v33
	v_max_f32_e32 v33, 0, v38
	v_mul_f32_e32 v38, v34, v34
	v_max_f32_e32 v34, 0, v39
	v_mul_f32_e32 v32, v32, v32
	v_mul_f32_e32 v33, v33, v33
	v_mul_f32_e32 v34, v34, v34
	v_max_f32_e32 v24, 0, v24
	v_lshl_add_u64 v[48:49], v[144:145], 0, s[16:17]
	v_mul_f32_e32 v36, v36, v36
	v_mul_f32_e32 v35, v35, v35
	v_cvt_pk_bf16_f32 v32, v36, v32
	v_cvt_pk_bf16_f32 v33, v33, v34
	v_cvt_pk_bf16_f32 v34, v40, v37
	v_max_f32_e32 v25, 0, v25
	v_max_f32_e32 v26, 0, v26
	v_cvt_pk_bf16_f32 v35, v38, v35
	global_store_dwordx4 v[48:49], v[32:35], off offset:256
	s_nop 0
	v_max_f32_e32 v28, 0, v28
	v_mul_f32_e32 v34, v24, v24
	v_max_f32_e32 v24, 0, v29
	v_mul_f32_e32 v29, v25, v25
	v_max_f32_e32 v25, 0, v30
	v_mul_f32_e32 v30, v26, v26
	v_max_f32_e32 v26, 0, v31
	v_mul_f32_e32 v28, v28, v28
	v_mul_f32_e32 v24, v24, v24
	v_max_f32_e32 v27, 0, v27
	v_mul_f32_e32 v25, v25, v25
	v_mul_f32_e32 v26, v26, v26
	v_cvt_pk_bf16_f32 v24, v28, v24
	v_add_co_u32_e32 v28, vcc, s67, v144
	v_max_f32_e32 v16, 0, v16
	v_max_f32_e32 v17, 0, v17
	v_max_f32_e32 v18, 0, v18
	v_mul_f32_e32 v27, v27, v27
	v_cvt_pk_bf16_f32 v25, v25, v26
	v_cvt_pk_bf16_f32 v26, v34, v29
	v_addc_co_u32_e32 v29, vcc, 0, v145, vcc
	v_cvt_pk_bf16_f32 v27, v30, v27
	global_store_dwordx4 v[28:29], v[24:27], off
	v_max_f32_e32 v20, 0, v20
	v_max_f32_e32 v19, 0, v19
	v_mul_f32_e32 v24, v16, v16
	v_max_f32_e32 v16, 0, v21
	v_mul_f32_e32 v21, v17, v17
	v_max_f32_e32 v17, 0, v22
	v_mul_f32_e32 v22, v18, v18
	v_max_f32_e32 v18, 0, v23
	v_mul_f32_e32 v16, v16, v16
	v_mul_f32_e32 v17, v17, v17
	v_mul_f32_e32 v18, v18, v18
	v_max_f32_e32 v8, 0, v8
	v_lshl_add_u64 v[32:33], v[144:145], 0, s[18:19]
	v_mul_f32_e32 v20, v20, v20
	v_mul_f32_e32 v19, v19, v19
	v_cvt_pk_bf16_f32 v16, v20, v16
	v_cvt_pk_bf16_f32 v17, v17, v18
	v_cvt_pk_bf16_f32 v18, v24, v21
	v_max_f32_e32 v9, 0, v9
	v_max_f32_e32 v10, 0, v10
	v_cvt_pk_bf16_f32 v19, v22, v19
	global_store_dwordx4 v[32:33], v[16:19], off offset:256
	s_nop 0
	v_max_f32_e32 v12, 0, v12
	v_mul_f32_e32 v18, v8, v8
	v_max_f32_e32 v8, 0, v13
	v_mul_f32_e32 v13, v9, v9
	v_max_f32_e32 v9, 0, v14
	v_mul_f32_e32 v14, v10, v10
	v_max_f32_e32 v10, 0, v15
	v_mul_f32_e32 v12, v12, v12
	v_mul_f32_e32 v8, v8, v8
	v_max_f32_e32 v11, 0, v11
	v_mul_f32_e32 v9, v9, v9
	v_mul_f32_e32 v10, v10, v10
	v_cvt_pk_bf16_f32 v8, v12, v8
	v_add_co_u32_e32 v12, vcc, s68, v144
	v_max_f32_e32 v0, 0, v0
	v_max_f32_e32 v1, 0, v1
	v_max_f32_e32 v2, 0, v2
	v_mul_f32_e32 v11, v11, v11
	v_cvt_pk_bf16_f32 v9, v9, v10
	v_cvt_pk_bf16_f32 v10, v18, v13
	v_addc_co_u32_e32 v13, vcc, 0, v145, vcc
	v_cvt_pk_bf16_f32 v11, v14, v11
	global_store_dwordx4 v[12:13], v[8:11], off
	v_max_f32_e32 v3, 0, v3
	v_max_f32_e32 v4, 0, v4
	v_mul_f32_e32 v8, v0, v0
	v_max_f32_e32 v0, 0, v5
	v_mul_f32_e32 v5, v1, v1
	v_max_f32_e32 v1, 0, v6
	v_mul_f32_e32 v6, v2, v2
	v_max_f32_e32 v2, 0, v7
	v_lshl_add_u64 v[16:17], v[144:145], 0, s[20:21]
	v_mul_f32_e32 v0, v0, v0
	v_mul_f32_e32 v1, v1, v1
	v_mul_f32_e32 v2, v2, v2
	v_mul_f32_e32 v3, v3, v3
	s_and_b64 vcc, exec, s[4:5]
	s_mov_b32 s69, s22
	s_mov_b32 s38, s24
	s_mov_b64 s[40:41], s[0:1]
	s_mov_b64 s[42:43], s[36:37]
	v_mul_f32_e32 v4, v4, v4
	v_cvt_pk_bf16_f32 v0, v4, v0
	v_cvt_pk_bf16_f32 v1, v1, v2
	v_cvt_pk_bf16_f32 v2, v8, v5
	v_cvt_pk_bf16_f32 v3, v6, v3
	global_store_dwordx4 v[16:17], v[0:3], off offset:256
	s_cbranch_vccz .LBB0_428
	s_waitcnt vmcnt(0)
	s_setprio 0
	s_cmpk_gt_u32 s46, 0xff
	s_cbranch_scc1 .LBB0_437
	s_barrier

; __device__ __forceinline__ unsigned xb_ld(unsigned* p)              { return __hip_atomic_load(p, __ATOMIC_RELAXED, __HIP_MEMORY_SCOPE_AGENT); }
; __device__ __forceinline__ void xcd_barrier_complete(unsigned* bar, unsigned x, unsigned& nloc, unsigned& nx) {
;     const unsigned G = gridDim.x * gridDim.y * gridDim.z;
;     unsigned sum, cnt, mine, sp = 0u;
;     for (;;) {
;         sum = 0u; cnt = 0u; mine = 0u;
; #pragma unroll
;         for (unsigned j = 0; j < 16; ++j) { const unsigned c = xb_ld(&bar[XB_XCNT(j)]); sum += c; cnt += (c > 0u) ? 1u : 0u; mine = (j == x) ? c : mine; }
; __device__ __forceinline__ void xcd_barrier(const XcdBarrier& b) {
;     asm volatile("s_waitcnt vmcnt(0)" ::: "memory");
;     __syncthreads();
;     if (threadIdx.x == 0) {
;         unsigned* bar = b.bar;
;         __builtin_amdgcn_s_waitcnt(0);
;         unsigned nloc = b.st[0], nx = b.st[1];
;         if (nloc == 0u) { xcd_barrier_complete(bar, b.x, nloc, nx); b.st[0] = nloc; b.st[1] = nx; }
.LBB0_438:
	s_nop 0
	s_nop 0
	s_nop 0
	s_nop 0
	s_nop 0
	s_nop 0
	s_nop 0
	s_nop 0
	s_nop 0
	s_nop 0
	s_nop 0
	s_nop 0
	s_nop 0
	s_nop 0
	s_nop 0
	s_nop 0
	s_nop 0
	s_nop 0
	s_nop 0
	s_nop 0
	s_nop 0
	s_nop 0
	s_nop 0
	s_nop 0
	s_nop 0
	s_nop 0
	s_nop 0
	s_nop 0
	s_nop 0
	s_nop 0
	s_nop 0
	s_nop 0
	s_nop 0
	s_nop 0
	s_nop 0
	s_nop 0
	s_nop 0
	s_nop 0
	s_nop 0
	s_nop 0
	s_nop 0
	s_cmp_gt_i32 s31, 5
	s_cselect_b64 s[0:1], -1, 0
	s_and_b64 s[4:5], s[6:7], s[0:1]
	s_andn2_b64 vcc, exec, s[4:5]
	s_cbranch_vccnz .LBB0_488
	s_waitcnt vmcnt(0)
	s_waitcnt vmcnt(0) lgkmcnt(0)
	s_barrier
	s_and_saveexec_b64 s[4:5], s[8:9]
	s_cbranch_execz .LBB0_487
	s_add_i32 s6, 0, 0x25ff0
	v_mov_b32_e32 v0, s6
	s_waitcnt vmcnt(0) expcnt(0) lgkmcnt(0)
	ds_read_b32 v2, v0
	s_add_i32 s6, 0, 0x25ff4
	v_mov_b32_e32 v0, s6
	ds_read_b32 v0, v0
	s_waitcnt lgkmcnt(1)
	v_cmp_ne_u32_e32 vcc, 0, v2
	s_cbranch_vccnz .LBB0_455
	s_load_dwordx2 s[10:11], s[52:53], 0x4
	s_add_u32 s6, s28, 0x3e800200
	s_addc_u32 s7, s29, 0
	s_add_u32 s8, s28, 0x3e800400
	s_addc_u32 s9, s29, 0
	s_waitcnt lgkmcnt(0)
	s_mul_i32 s31, s10, s3
	s_add_u32 s10, s28, 0x3e800500
	s_mul_i32 s31, s31, s11
	s_addc_u32 s11, s29, 0
	s_add_u32 s12, s28, 0x3e800600
	s_addc_u32 s13, s29, 0
	s_add_u32 s14, s28, 0x3e800700
	s_addc_u32 s15, s29, 0
	s_add_u32 s16, s28, 0x3e800800
	s_addc_u32 s17, s29, 0
	s_add_u32 s18, s28, 0x3e800900
	s_addc_u32 s19, s29, 0
	s_add_u32 s20, s28, 0x3e800a00
	s_addc_u32 s21, s29, 0
	s_add_u32 s22, s28, 0x3e800b00
	s_addc_u32 s23, s29, 0
	s_add_u32 s24, s28, 0x3e800c00
	s_addc_u32 s25, s29, 0
	s_add_u32 s36, s28, 0x3e800d00
	s_addc_u32 s37, s29, 0
	s_add_u32 s38, s28, 0x3e800e00
	s_addc_u32 s39, s29, 0
	s_add_u32 s40, s28, 0x3e800f00
	s_addc_u32 s41, s29, 0
	s_add_u32 s42, s28, 0x3e801000
	s_addc_u32 s43, s29, 0
	s_add_u32 s44, s28, 0x3e801100
	s_addc_u32 s45, s29, 0
	s_add_u32 s46, s28, 0x3e801200
	s_addc_u32 s47, s29, 0
	s_add_u32 s48, s28, 0x3e801300
	s_addc_u32 s49, s29, 0
	s_mov_b32 s56, 1
	v_mov_b32_e32 v16, 0
	s_branch .LBB0_443

; #define PG8_STAGE(bufoff, gbase, voff) do { _Pragma("unroll") for (int _i = 0; _i < 2; ++_i) \
;         __builtin_amdgcn_global_load_lds((const unsigned*)((const char*)(gbase) + (voff)[_i]), (LAS unsigned*)(lds + (bufoff) + ldsw + _i * 8192), 16, 0, 0); } while (0)
; #define PG8_LDA(dst, b, h) do { _Pragma("unroll") for (int m = 0; m < 4; ++m) _Pragma("unroll") for (int k = 0; k < 2; ++k) dst[m][k] = *(const LAS bf16x8*)(lds + PG8_SA(b, h) + aoff + m * 2048 + k * 1024); } while (0)
; #define PG8_LDB(dst, b, h) do { _Pragma("unroll") for (int n = 0; n < 2; ++n) _Pragma("unroll") for (int k = 0; k < 2; ++k) dst[n][k] = *(const LAS bf16x8*)(lds + PG8_SB(b, h) + boff + n * 2048 + k * 1024); } while (0)
; #define PG8_MMA(ai, bj, At, Bt) do { __builtin_amdgcn_s_setprio(1); _Pragma("unroll") for (int m = 0; m < 4; ++m) _Pragma("unroll") for (int n = 0; n < 2; ++n) _Pragma("unroll") for (int k = 0; k < 2; ++k) \
;         acc[ai][bj][m][n] = __builtin_amdgcn_mfma_f32_16x16x32_bf16(Bt[n][k], At[m][k], acc[ai][bj][m][n], 0, 0, 0); __builtin_amdgcn_s_setprio(0); } while (0)
; #define PG8_WAIT_V(n) asm volatile("s_waitcnt vmcnt(" #n ")" ::: "memory")
; #define PG8_WAIT_L(n) asm volatile("s_waitcnt lgkmcnt(" #n ")" ::: "memory")
; template <class Epi, class Ptrs>
; __device__ __forceinline__ void gemm_phase(LAS unsigned char* lds, const int K, const StaticOrder& S, const Ptrs& P, const Epi& E) {
;     ...
;         for (int t = 0; t < nt; t += 2) {
;             const bool last = (t == nt - 2);
;             const char* a1 = cA + (size_t)(t + 1) * kstep;
;             const char* a2 = last ? nA : cA + (size_t)(t + 2) * kstep; const char* b2 = last ? nB : cB + (size_t)(t + 2) * kstep;
;             const char* a3 = a2 + kstep; const char* b3 = b2 + kstep;
;             PG8_LDB(B0, 0, 0); PG8_SCHED; PG8_LDA(At, 0, 0); PG8_STAGE(PG8_SA(1, 1), a1 + hstep, voffA);
;             PG8_WAIT_L(8); PG8_BAR; PG8_WAIT_L(0); PG8_MMA(0, 0, At, B0); PG8_BAR; PG8_SCHED;
;             PG8_LDB(B1, 0, 1); PG8_STAGE(PG8_SB(0, 0), b2, voffB);
;             PG8_BAR; PG8_WAIT_L(0); PG8_MMA(0, 1, At, B1); PG8_BAR;
;             PG8_LDA(At, 0, 1); PG8_STAGE(PG8_SA(0, 0), a2, voffA);
;             PG8_BAR; PG8_WAIT_L(0); PG8_MMA(1, 0, At, B0); PG8_BAR; PG8_SCHED;
;             PG8_STAGE(PG8_SB(0, 1), b2 + hstep, voffB);
;             PG8_WAIT_V(6); PG8_BAR; PG8_MMA(1, 1, At, B1); PG8_BAR;
.LBB0_521:
	s_add_u32 s20, s20, 0x100080
	s_addc_u32 s21, s21, 0
	s_add_u32 s11, s22, 0x100
	s_addc_u32 s13, s23, 0
	s_mov_b32 s46, -2
	v_add_u32_e32 v252, 0x18000, v187
	v_add_u32_e32 v253, 0x1c000, v187
	ds_read_b128 v[128:131], v193
	ds_read_b128 v[132:135], v193 offset:1024
	ds_read_b128 v[136:139], v193 offset:2048
	ds_read_b128 v[140:143], v193 offset:3072
	s_add_u32 s22, s20, 0xfff00080
	s_addc_u32 s23, s21, -1
	s_cmp_eq_u32 s46, 60
	s_cselect_b32 s25, s5, s23
	s_cselect_b32 s24, s4, s22
	s_cselect_b32 s23, s15, s13
	s_cselect_b32 s22, s14, s11
	s_add_i32 m0, s17, 0xc000
	ds_read_b128 v[144:147], v194
	ds_read_b128 v[148:151], v194 offset:1024
	ds_read_b128 v[152:155], v194 offset:2048
	ds_read_b128 v[156:159], v194 offset:3072
	ds_read_b128 v[176:179], v194 offset:4096
	ds_read_b128 v[180:183], v194 offset:5120
	ds_read_b128 v[196:199], v194 offset:6144
	ds_read_b128 v[200:203], v194 offset:7168
	global_load_lds_dwordx4 v168, s[20:21]
	s_add_i32 m0, s17, 0xe000
	s_nop 0
	global_load_lds_dwordx4 v170, s[20:21]
	s_barrier
	s_waitcnt lgkmcnt(0)
	v_mfma_f32_16x16x32_bf16 v[124:127], v[128:131], v[144:147], 0
	v_mfma_f32_16x16x32_bf16 v[124:127], v[132:135], v[148:151], v[124:127]
	v_mfma_f32_16x16x32_bf16 v[120:123], v[140:143], v[148:151], 0
	v_mfma_f32_16x16x32_bf16 v[120:123], v[136:139], v[144:147], v[120:123]
	v_mfma_f32_16x16x32_bf16 v[104:107], v[136:139], v[152:155], 0
	v_mfma_f32_16x16x32_bf16 v[104:107], v[140:143], v[156:159], v[104:107]
	v_mfma_f32_16x16x32_bf16 v[112:115], v[132:135], v[156:159], 0
	v_mfma_f32_16x16x32_bf16 v[112:115], v[128:131], v[152:155], v[112:115]
	v_mfma_f32_16x16x32_bf16 v[92:95], v[128:131], v[176:179], 0
	v_mfma_f32_16x16x32_bf16 v[92:95], v[132:135], v[180:183], v[92:95]
	v_mfma_f32_16x16x32_bf16 v[88:91], v[140:143], v[180:183], 0
	v_mfma_f32_16x16x32_bf16 v[88:91], v[136:139], v[176:179], v[88:91]
	v_mfma_f32_16x16x32_bf16 v[72:75], v[136:139], v[196:199], 0
	v_mfma_f32_16x16x32_bf16 v[72:75], v[140:143], v[200:203], v[72:75]
	v_mfma_f32_16x16x32_bf16 v[76:79], v[132:135], v[200:203], 0
	v_mfma_f32_16x16x32_bf16 v[76:79], v[128:131], v[196:199], v[76:79]
	s_barrier
	s_add_i32 s47, s42, s34
	s_add_u32 s90, s22, 0x80
	s_addc_u32 s91, s23, 0
	s_mov_b32 m0, s47
	ds_read_b128 v[204:207], v195
	ds_read_b128 v[208:211], v195 offset:1024
	ds_read_b128 v[212:215], v195 offset:2048
	ds_read_b128 v[216:219], v195 offset:3072
	global_load_lds_dwordx4 v162, s[22:23]
	s_add_i32 m0, s47, 0x2000
	s_nop 0
	global_load_lds_dwordx4 v166, s[22:23]
	s_barrier
	s_waitcnt lgkmcnt(0)
	v_mfma_f32_16x16x32_bf16 v[116:119], v[204:207], v[144:147], 0
	v_mfma_f32_16x16x32_bf16 v[116:119], v[208:211], v[148:151], v[116:119]
	v_mfma_f32_16x16x32_bf16 v[108:111], v[216:219], v[148:151], 0
	v_mfma_f32_16x16x32_bf16 v[108:111], v[212:215], v[144:147], v[108:111]
	v_mfma_f32_16x16x32_bf16 v[96:99], v[212:215], v[152:155], 0
	v_mfma_f32_16x16x32_bf16 v[96:99], v[216:219], v[156:159], v[96:99]
	v_mfma_f32_16x16x32_bf16 v[100:103], v[208:211], v[156:159], 0
	v_mfma_f32_16x16x32_bf16 v[100:103], v[204:207], v[152:155], v[100:103]
	v_mfma_f32_16x16x32_bf16 v[84:87], v[204:207], v[176:179], 0
	v_mfma_f32_16x16x32_bf16 v[84:87], v[208:211], v[180:183], v[84:87]
	v_mfma_f32_16x16x32_bf16 v[80:83], v[216:219], v[180:183], 0
	v_mfma_f32_16x16x32_bf16 v[80:83], v[212:215], v[176:179], v[80:83]
	v_mfma_f32_16x16x32_bf16 v[64:67], v[212:215], v[196:199], 0
	v_mfma_f32_16x16x32_bf16 v[64:67], v[216:219], v[200:203], v[64:67]
	v_mfma_f32_16x16x32_bf16 v[68:71], v[208:211], v[200:203], 0
	v_mfma_f32_16x16x32_bf16 v[68:71], v[204:207], v[196:199], v[68:71]
	s_barrier
	s_mov_b32 m0, s17
	s_add_u32 s92, s24, 0x80
	s_addc_u32 s93, s25, 0
	ds_read_b128 v[144:147], v194 offset:16384
	ds_read_b128 v[148:151], v194 offset:17408
	ds_read_b128 v[152:155], v194 offset:18432
	ds_read_b128 v[156:159], v194 offset:19456
	ds_read_b128 v[176:179], v194 offset:20480
	ds_read_b128 v[180:183], v194 offset:21504
	ds_read_b128 v[196:199], v194 offset:22528
	ds_read_b128 v[200:203], v194 offset:23552
	global_load_lds_dwordx4 v160, s[24:25]
	s_mov_b32 m0, s19
	s_nop 0
	global_load_lds_dwordx4 v164, s[24:25]
	s_barrier
	s_waitcnt lgkmcnt(0)
	v_mfma_f32_16x16x32_bf16 v[60:63], v[128:131], v[144:147], 0
	v_mfma_f32_16x16x32_bf16 v[60:63], v[132:135], v[148:151], v[60:63]
	v_mfma_f32_16x16x32_bf16 v[56:59], v[140:143], v[148:151], 0
	v_mfma_f32_16x16x32_bf16 v[56:59], v[136:139], v[144:147], v[56:59]
	v_mfma_f32_16x16x32_bf16 v[40:43], v[136:139], v[152:155], 0
	v_mfma_f32_16x16x32_bf16 v[40:43], v[140:143], v[156:159], v[40:43]
	v_mfma_f32_16x16x32_bf16 v[48:51], v[132:135], v[156:159], 0
	v_mfma_f32_16x16x32_bf16 v[48:51], v[128:131], v[152:155], v[48:51]
	v_mfma_f32_16x16x32_bf16 v[32:35], v[128:131], v[176:179], 0
	v_mfma_f32_16x16x32_bf16 v[32:35], v[132:135], v[180:183], v[32:35]
	v_mfma_f32_16x16x32_bf16 v[24:27], v[140:143], v[180:183], 0
	v_mfma_f32_16x16x32_bf16 v[24:27], v[136:139], v[176:179], v[24:27]
	v_mfma_f32_16x16x32_bf16 v[8:11], v[136:139], v[196:199], 0
	v_mfma_f32_16x16x32_bf16 v[8:11], v[140:143], v[200:203], v[8:11]
	v_mfma_f32_16x16x32_bf16 v[16:19], v[132:135], v[200:203], 0
	v_mfma_f32_16x16x32_bf16 v[16:19], v[128:131], v[196:199], v[16:19]
	s_barrier
	s_add_u32 s48, s22, 0x100000
	s_addc_u32 s49, s23, 0
	s_add_i32 s47, s43, s34
	s_mov_b32 m0, s47
	s_nop 0
	global_load_lds_dwordx4 v162, s[48:49]
	s_add_i32 m0, s47, 0x2000
	s_nop 0
	global_load_lds_dwordx4 v166, s[48:49]
	s_waitcnt vmcnt(6)
	s_barrier
; #define PG8_STAGE(bufoff, gbase, voff) do { _Pragma("unroll") for (int _i = 0; _i < 2; ++_i) \
;         __builtin_amdgcn_global_load_lds((const unsigned*)((const char*)(gbase) + (voff)[_i]), (LAS unsigned*)(lds + (bufoff) + ldsw + _i * 8192), 16, 0, 0); } while (0)
; #define PG8_LDA(dst, b, h) do { _Pragma("unroll") for (int m = 0; m < 4; ++m) _Pragma("unroll") for (int k = 0; k < 2; ++k) dst[m][k] = *(const LAS bf16x8*)(lds + PG8_SA(b, h) + aoff + m * 2048 + k * 1024); } while (0)
; #define PG8_LDB(dst, b, h) do { _Pragma("unroll") for (int n = 0; n < 2; ++n) _Pragma("unroll") for (int k = 0; k < 2; ++k) dst[n][k] = *(const LAS bf16x8*)(lds + PG8_SB(b, h) + boff + n * 2048 + k * 1024); } while (0)
; #define PG8_MMA(ai, bj, At, Bt) do { __builtin_amdgcn_s_setprio(1); _Pragma("unroll") for (int m = 0; m < 4; ++m) _Pragma("unroll") for (int n = 0; n < 2; ++n) _Pragma("unroll") for (int k = 0; k < 2; ++k) \
;         acc[ai][bj][m][n] = __builtin_amdgcn_mfma_f32_16x16x32_bf16(Bt[n][k], At[m][k], acc[ai][bj][m][n], 0, 0, 0); __builtin_amdgcn_s_setprio(0); } while (0)
; #define PG8_WAIT_V(n) asm volatile("s_waitcnt vmcnt(" #n ")" ::: "memory")
; #define PG8_WAIT_L(n) asm volatile("s_waitcnt lgkmcnt(" #n ")" ::: "memory")
; #define PG8_BAR __builtin_amdgcn_s_barrier()
; #define PG8_SCHED __builtin_amdgcn_sched_barrier(0)
; template <class Epi, class Ptrs>
; __device__ __forceinline__ void gemm_phase(LAS unsigned char* lds, const int K, const StaticOrder& S, const Ptrs& P, const Epi& E) {
;     ...
;             PG8_WAIT_V(6); PG8_BAR; PG8_MMA(1, 1, At, B1); PG8_BAR;
;             PG8_LDB(B0, 1, 0); PG8_SCHED; PG8_LDA(At, 1, 0); PG8_STAGE(PG8_SA(0, 1), a2 + hstep, voffA);
;             PG8_WAIT_L(8); PG8_BAR; PG8_WAIT_L(0); PG8_MMA(0, 0, At, B0); PG8_BAR; PG8_SCHED;
;             PG8_LDB(B1, 1, 1); PG8_STAGE(PG8_SB(1, 0), b3, voffB);
;             PG8_BAR; PG8_WAIT_L(0); PG8_MMA(0, 1, At, B1); PG8_BAR;
;             PG8_LDA(At, 1, 1); PG8_STAGE(PG8_SA(1, 0), a3, voffA);
;             PG8_BAR; PG8_WAIT_L(0); PG8_MMA(1, 0, At, B0); PG8_BAR; PG8_SCHED;
;             PG8_STAGE(PG8_SB(1, 1), b3 + hstep, voffB);
;             PG8_WAIT_V(6); PG8_BAR; PG8_MMA(1, 1, At, B1); PG8_BAR;
	v_mfma_f32_16x16x32_bf16 v[52:55], v[204:207], v[144:147], 0
	v_mfma_f32_16x16x32_bf16 v[52:55], v[208:211], v[148:151], v[52:55]
	v_mfma_f32_16x16x32_bf16 v[44:47], v[216:219], v[148:151], 0
	v_mfma_f32_16x16x32_bf16 v[44:47], v[212:215], v[144:147], v[44:47]
	v_mfma_f32_16x16x32_bf16 v[28:31], v[212:215], v[152:155], 0
	v_mfma_f32_16x16x32_bf16 v[28:31], v[216:219], v[156:159], v[28:31]
	v_mfma_f32_16x16x32_bf16 v[36:39], v[208:211], v[156:159], 0
	v_mfma_f32_16x16x32_bf16 v[36:39], v[204:207], v[152:155], v[36:39]
	v_mfma_f32_16x16x32_bf16 v[20:23], v[204:207], v[176:179], 0
	v_mfma_f32_16x16x32_bf16 v[20:23], v[208:211], v[180:183], v[20:23]
	v_mfma_f32_16x16x32_bf16 v[12:15], v[216:219], v[180:183], 0
	v_mfma_f32_16x16x32_bf16 v[12:15], v[212:215], v[176:179], v[12:15]
	v_mfma_f32_16x16x32_bf16 v[0:3], v[212:215], v[196:199], 0
	v_mfma_f32_16x16x32_bf16 v[0:3], v[216:219], v[200:203], v[0:3]
	v_mfma_f32_16x16x32_bf16 v[4:7], v[208:211], v[200:203], 0
	v_mfma_f32_16x16x32_bf16 v[4:7], v[204:207], v[196:199], v[4:7]
	s_barrier
	s_add_i32 s47, 0, 0x18000
	ds_read_b128 v[128:131], v252
	ds_read_b128 v[132:135], v252 offset:1024
	ds_read_b128 v[136:139], v252 offset:2048
	ds_read_b128 v[140:143], v252 offset:3072
	s_add_u32 s24, s24, 0x100000
	s_addc_u32 s25, s25, 0
	s_mov_b32 m0, s40
	ds_read_b128 v[144:147], v194 offset:32768
	ds_read_b128 v[148:151], v194 offset:33792
	ds_read_b128 v[152:155], v194 offset:34816
	ds_read_b128 v[156:159], v194 offset:35840
	ds_read_b128 v[176:179], v194 offset:36864
	ds_read_b128 v[180:183], v194 offset:37888
	ds_read_b128 v[196:199], v194 offset:38912
	ds_read_b128 v[200:203], v194 offset:39936
	global_load_lds_dwordx4 v160, s[24:25]
	s_mov_b32 m0, s41
	s_nop 0
	global_load_lds_dwordx4 v164, s[24:25]
	s_barrier
	s_waitcnt lgkmcnt(0)
	v_mfma_f32_16x16x32_bf16 v[124:127], v[128:131], v[144:147], v[124:127]
	v_mfma_f32_16x16x32_bf16 v[124:127], v[132:135], v[148:151], v[124:127]
	v_mfma_f32_16x16x32_bf16 v[120:123], v[140:143], v[148:151], v[120:123]
	v_mfma_f32_16x16x32_bf16 v[120:123], v[136:139], v[144:147], v[120:123]
	v_mfma_f32_16x16x32_bf16 v[104:107], v[136:139], v[152:155], v[104:107]
	v_mfma_f32_16x16x32_bf16 v[104:107], v[140:143], v[156:159], v[104:107]
	v_mfma_f32_16x16x32_bf16 v[112:115], v[132:135], v[156:159], v[112:115]
	v_mfma_f32_16x16x32_bf16 v[112:115], v[128:131], v[152:155], v[112:115]
	v_mfma_f32_16x16x32_bf16 v[92:95], v[128:131], v[176:179], v[92:95]
	v_mfma_f32_16x16x32_bf16 v[92:95], v[132:135], v[180:183], v[92:95]
	v_mfma_f32_16x16x32_bf16 v[88:91], v[140:143], v[180:183], v[88:91]
	v_mfma_f32_16x16x32_bf16 v[88:91], v[136:139], v[176:179], v[88:91]
	v_mfma_f32_16x16x32_bf16 v[72:75], v[136:139], v[196:199], v[72:75]
	v_mfma_f32_16x16x32_bf16 v[72:75], v[140:143], v[200:203], v[72:75]
	v_mfma_f32_16x16x32_bf16 v[76:79], v[132:135], v[200:203], v[76:79]
	v_mfma_f32_16x16x32_bf16 v[76:79], v[128:131], v[196:199], v[76:79]
	s_barrier
	s_add_i32 s24, 0, 0x1c000
	s_add_i32 s25, s47, s34
	s_mov_b32 m0, s25
	ds_read_b128 v[204:207], v253
	ds_read_b128 v[208:211], v253 offset:1024
	ds_read_b128 v[212:215], v253 offset:2048
	ds_read_b128 v[216:219], v253 offset:3072
	global_load_lds_dwordx4 v162, s[90:91]
	s_add_i32 m0, s25, 0x2000
	s_nop 0
	global_load_lds_dwordx4 v166, s[90:91]
	s_barrier
	s_waitcnt lgkmcnt(0)
	v_mfma_f32_16x16x32_bf16 v[116:119], v[204:207], v[144:147], v[116:119]
	v_mfma_f32_16x16x32_bf16 v[116:119], v[208:211], v[148:151], v[116:119]
	v_mfma_f32_16x16x32_bf16 v[108:111], v[216:219], v[148:151], v[108:111]
	v_mfma_f32_16x16x32_bf16 v[108:111], v[212:215], v[144:147], v[108:111]
	v_mfma_f32_16x16x32_bf16 v[96:99], v[212:215], v[152:155], v[96:99]
	v_mfma_f32_16x16x32_bf16 v[96:99], v[216:219], v[156:159], v[96:99]
	v_mfma_f32_16x16x32_bf16 v[100:103], v[208:211], v[156:159], v[100:103]
	v_mfma_f32_16x16x32_bf16 v[100:103], v[204:207], v[152:155], v[100:103]
	v_mfma_f32_16x16x32_bf16 v[84:87], v[204:207], v[176:179], v[84:87]
	v_mfma_f32_16x16x32_bf16 v[84:87], v[208:211], v[180:183], v[84:87]
	v_mfma_f32_16x16x32_bf16 v[80:83], v[216:219], v[180:183], v[80:83]
	v_mfma_f32_16x16x32_bf16 v[80:83], v[212:215], v[176:179], v[80:83]
	v_mfma_f32_16x16x32_bf16 v[64:67], v[212:215], v[196:199], v[64:67]
	v_mfma_f32_16x16x32_bf16 v[64:67], v[216:219], v[200:203], v[64:67]
	v_mfma_f32_16x16x32_bf16 v[68:71], v[208:211], v[200:203], v[68:71]
	v_mfma_f32_16x16x32_bf16 v[68:71], v[204:207], v[196:199], v[68:71]
	s_barrier
	s_mov_b32 m0, s28
	ds_read_b128 v[144:147], v194 offset:49152
	ds_read_b128 v[148:151], v194 offset:50176
	ds_read_b128 v[152:155], v194 offset:51200
	ds_read_b128 v[156:159], v194 offset:52224
	ds_read_b128 v[176:179], v194 offset:53248
	ds_read_b128 v[180:183], v194 offset:54272
	ds_read_b128 v[196:199], v194 offset:55296
	ds_read_b128 v[200:203], v194 offset:56320
	global_load_lds_dwordx4 v160, s[92:93]
	s_mov_b32 m0, s29
	s_nop 0
	global_load_lds_dwordx4 v164, s[92:93]
	s_barrier
	s_waitcnt lgkmcnt(0)
	v_mfma_f32_16x16x32_bf16 v[60:63], v[128:131], v[144:147], v[60:63]
	v_mfma_f32_16x16x32_bf16 v[60:63], v[132:135], v[148:151], v[60:63]
	v_mfma_f32_16x16x32_bf16 v[56:59], v[140:143], v[148:151], v[56:59]
	v_mfma_f32_16x16x32_bf16 v[56:59], v[136:139], v[144:147], v[56:59]
	v_mfma_f32_16x16x32_bf16 v[40:43], v[136:139], v[152:155], v[40:43]
	v_mfma_f32_16x16x32_bf16 v[40:43], v[140:143], v[156:159], v[40:43]
	v_mfma_f32_16x16x32_bf16 v[48:51], v[132:135], v[156:159], v[48:51]
	v_mfma_f32_16x16x32_bf16 v[48:51], v[128:131], v[152:155], v[48:51]
	v_mfma_f32_16x16x32_bf16 v[32:35], v[128:131], v[176:179], v[32:35]
	v_mfma_f32_16x16x32_bf16 v[32:35], v[132:135], v[180:183], v[32:35]
	v_mfma_f32_16x16x32_bf16 v[24:27], v[140:143], v[180:183], v[24:27]
	v_mfma_f32_16x16x32_bf16 v[24:27], v[136:139], v[176:179], v[24:27]
	v_mfma_f32_16x16x32_bf16 v[8:11], v[136:139], v[196:199], v[8:11]
	v_mfma_f32_16x16x32_bf16 v[8:11], v[140:143], v[200:203], v[8:11]
	v_mfma_f32_16x16x32_bf16 v[16:19], v[132:135], v[200:203], v[16:19]
	v_mfma_f32_16x16x32_bf16 v[16:19], v[128:131], v[196:199], v[16:19]
	s_barrier
; #define PG8_STAGE(bufoff, gbase, voff) do { _Pragma("unroll") for (int _i = 0; _i < 2; ++_i) \
;         __builtin_amdgcn_global_load_lds((const unsigned*)((const char*)(gbase) + (voff)[_i]), (LAS unsigned*)(lds + (bufoff) + ldsw + _i * 8192), 16, 0, 0); } while (0)
; #define PG8_LDA(dst, b, h) do { _Pragma("unroll") for (int m = 0; m < 4; ++m) _Pragma("unroll") for (int k = 0; k < 2; ++k) dst[m][k] = *(const LAS bf16x8*)(lds + PG8_SA(b, h) + aoff + m * 2048 + k * 1024); } while (0)
; #define PG8_LDB(dst, b, h) do { _Pragma("unroll") for (int n = 0; n < 2; ++n) _Pragma("unroll") for (int k = 0; k < 2; ++k) dst[n][k] = *(const LAS bf16x8*)(lds + PG8_SB(b, h) + boff + n * 2048 + k * 1024); } while (0)
; #define PG8_MMA(ai, bj, At, Bt) do { __builtin_amdgcn_s_setprio(1); _Pragma("unroll") for (int m = 0; m < 4; ++m) _Pragma("unroll") for (int n = 0; n < 2; ++n) _Pragma("unroll") for (int k = 0; k < 2; ++k) \
;         acc[ai][bj][m][n] = __builtin_amdgcn_mfma_f32_16x16x32_bf16(Bt[n][k], At[m][k], acc[ai][bj][m][n], 0, 0, 0); __builtin_amdgcn_s_setprio(0); } while (0)
; #define PG8_WAIT_V(n) asm volatile("s_waitcnt vmcnt(" #n ")" ::: "memory")
; #define PG8_WAIT_L(n) asm volatile("s_waitcnt lgkmcnt(" #n ")" ::: "memory")
; #define PG8_BAR __builtin_amdgcn_s_barrier()
; #define PG8_SCHED __builtin_amdgcn_sched_barrier(0)
; template <class Epi, class Ptrs>
; __device__ __forceinline__ void gemm_phase(LAS unsigned char* lds, const int K, const StaticOrder& S, const Ptrs& P, const Epi& E) {
;     ...
;             PG8_LDB(B0, 0, 0); PG8_SCHED; PG8_LDA(At, 0, 0); PG8_STAGE(PG8_SA(1, 1), a1 + hstep, voffA);
;             PG8_WAIT_L(8); PG8_BAR; PG8_WAIT_L(0); PG8_MMA(0, 0, At, B0); PG8_BAR; PG8_SCHED;
;             PG8_LDB(B1, 0, 1); PG8_STAGE(PG8_SB(0, 0), b2, voffB);
;             PG8_BAR; PG8_WAIT_L(0); PG8_MMA(0, 1, At, B1); PG8_BAR;
;             PG8_LDA(At, 0, 1); PG8_STAGE(PG8_SA(0, 0), a2, voffA);
;             PG8_BAR; PG8_WAIT_L(0); PG8_MMA(1, 0, At, B0); PG8_BAR; PG8_SCHED;
;     ...
;             PG8_STAGE(PG8_SB(1, 1), b3 + hstep, voffB);
;             PG8_WAIT_V(6); PG8_BAR; PG8_MMA(1, 1, At, B1); PG8_BAR;
	s_add_u32 s22, s22, 0x100080
	s_addc_u32 s23, s23, 0
	s_add_i32 s24, s24, s34
	s_mov_b32 m0, s24
	s_nop 0
	global_load_lds_dwordx4 v162, s[22:23]
	s_add_i32 m0, s24, 0x2000
	s_nop 0
	global_load_lds_dwordx4 v166, s[22:23]
	s_waitcnt vmcnt(6)
	s_barrier
	v_mfma_f32_16x16x32_bf16 v[52:55], v[204:207], v[144:147], v[52:55]
	v_mfma_f32_16x16x32_bf16 v[52:55], v[208:211], v[148:151], v[52:55]
	v_mfma_f32_16x16x32_bf16 v[44:47], v[216:219], v[148:151], v[44:47]
	v_mfma_f32_16x16x32_bf16 v[44:47], v[212:215], v[144:147], v[44:47]
	v_mfma_f32_16x16x32_bf16 v[28:31], v[212:215], v[152:155], v[28:31]
	v_mfma_f32_16x16x32_bf16 v[28:31], v[216:219], v[156:159], v[28:31]
	v_mfma_f32_16x16x32_bf16 v[36:39], v[208:211], v[156:159], v[36:39]
	v_mfma_f32_16x16x32_bf16 v[36:39], v[204:207], v[152:155], v[36:39]
	v_mfma_f32_16x16x32_bf16 v[20:23], v[204:207], v[176:179], v[20:23]
	v_mfma_f32_16x16x32_bf16 v[20:23], v[208:211], v[180:183], v[20:23]
	v_mfma_f32_16x16x32_bf16 v[12:15], v[216:219], v[180:183], v[12:15]
	v_mfma_f32_16x16x32_bf16 v[12:15], v[212:215], v[176:179], v[12:15]
	v_mfma_f32_16x16x32_bf16 v[0:3], v[212:215], v[196:199], v[0:3]
	v_mfma_f32_16x16x32_bf16 v[0:3], v[216:219], v[200:203], v[0:3]
	v_mfma_f32_16x16x32_bf16 v[4:7], v[208:211], v[200:203], v[4:7]
	v_mfma_f32_16x16x32_bf16 v[4:7], v[204:207], v[196:199], v[4:7]
	s_barrier
	s_add_i32 s46, s46, 2
	s_add_u32 s20, s20, 0x100
	s_addc_u32 s21, s21, 0
	s_add_u32 s11, s11, 0x100
	s_addc_u32 s13, s13, 0
	s_cmp_gt_u32 s46, 61
.LBB0_522:
	ds_read_b128 v[128:131], v193
	ds_read_b128 v[132:135], v193 offset:1024
	ds_read_b128 v[136:139], v193 offset:2048
	ds_read_b128 v[140:143], v193 offset:3072
	s_add_u32 s22, s20, 0xfff00080
	s_addc_u32 s23, s21, -1
	s_cmp_eq_u32 s46, 60
	s_cselect_b32 s25, s5, s23
	s_cselect_b32 s24, s4, s22
	s_cselect_b32 s23, s15, s13
	s_cselect_b32 s22, s14, s11
	s_add_i32 m0, s17, 0xc000
	ds_read_b128 v[144:147], v194
	ds_read_b128 v[148:151], v194 offset:1024
	ds_read_b128 v[152:155], v194 offset:2048
	ds_read_b128 v[156:159], v194 offset:3072
	ds_read_b128 v[176:179], v194 offset:4096
	ds_read_b128 v[180:183], v194 offset:5120
	ds_read_b128 v[196:199], v194 offset:6144
	ds_read_b128 v[200:203], v194 offset:7168
	global_load_lds_dwordx4 v168, s[20:21]
	s_add_i32 m0, s17, 0xe000
	s_nop 0
	global_load_lds_dwordx4 v170, s[20:21]
	s_barrier
	s_waitcnt lgkmcnt(0)
	v_mfma_f32_16x16x32_bf16 v[124:127], v[128:131], v[144:147], v[124:127]
	v_mfma_f32_16x16x32_bf16 v[124:127], v[132:135], v[148:151], v[124:127]
	v_mfma_f32_16x16x32_bf16 v[120:123], v[140:143], v[148:151], v[120:123]
	v_mfma_f32_16x16x32_bf16 v[120:123], v[136:139], v[144:147], v[120:123]
	v_mfma_f32_16x16x32_bf16 v[104:107], v[136:139], v[152:155], v[104:107]
	v_mfma_f32_16x16x32_bf16 v[104:107], v[140:143], v[156:159], v[104:107]
	v_mfma_f32_16x16x32_bf16 v[112:115], v[132:135], v[156:159], v[112:115]
	v_mfma_f32_16x16x32_bf16 v[112:115], v[128:131], v[152:155], v[112:115]
	v_mfma_f32_16x16x32_bf16 v[92:95], v[128:131], v[176:179], v[92:95]
	v_mfma_f32_16x16x32_bf16 v[92:95], v[132:135], v[180:183], v[92:95]
	v_mfma_f32_16x16x32_bf16 v[88:91], v[140:143], v[180:183], v[88:91]
	v_mfma_f32_16x16x32_bf16 v[88:91], v[136:139], v[176:179], v[88:91]
	v_mfma_f32_16x16x32_bf16 v[72:75], v[136:139], v[196:199], v[72:75]
	v_mfma_f32_16x16x32_bf16 v[72:75], v[140:143], v[200:203], v[72:75]
	v_mfma_f32_16x16x32_bf16 v[76:79], v[132:135], v[200:203], v[76:79]
	v_mfma_f32_16x16x32_bf16 v[76:79], v[128:131], v[196:199], v[76:79]
	s_barrier
	s_add_i32 s47, s42, s34
	s_add_u32 s90, s22, 0x80
	s_addc_u32 s91, s23, 0
	s_mov_b32 m0, s47
	ds_read_b128 v[204:207], v195
	ds_read_b128 v[208:211], v195 offset:1024
	ds_read_b128 v[212:215], v195 offset:2048
	ds_read_b128 v[216:219], v195 offset:3072
	global_load_lds_dwordx4 v162, s[22:23]
	s_add_i32 m0, s47, 0x2000
	s_nop 0
	global_load_lds_dwordx4 v166, s[22:23]
	s_barrier
	s_waitcnt lgkmcnt(0)
	v_mfma_f32_16x16x32_bf16 v[116:119], v[204:207], v[144:147], v[116:119]
	v_mfma_f32_16x16x32_bf16 v[116:119], v[208:211], v[148:151], v[116:119]
	v_mfma_f32_16x16x32_bf16 v[108:111], v[216:219], v[148:151], v[108:111]
	v_mfma_f32_16x16x32_bf16 v[108:111], v[212:215], v[144:147], v[108:111]
	v_mfma_f32_16x16x32_bf16 v[96:99], v[212:215], v[152:155], v[96:99]
	v_mfma_f32_16x16x32_bf16 v[96:99], v[216:219], v[156:159], v[96:99]
	v_mfma_f32_16x16x32_bf16 v[100:103], v[208:211], v[156:159], v[100:103]
	v_mfma_f32_16x16x32_bf16 v[100:103], v[204:207], v[152:155], v[100:103]
	v_mfma_f32_16x16x32_bf16 v[84:87], v[204:207], v[176:179], v[84:87]
	v_mfma_f32_16x16x32_bf16 v[84:87], v[208:211], v[180:183], v[84:87]
	v_mfma_f32_16x16x32_bf16 v[80:83], v[216:219], v[180:183], v[80:83]
	v_mfma_f32_16x16x32_bf16 v[80:83], v[212:215], v[176:179], v[80:83]
	v_mfma_f32_16x16x32_bf16 v[64:67], v[212:215], v[196:199], v[64:67]
	v_mfma_f32_16x16x32_bf16 v[64:67], v[216:219], v[200:203], v[64:67]
	v_mfma_f32_16x16x32_bf16 v[68:71], v[208:211], v[200:203], v[68:71]
	v_mfma_f32_16x16x32_bf16 v[68:71], v[204:207], v[196:199], v[68:71]
	s_barrier
	s_mov_b32 m0, s17
	s_add_u32 s92, s24, 0x80
	s_addc_u32 s93, s25, 0
	ds_read_b128 v[144:147], v194 offset:16384
	ds_read_b128 v[148:151], v194 offset:17408
	ds_read_b128 v[152:155], v194 offset:18432
	ds_read_b128 v[156:159], v194 offset:19456
	ds_read_b128 v[176:179], v194 offset:20480
	ds_read_b128 v[180:183], v194 offset:21504
	ds_read_b128 v[196:199], v194 offset:22528
	ds_read_b128 v[200:203], v194 offset:23552
	global_load_lds_dwordx4 v160, s[24:25]
	s_mov_b32 m0, s19
	s_nop 0
	global_load_lds_dwordx4 v164, s[24:25]
	s_barrier
; #define PG8_STAGE(bufoff, gbase, voff) do { _Pragma("unroll") for (int _i = 0; _i < 2; ++_i) \
;         __builtin_amdgcn_global_load_lds((const unsigned*)((const char*)(gbase) + (voff)[_i]), (LAS unsigned*)(lds + (bufoff) + ldsw + _i * 8192), 16, 0, 0); } while (0)
; #define PG8_LDA(dst, b, h) do { _Pragma("unroll") for (int m = 0; m < 4; ++m) _Pragma("unroll") for (int k = 0; k < 2; ++k) dst[m][k] = *(const LAS bf16x8*)(lds + PG8_SA(b, h) + aoff + m * 2048 + k * 1024); } while (0)
; #define PG8_LDB(dst, b, h) do { _Pragma("unroll") for (int n = 0; n < 2; ++n) _Pragma("unroll") for (int k = 0; k < 2; ++k) dst[n][k] = *(const LAS bf16x8*)(lds + PG8_SB(b, h) + boff + n * 2048 + k * 1024); } while (0)
; #define PG8_MMA(ai, bj, At, Bt) do { __builtin_amdgcn_s_setprio(1); _Pragma("unroll") for (int m = 0; m < 4; ++m) _Pragma("unroll") for (int n = 0; n < 2; ++n) _Pragma("unroll") for (int k = 0; k < 2; ++k) \
;         acc[ai][bj][m][n] = __builtin_amdgcn_mfma_f32_16x16x32_bf16(Bt[n][k], At[m][k], acc[ai][bj][m][n], 0, 0, 0); __builtin_amdgcn_s_setprio(0); } while (0)
; #define PG8_WAIT_V(n) asm volatile("s_waitcnt vmcnt(" #n ")" ::: "memory")
; #define PG8_WAIT_L(n) asm volatile("s_waitcnt lgkmcnt(" #n ")" ::: "memory")
; #define PG8_BAR __builtin_amdgcn_s_barrier()
; #define PG8_SCHED __builtin_amdgcn_sched_barrier(0)
; template <class Epi, class Ptrs>
; __device__ __forceinline__ void gemm_phase(LAS unsigned char* lds, const int K, const StaticOrder& S, const Ptrs& P, const Epi& E) {
;     ...
;             PG8_BAR; PG8_WAIT_L(0); PG8_MMA(1, 0, At, B0); PG8_BAR; PG8_SCHED;
;             PG8_STAGE(PG8_SB(0, 1), b2 + hstep, voffB);
;             PG8_WAIT_V(6); PG8_BAR; PG8_MMA(1, 1, At, B1); PG8_BAR;
;             PG8_LDB(B0, 1, 0); PG8_SCHED; PG8_LDA(At, 1, 0); PG8_STAGE(PG8_SA(0, 1), a2 + hstep, voffA);
;             PG8_WAIT_L(8); PG8_BAR; PG8_WAIT_L(0); PG8_MMA(0, 0, At, B0); PG8_BAR; PG8_SCHED;
;             PG8_LDB(B1, 1, 1); PG8_STAGE(PG8_SB(1, 0), b3, voffB);
;             PG8_BAR; PG8_WAIT_L(0); PG8_MMA(0, 1, At, B1); PG8_BAR;
;             PG8_LDA(At, 1, 1); PG8_STAGE(PG8_SA(1, 0), a3, voffA);
;             PG8_BAR; PG8_WAIT_L(0); PG8_MMA(1, 0, At, B0); PG8_BAR; PG8_SCHED;
	s_waitcnt lgkmcnt(0)
	v_mfma_f32_16x16x32_bf16 v[60:63], v[128:131], v[144:147], v[60:63]
	v_mfma_f32_16x16x32_bf16 v[60:63], v[132:135], v[148:151], v[60:63]
	v_mfma_f32_16x16x32_bf16 v[56:59], v[140:143], v[148:151], v[56:59]
	v_mfma_f32_16x16x32_bf16 v[56:59], v[136:139], v[144:147], v[56:59]
	v_mfma_f32_16x16x32_bf16 v[40:43], v[136:139], v[152:155], v[40:43]
	v_mfma_f32_16x16x32_bf16 v[40:43], v[140:143], v[156:159], v[40:43]
	v_mfma_f32_16x16x32_bf16 v[48:51], v[132:135], v[156:159], v[48:51]
	v_mfma_f32_16x16x32_bf16 v[48:51], v[128:131], v[152:155], v[48:51]
	v_mfma_f32_16x16x32_bf16 v[32:35], v[128:131], v[176:179], v[32:35]
	v_mfma_f32_16x16x32_bf16 v[32:35], v[132:135], v[180:183], v[32:35]
	v_mfma_f32_16x16x32_bf16 v[24:27], v[140:143], v[180:183], v[24:27]
	v_mfma_f32_16x16x32_bf16 v[24:27], v[136:139], v[176:179], v[24:27]
	v_mfma_f32_16x16x32_bf16 v[8:11], v[136:139], v[196:199], v[8:11]
	v_mfma_f32_16x16x32_bf16 v[8:11], v[140:143], v[200:203], v[8:11]
	v_mfma_f32_16x16x32_bf16 v[16:19], v[132:135], v[200:203], v[16:19]
	v_mfma_f32_16x16x32_bf16 v[16:19], v[128:131], v[196:199], v[16:19]
	s_barrier
	s_add_u32 s48, s22, 0x100000
	s_addc_u32 s49, s23, 0
	s_add_i32 s47, s43, s34
	s_mov_b32 m0, s47
	s_nop 0
	global_load_lds_dwordx4 v162, s[48:49]
	s_add_i32 m0, s47, 0x2000
	s_nop 0
	global_load_lds_dwordx4 v166, s[48:49]
	s_waitcnt vmcnt(6)
	s_barrier
	v_mfma_f32_16x16x32_bf16 v[52:55], v[204:207], v[144:147], v[52:55]
	v_mfma_f32_16x16x32_bf16 v[52:55], v[208:211], v[148:151], v[52:55]
	v_mfma_f32_16x16x32_bf16 v[44:47], v[216:219], v[148:151], v[44:47]
	v_mfma_f32_16x16x32_bf16 v[44:47], v[212:215], v[144:147], v[44:47]
	v_mfma_f32_16x16x32_bf16 v[28:31], v[212:215], v[152:155], v[28:31]
	v_mfma_f32_16x16x32_bf16 v[28:31], v[216:219], v[156:159], v[28:31]
	v_mfma_f32_16x16x32_bf16 v[36:39], v[208:211], v[156:159], v[36:39]
	v_mfma_f32_16x16x32_bf16 v[36:39], v[204:207], v[152:155], v[36:39]
	v_mfma_f32_16x16x32_bf16 v[20:23], v[204:207], v[176:179], v[20:23]
	v_mfma_f32_16x16x32_bf16 v[20:23], v[208:211], v[180:183], v[20:23]
	v_mfma_f32_16x16x32_bf16 v[12:15], v[216:219], v[180:183], v[12:15]
	v_mfma_f32_16x16x32_bf16 v[12:15], v[212:215], v[176:179], v[12:15]
	v_mfma_f32_16x16x32_bf16 v[0:3], v[212:215], v[196:199], v[0:3]
	v_mfma_f32_16x16x32_bf16 v[0:3], v[216:219], v[200:203], v[0:3]
	v_mfma_f32_16x16x32_bf16 v[4:7], v[208:211], v[200:203], v[4:7]
	v_mfma_f32_16x16x32_bf16 v[4:7], v[204:207], v[196:199], v[4:7]
	s_barrier
	s_add_i32 s47, 0, 0x18000
	ds_read_b128 v[128:131], v252
	ds_read_b128 v[132:135], v252 offset:1024
	ds_read_b128 v[136:139], v252 offset:2048
	ds_read_b128 v[140:143], v252 offset:3072
	s_add_u32 s24, s24, 0x100000
	s_addc_u32 s25, s25, 0
	s_mov_b32 m0, s40
	ds_read_b128 v[144:147], v194 offset:32768
	ds_read_b128 v[148:151], v194 offset:33792
	ds_read_b128 v[152:155], v194 offset:34816
	ds_read_b128 v[156:159], v194 offset:35840
	ds_read_b128 v[176:179], v194 offset:36864
	ds_read_b128 v[180:183], v194 offset:37888
	ds_read_b128 v[196:199], v194 offset:38912
	ds_read_b128 v[200:203], v194 offset:39936
	global_load_lds_dwordx4 v160, s[24:25]
	s_mov_b32 m0, s41
	s_nop 0
	global_load_lds_dwordx4 v164, s[24:25]
	s_barrier
	s_waitcnt lgkmcnt(0)
	v_mfma_f32_16x16x32_bf16 v[124:127], v[128:131], v[144:147], v[124:127]
	v_mfma_f32_16x16x32_bf16 v[124:127], v[132:135], v[148:151], v[124:127]
	v_mfma_f32_16x16x32_bf16 v[120:123], v[140:143], v[148:151], v[120:123]
	v_mfma_f32_16x16x32_bf16 v[120:123], v[136:139], v[144:147], v[120:123]
	v_mfma_f32_16x16x32_bf16 v[104:107], v[136:139], v[152:155], v[104:107]
	v_mfma_f32_16x16x32_bf16 v[104:107], v[140:143], v[156:159], v[104:107]
	v_mfma_f32_16x16x32_bf16 v[112:115], v[132:135], v[156:159], v[112:115]
	v_mfma_f32_16x16x32_bf16 v[112:115], v[128:131], v[152:155], v[112:115]
	v_mfma_f32_16x16x32_bf16 v[92:95], v[128:131], v[176:179], v[92:95]
	v_mfma_f32_16x16x32_bf16 v[92:95], v[132:135], v[180:183], v[92:95]
	v_mfma_f32_16x16x32_bf16 v[88:91], v[140:143], v[180:183], v[88:91]
	v_mfma_f32_16x16x32_bf16 v[88:91], v[136:139], v[176:179], v[88:91]
	v_mfma_f32_16x16x32_bf16 v[72:75], v[136:139], v[196:199], v[72:75]
	v_mfma_f32_16x16x32_bf16 v[72:75], v[140:143], v[200:203], v[72:75]
	v_mfma_f32_16x16x32_bf16 v[76:79], v[132:135], v[200:203], v[76:79]
	v_mfma_f32_16x16x32_bf16 v[76:79], v[128:131], v[196:199], v[76:79]
	s_barrier
	s_add_i32 s24, 0, 0x1c000
	s_add_i32 s25, s47, s34
	s_mov_b32 m0, s25
	ds_read_b128 v[204:207], v253
	ds_read_b128 v[208:211], v253 offset:1024
	ds_read_b128 v[212:215], v253 offset:2048
	ds_read_b128 v[216:219], v253 offset:3072
	global_load_lds_dwordx4 v162, s[90:91]
	s_add_i32 m0, s25, 0x2000
	s_nop 0
	global_load_lds_dwordx4 v166, s[90:91]
	s_barrier
	s_waitcnt lgkmcnt(0)
	v_mfma_f32_16x16x32_bf16 v[116:119], v[204:207], v[144:147], v[116:119]
	v_mfma_f32_16x16x32_bf16 v[116:119], v[208:211], v[148:151], v[116:119]
	v_mfma_f32_16x16x32_bf16 v[108:111], v[216:219], v[148:151], v[108:111]
	v_mfma_f32_16x16x32_bf16 v[108:111], v[212:215], v[144:147], v[108:111]
	v_mfma_f32_16x16x32_bf16 v[96:99], v[212:215], v[152:155], v[96:99]
	v_mfma_f32_16x16x32_bf16 v[96:99], v[216:219], v[156:159], v[96:99]
	v_mfma_f32_16x16x32_bf16 v[100:103], v[208:211], v[156:159], v[100:103]
	v_mfma_f32_16x16x32_bf16 v[100:103], v[204:207], v[152:155], v[100:103]
	v_mfma_f32_16x16x32_bf16 v[84:87], v[204:207], v[176:179], v[84:87]
	v_mfma_f32_16x16x32_bf16 v[84:87], v[208:211], v[180:183], v[84:87]
	v_mfma_f32_16x16x32_bf16 v[80:83], v[216:219], v[180:183], v[80:83]
	v_mfma_f32_16x16x32_bf16 v[80:83], v[212:215], v[176:179], v[80:83]
	v_mfma_f32_16x16x32_bf16 v[64:67], v[212:215], v[196:199], v[64:67]
	v_mfma_f32_16x16x32_bf16 v[64:67], v[216:219], v[200:203], v[64:67]
	v_mfma_f32_16x16x32_bf16 v[68:71], v[208:211], v[200:203], v[68:71]
	v_mfma_f32_16x16x32_bf16 v[68:71], v[204:207], v[196:199], v[68:71]
	s_barrier
; #define PG8_STAGE(bufoff, gbase, voff) do { _Pragma("unroll") for (int _i = 0; _i < 2; ++_i) \
;         __builtin_amdgcn_global_load_lds((const unsigned*)((const char*)(gbase) + (voff)[_i]), (LAS unsigned*)(lds + (bufoff) + ldsw + _i * 8192), 16, 0, 0); } while (0)
; #define PG8_LDA(dst, b, h) do { _Pragma("unroll") for (int m = 0; m < 4; ++m) _Pragma("unroll") for (int k = 0; k < 2; ++k) dst[m][k] = *(const LAS bf16x8*)(lds + PG8_SA(b, h) + aoff + m * 2048 + k * 1024); } while (0)
; #define PG8_MMA(ai, bj, At, Bt) do { __builtin_amdgcn_s_setprio(1); _Pragma("unroll") for (int m = 0; m < 4; ++m) _Pragma("unroll") for (int n = 0; n < 2; ++n) _Pragma("unroll") for (int k = 0; k < 2; ++k) \
;         acc[ai][bj][m][n] = __builtin_amdgcn_mfma_f32_16x16x32_bf16(Bt[n][k], At[m][k], acc[ai][bj][m][n], 0, 0, 0); __builtin_amdgcn_s_setprio(0); } while (0)
; #define PG8_WAIT_V(n) asm volatile("s_waitcnt vmcnt(" #n ")" ::: "memory")
; #define PG8_WAIT_L(n) asm volatile("s_waitcnt lgkmcnt(" #n ")" ::: "memory")
; #define PG8_BAR __builtin_amdgcn_s_barrier()
; #define PG8_SCHED __builtin_amdgcn_sched_barrier(0)
; template <class Epi, class Ptrs>
; __device__ __forceinline__ void gemm_phase(LAS unsigned char* lds, const int K, const StaticOrder& S, const Ptrs& P, const Epi& E) {
;     ...
;             PG8_LDA(At, 1, 1); PG8_STAGE(PG8_SA(1, 0), a3, voffA);
;             PG8_BAR; PG8_WAIT_L(0); PG8_MMA(1, 0, At, B0); PG8_BAR; PG8_SCHED;
;             PG8_STAGE(PG8_SB(1, 1), b3 + hstep, voffB);
;             PG8_WAIT_V(6); PG8_BAR; PG8_MMA(1, 1, At, B1); PG8_BAR;
;     __device__ __forceinline__ void operator()(const f32x4 (&acc)[2][2][4][2], const Unit& u, int ui, int wr, int wc, int fr, int fq) const {
;         const int rl0 = wr * 64 + fr, col0 = u.pn * 256 + wc * 32 + 8 * fq;
;         u32x4 xv[2][4][2];
; #pragma unroll
;         for (int ai = 0; ai < 2; ++ai)
; #pragma unroll
;             for (int m = 0; m < 4; ++m)
; #pragma unroll
;                 for (int bj = 0; bj < 2; ++bj) xv[ai][m][bj] = *(const u32x4*)(xb + (size_t)(u.pm * 256 + rl0 + ai * 128 + m * 16) * DM + col0 + bj * 128);
	s_mov_b32 m0, s28
	ds_read_b128 v[144:147], v194 offset:49152
	ds_read_b128 v[148:151], v194 offset:50176
	ds_read_b128 v[152:155], v194 offset:51200
	ds_read_b128 v[156:159], v194 offset:52224
	ds_read_b128 v[176:179], v194 offset:53248
	ds_read_b128 v[180:183], v194 offset:54272
	ds_read_b128 v[196:199], v194 offset:55296
	ds_read_b128 v[200:203], v194 offset:56320
	global_load_lds_dwordx4 v160, s[92:93]
	s_mov_b32 m0, s29
	s_nop 0
	global_load_lds_dwordx4 v164, s[92:93]
	s_barrier
	s_waitcnt lgkmcnt(0)
	v_mfma_f32_16x16x32_bf16 v[60:63], v[128:131], v[144:147], v[60:63]
	v_mfma_f32_16x16x32_bf16 v[60:63], v[132:135], v[148:151], v[60:63]
	v_mfma_f32_16x16x32_bf16 v[56:59], v[140:143], v[148:151], v[56:59]
	v_mfma_f32_16x16x32_bf16 v[56:59], v[136:139], v[144:147], v[56:59]
	v_mfma_f32_16x16x32_bf16 v[40:43], v[136:139], v[152:155], v[40:43]
	v_mfma_f32_16x16x32_bf16 v[40:43], v[140:143], v[156:159], v[40:43]
	v_mfma_f32_16x16x32_bf16 v[48:51], v[132:135], v[156:159], v[48:51]
	v_mfma_f32_16x16x32_bf16 v[48:51], v[128:131], v[152:155], v[48:51]
	v_mfma_f32_16x16x32_bf16 v[32:35], v[128:131], v[176:179], v[32:35]
	v_mfma_f32_16x16x32_bf16 v[32:35], v[132:135], v[180:183], v[32:35]
	v_mfma_f32_16x16x32_bf16 v[24:27], v[140:143], v[180:183], v[24:27]
	v_mfma_f32_16x16x32_bf16 v[24:27], v[136:139], v[176:179], v[24:27]
	v_mfma_f32_16x16x32_bf16 v[8:11], v[136:139], v[196:199], v[8:11]
	v_mfma_f32_16x16x32_bf16 v[8:11], v[140:143], v[200:203], v[8:11]
	v_mfma_f32_16x16x32_bf16 v[16:19], v[132:135], v[200:203], v[16:19]
	v_mfma_f32_16x16x32_bf16 v[16:19], v[128:131], v[196:199], v[16:19]
	s_barrier
	s_add_u32 s22, s22, 0x100080
	s_addc_u32 s23, s23, 0
	s_add_i32 s24, s24, s34
	s_mov_b32 m0, s24
	s_nop 0
	global_load_lds_dwordx4 v162, s[22:23]
	s_add_i32 m0, s24, 0x2000
	s_nop 0
	global_load_lds_dwordx4 v166, s[22:23]
	s_waitcnt vmcnt(6)
	s_barrier
	v_mfma_f32_16x16x32_bf16 v[52:55], v[204:207], v[144:147], v[52:55]
	v_mfma_f32_16x16x32_bf16 v[52:55], v[208:211], v[148:151], v[52:55]
	v_mfma_f32_16x16x32_bf16 v[44:47], v[216:219], v[148:151], v[44:47]
	v_mfma_f32_16x16x32_bf16 v[44:47], v[212:215], v[144:147], v[44:47]
	v_mfma_f32_16x16x32_bf16 v[28:31], v[212:215], v[152:155], v[28:31]
	v_mfma_f32_16x16x32_bf16 v[28:31], v[216:219], v[156:159], v[28:31]
	v_mfma_f32_16x16x32_bf16 v[36:39], v[208:211], v[156:159], v[36:39]
	v_mfma_f32_16x16x32_bf16 v[36:39], v[204:207], v[152:155], v[36:39]
	v_mfma_f32_16x16x32_bf16 v[20:23], v[204:207], v[176:179], v[20:23]
	v_mfma_f32_16x16x32_bf16 v[20:23], v[208:211], v[180:183], v[20:23]
	v_mfma_f32_16x16x32_bf16 v[12:15], v[216:219], v[180:183], v[12:15]
	v_mfma_f32_16x16x32_bf16 v[12:15], v[212:215], v[176:179], v[12:15]
	v_mfma_f32_16x16x32_bf16 v[0:3], v[212:215], v[196:199], v[0:3]
	v_mfma_f32_16x16x32_bf16 v[0:3], v[216:219], v[200:203], v[0:3]
	v_mfma_f32_16x16x32_bf16 v[4:7], v[208:211], v[200:203], v[4:7]
	v_mfma_f32_16x16x32_bf16 v[4:7], v[204:207], v[196:199], v[4:7]
	s_barrier
	s_add_i32 s46, s46, 2
	s_add_u32 s20, s20, 0x100
	s_addc_u32 s21, s21, 0
	s_add_u32 s11, s11, 0x100
	s_addc_u32 s13, s13, 0
	s_cmp_gt_u32 s46, 61
	s_cbranch_scc0 .LBB0_522
	s_lshl_b32 s11, s18, 8
	v_lshl_or_b32 v128, s16, 8, v191
	v_add_u32_e32 v130, s11, v186
	v_ashrrev_i32_e32 v129, 31, v128
	v_ashrrev_i32_e32 v131, 31, v130
	v_lshl_add_u64 v[132:133], v[128:129], 1, s[6:7]
	v_lshlrev_b64 v[134:135], 11, v[130:131]
	v_lshl_add_u64 v[134:135], v[132:133], 0, v[134:135]
	global_load_dwordx4 v[198:201], v[134:135], off
	global_load_dwordx4 v[202:205], v[134:135], off offset:256
	v_or_b32_e32 v134, 16, v130
	v_ashrrev_i32_e32 v135, 31, v134
	v_lshlrev_b64 v[134:135], 11, v[134:135]
	v_lshl_add_u64 v[134:135], v[132:133], 0, v[134:135]
	global_load_dwordx4 v[206:209], v[134:135], off
	global_load_dwordx4 v[210:213], v[134:135], off offset:256
	v_or_b32_e32 v136, 32, v130
	v_ashrrev_i32_e32 v137, 31, v136
	v_or_b32_e32 v138, 48, v130
	v_add_u32_e32 v184, 0x80, v130
	v_add_u32_e32 v182, 0x90, v130
	v_add_u32_e32 v180, 0xa0, v130
	v_add_u32_e32 v178, 0xb0, v130
	v_lshlrev_b64 v[176:177], 2, v[128:129]
	v_lshlrev_b64 v[128:129], 12, v[130:131]
	v_lshlrev_b64 v[130:131], 11, v[136:137]
	v_lshl_add_u64 v[130:131], v[132:133], 0, v[130:131]
	global_load_dwordx4 v[214:217], v[130:131], off
	v_ashrrev_i32_e32 v139, 31, v138
	v_ashrrev_i32_e32 v185, 31, v184
	v_ashrrev_i32_e32 v183, 31, v182
	v_ashrrev_i32_e32 v181, 31, v180
	v_ashrrev_i32_e32 v179, 31, v178
	v_lshlrev_b64 v[134:135], 11, v[138:139]
	v_lshlrev_b64 v[136:137], 11, v[184:185]
	v_lshlrev_b64 v[138:139], 11, v[182:183]
	v_lshl_add_u32 v196, s45, 10, v192
	v_lshlrev_b64 v[140:141], 11, v[180:181]
	v_lshlrev_b64 v[142:143], 11, v[178:179]
	v_lshl_add_u64 v[128:129], s[26:27], 0, v[128:129]
	v_lshl_add_u64 v[134:135], v[132:133], 0, v[134:135]
	v_lshl_add_u64 v[136:137], v[132:133], 0, v[136:137]
	v_lshl_add_u64 v[138:139], v[132:133], 0, v[138:139]
	ds_read2_b32 v[230:231], v196 offset1:16
	v_lshl_add_u64 v[234:235], v[132:133], 0, v[140:141]
	v_lshl_add_u64 v[236:237], v[132:133], 0, v[142:143]
	v_lshl_add_u64 v[238:239], v[128:129], 0, v[176:177]
	global_load_dwordx4 v[218:221], v[130:131], off offset:256
	global_load_dwordx4 v[222:225], v[134:135], off
	global_load_dwordx4 v[226:229], v[134:135], off offset:256
	global_load_dwordx4 v[156:159], v[136:137], off
	global_load_dwordx4 v[152:155], v[136:137], off offset:256
	global_load_dwordx4 v[148:151], v[138:139], off
	global_load_dwordx4 v[144:147], v[138:139], off offset:256
	global_load_dwordx4 v[140:143], v[234:235], off
	s_nop 0
	global_load_dwordx4 v[136:139], v[234:235], off offset:256
	global_load_dwordx4 v[132:135], v[236:237], off
	global_load_dwordx4 v[128:131], v[236:237], off offset:256
	v_add_u32_e32 v232, s11, v188
	v_ashrrev_i32_e32 v233, 31, v232
	s_and_b64 vcc, exec, s[0:1]
	s_mov_b32 s16, s10
	s_mov_b32 s18, s12
	s_mov_b64 s[20:21], s[4:5]
	s_mov_b64 s[22:23], s[14:15]
	s_mov_b32 s45, s44
	s_waitcnt vmcnt(0)
; __device__ __forceinline__ float bf_lo(unsigned w) { return __uint_as_float(w << 16); }
; __device__ __forceinline__ float bf_hi(unsigned w) { return __uint_as_float(w & 0xffff0000u); }
;     __device__ __forceinline__ void operator()(const f32x4 (&acc)[2][2][4][2], const Unit& u, int ui, int wr, int wc, int fr, int fq) const {
;     ...
; #pragma unroll
;         for (int ai = 0; ai < 2; ++ai)
; #pragma unroll
;             for (int m = 0; m < 4; ++m) { const int rl = rl0 + ai * 128 + m * 16; float* rowp = out + (size_t)(u.pm * 256 + rl) * DM + col0;
;                 const float r2 = tab[ui * 256 + rl];
; #pragma unroll
;                 for (int bj = 0; bj < 2; ++bj) { const u32x4 x = xv[ai][m][bj];
;                     const f32x4 x0 = {bf_lo(x.x), bf_hi(x.x), bf_lo(x.y), bf_hi(x.y)}, x1 = {bf_lo(x.z), bf_hi(x.z), bf_lo(x.w), bf_hi(x.w)};
;                     *(f32x4*)(rowp + bj * 128) = acc[ai][bj][m][0] * r2 + x0; *(f32x4*)(rowp + bj * 128 + 4) = acc[ai][bj][m][1] * r2 + x1; } }
	v_lshlrev_b32_e32 v234, 16, v198
	v_and_b32_e32 v235, 0xffff0000, v198
	v_lshlrev_b32_e32 v198, 16, v199
	v_and_b32_e32 v199, 0xffff0000, v199
	v_lshlrev_b32_e32 v242, 16, v204
	v_and_b32_e32 v243, 0xffff0000, v204
	v_lshlrev_b32_e32 v236, 16, v200
	v_and_b32_e32 v237, 0xffff0000, v200
	v_lshlrev_b32_e32 v200, 16, v201
	v_and_b32_e32 v201, 0xffff0000, v201
	v_lshlrev_b32_e32 v240, 16, v202
	v_and_b32_e32 v241, 0xffff0000, v202
	v_lshlrev_b32_e32 v202, 16, v203
	v_and_b32_e32 v203, 0xffff0000, v203
	v_lshlrev_b32_e32 v204, 16, v205
	v_and_b32_e32 v205, 0xffff0000, v205
	s_waitcnt lgkmcnt(0)
	v_pk_fma_f32 v[126:127], v[126:127], v[230:231], v[198:199] op_sel_hi:[1,0,1]
	v_pk_fma_f32 v[124:125], v[124:125], v[230:231], v[234:235] op_sel_hi:[1,0,1]
	v_pk_fma_f32 v[108:109], v[108:109], v[230:231], v[242:243] op_sel_hi:[1,0,1]
	v_pk_fma_f32 v[122:123], v[122:123], v[230:231], v[200:201] op_sel_hi:[1,0,1]
	v_pk_fma_f32 v[120:121], v[120:121], v[230:231], v[236:237] op_sel_hi:[1,0,1]
	v_pk_fma_f32 v[118:119], v[118:119], v[230:231], v[202:203] op_sel_hi:[1,0,1]
	v_pk_fma_f32 v[116:117], v[116:117], v[230:231], v[240:241] op_sel_hi:[1,0,1]
	v_pk_fma_f32 v[110:111], v[110:111], v[230:231], v[204:205] op_sel_hi:[1,0,1]
	global_store_dwordx4 v[238:239], v[124:127], off
	global_store_dwordx4 v[238:239], v[120:123], off offset:16
	global_store_dwordx4 v[238:239], v[116:119], off offset:512
	global_store_dwordx4 v[238:239], v[108:111], off offset:528
	v_mov_b32_e32 v122, v231
	v_lshlrev_b32_e32 v118, 16, v208
	v_lshlrev_b64 v[108:109], 12, v[232:233]
	v_lshl_add_u64 v[108:109], s[26:27], 0, v[108:109]
	v_lshl_add_u64 v[116:117], v[108:109], 0, v[176:177]
	v_lshlrev_b32_e32 v108, 16, v206
	v_and_b32_e32 v109, 0xffff0000, v206
	v_lshlrev_b32_e32 v110, 16, v207
	v_and_b32_e32 v111, 0xffff0000, v207
	v_pk_fma_f32 v[110:111], v[114:115], v[122:123], v[110:111] op_sel_hi:[1,0,1]
	v_pk_fma_f32 v[108:109], v[112:113], v[122:123], v[108:109] op_sel_hi:[1,0,1]
	global_store_dwordx4 v[116:117], v[108:111], off
	v_and_b32_e32 v119, 0xffff0000, v208
	v_lshlrev_b32_e32 v120, 16, v209
	v_lshlrev_b32_e32 v108, 16, v212
	v_and_b32_e32 v109, 0xffff0000, v212
	v_lshlrev_b32_e32 v110, 16, v213
	v_and_b32_e32 v111, 0xffff0000, v213
	v_pk_fma_f32 v[98:99], v[98:99], v[122:123], v[110:111] op_sel_hi:[1,0,1]
	v_pk_fma_f32 v[96:97], v[96:97], v[122:123], v[108:109] op_sel_hi:[1,0,1]
	v_and_b32_e32 v121, 0xffff0000, v209
	global_store_dwordx4 v[116:117], v[96:99], off offset:528
	ds_read2_b32 v[98:99], v196 offset0:32 offset1:48
	v_pk_fma_f32 v[106:107], v[106:107], v[122:123], v[120:121] op_sel_hi:[1,0,1]
	v_pk_fma_f32 v[104:105], v[104:105], v[122:123], v[118:119] op_sel_hi:[1,0,1]
	v_add_u32_e32 v96, s11, v189
	global_store_dwordx4 v[116:117], v[104:107], off offset:16
	v_ashrrev_i32_e32 v97, 31, v96
	v_lshlrev_b64 v[96:97], 12, v[96:97]
	v_lshlrev_b32_e32 v104, 16, v210
	v_and_b32_e32 v105, 0xffff0000, v210
	v_lshlrev_b32_e32 v106, 16, v211
	v_and_b32_e32 v107, 0xffff0000, v211
	v_pk_fma_f32 v[102:103], v[102:103], v[122:123], v[106:107] op_sel_hi:[1,0,1]
	v_pk_fma_f32 v[100:101], v[100:101], v[122:123], v[104:105] op_sel_hi:[1,0,1]
	global_store_dwordx4 v[116:117], v[100:103], off offset:512
	v_lshl_add_u64 v[96:97], s[26:27], 0, v[96:97]
	v_lshl_add_u64 v[96:97], v[96:97], 0, v[176:177]
	v_lshlrev_b32_e32 v100, 16, v214
	v_and_b32_e32 v101, 0xffff0000, v214
	v_lshlrev_b32_e32 v102, 16, v215
	v_and_b32_e32 v103, 0xffff0000, v215
	s_waitcnt lgkmcnt(0)
	v_pk_fma_f32 v[94:95], v[94:95], v[98:99], v[102:103] op_sel_hi:[1,0,1]
	v_pk_fma_f32 v[92:93], v[92:93], v[98:99], v[100:101] op_sel_hi:[1,0,1]
	global_store_dwordx4 v[96:97], v[92:95], off
	v_lshlrev_b32_e32 v104, 16, v216
	v_and_b32_e32 v105, 0xffff0000, v216
	v_lshlrev_b32_e32 v92, 16, v220
	v_and_b32_e32 v93, 0xffff0000, v220
	v_lshlrev_b32_e32 v94, 16, v221
	v_and_b32_e32 v95, 0xffff0000, v221
	v_lshlrev_b32_e32 v106, 16, v217
	v_and_b32_e32 v107, 0xffff0000, v217
	v_pk_fma_f32 v[82:83], v[82:83], v[98:99], v[94:95] op_sel_hi:[1,0,1]
	v_pk_fma_f32 v[80:81], v[80:81], v[98:99], v[92:93] op_sel_hi:[1,0,1]
	v_pk_fma_f32 v[90:91], v[90:91], v[98:99], v[106:107] op_sel_hi:[1,0,1]
	v_pk_fma_f32 v[88:89], v[88:89], v[98:99], v[104:105] op_sel_hi:[1,0,1]
	global_store_dwordx4 v[96:97], v[80:83], off offset:528
	global_store_dwordx4 v[96:97], v[88:91], off offset:16
	s_nop 0
	v_add_u32_e32 v80, s11, v190
	v_lshlrev_b32_e32 v88, 16, v218
	v_and_b32_e32 v89, 0xffff0000, v218
	v_lshlrev_b32_e32 v90, 16, v219
	v_and_b32_e32 v91, 0xffff0000, v219
	v_ashrrev_i32_e32 v81, 31, v80
	v_pk_fma_f32 v[86:87], v[86:87], v[98:99], v[90:91] op_sel_hi:[1,0,1]
	v_pk_fma_f32 v[84:85], v[84:85], v[98:99], v[88:89] op_sel_hi:[1,0,1]
	v_lshlrev_b64 v[80:81], 12, v[80:81]
	global_store_dwordx4 v[96:97], v[84:87], off offset:512
	v_lshl_add_u64 v[80:81], s[26:27], 0, v[80:81]
	v_lshlrev_b32_e32 v82, 16, v222
	v_and_b32_e32 v83, 0xffff0000, v222
	v_lshlrev_b32_e32 v84, 16, v223
	v_and_b32_e32 v85, 0xffff0000, v223
	v_mov_b32_e32 v90, v99
	v_lshl_add_u64 v[80:81], v[80:81], 0, v[176:177]
	v_pk_fma_f32 v[78:79], v[78:79], v[90:91], v[84:85] op_sel_hi:[1,0,1]
	v_pk_fma_f32 v[76:77], v[76:77], v[90:91], v[82:83] op_sel_hi:[1,0,1]
	global_store_dwordx4 v[80:81], v[76:79], off
	v_lshlrev_b32_e32 v86, 16, v224
	v_and_b32_e32 v87, 0xffff0000, v224
	v_lshlrev_b32_e32 v76, 16, v228
	v_and_b32_e32 v77, 0xffff0000, v228
	v_lshlrev_b32_e32 v78, 16, v229
	v_and_b32_e32 v79, 0xffff0000, v229
	v_pk_fma_f32 v[66:67], v[66:67], v[90:91], v[78:79] op_sel_hi:[1,0,1]
	v_pk_fma_f32 v[64:65], v[64:65], v[90:91], v[76:77] op_sel_hi:[1,0,1]
	v_lshlrev_b32_e32 v88, 16, v225
	v_and_b32_e32 v89, 0xffff0000, v225
	global_store_dwordx4 v[80:81], v[64:67], off offset:528
	ds_read2_b32 v[66:67], v196 offset0:128 offset1:144
	v_pk_fma_f32 v[74:75], v[74:75], v[90:91], v[88:89] op_sel_hi:[1,0,1]
	v_pk_fma_f32 v[72:73], v[72:73], v[90:91], v[86:87] op_sel_hi:[1,0,1]
	global_store_dwordx4 v[80:81], v[72:75], off offset:16
	v_lshlrev_b64 v[64:65], 12, v[184:185]
	v_lshl_add_u64 v[64:65], s[26:27], 0, v[64:65]
	v_lshlrev_b32_e32 v72, 16, v226
	v_and_b32_e32 v73, 0xffff0000, v226
	v_lshlrev_b32_e32 v74, 16, v227
	v_and_b32_e32 v75, 0xffff0000, v227
	v_pk_fma_f32 v[70:71], v[70:71], v[90:91], v[74:75] op_sel_hi:[1,0,1]
	v_pk_fma_f32 v[68:69], v[68:69], v[90:91], v[72:73] op_sel_hi:[1,0,1]
	global_store_dwordx4 v[80:81], v[68:71], off offset:512
	v_lshl_add_u64 v[64:65], v[64:65], 0, v[176:177]
	v_lshlrev_b32_e32 v72, 16, v158
	v_lshlrev_b32_e32 v68, 16, v156
	v_and_b32_e32 v69, 0xffff0000, v156
	v_lshlrev_b32_e32 v70, 16, v157
	v_and_b32_e32 v71, 0xffff0000, v157
	v_and_b32_e32 v73, 0xffff0000, v158
	v_lshlrev_b32_e32 v74, 16, v159
	v_and_b32_e32 v75, 0xffff0000, v159
	s_waitcnt lgkmcnt(0)
; __device__ __forceinline__ float bf_lo(unsigned w) { return __uint_as_float(w << 16); }
; __device__ __forceinline__ float bf_hi(unsigned w) { return __uint_as_float(w & 0xffff0000u); }
; #define PG8_WAIT_V(n) asm volatile("s_waitcnt vmcnt(" #n ")" ::: "memory")
; #define PG8_BAR __builtin_amdgcn_s_barrier()
; template <class Epi, class Ptrs>
; __device__ __forceinline__ void gemm_phase(LAS unsigned char* lds, const int K, const StaticOrder& S, const Ptrs& P, const Epi& E) {
;     ...
;         if (!has_next) break;
; #pragma unroll
;         for (int a = 0; a < 2; ++a)
; #pragma unroll
;             for (int b = 0; b < 2; ++b)
; #pragma unroll
;                 for (int m = 0; m < 4; ++m)
; #pragma unroll
;                     for (int n = 0; n < 2; ++n) acc[a][b][m][n] = (f32x4){0.f, 0.f, 0.f, 0.f};
;         cur = nxt; cA = nA; cB = nB; ++ui;
;     }
;     PG8_WAIT_V(0);
;     if (wr == 0) PG8_BAR;
;     PG8_BAR;
;     __device__ __forceinline__ void operator()(const f32x4 (&acc)[2][2][4][2], const Unit& u, int ui, int wr, int wc, int fr, int fq) const {
;     ...
; #pragma unroll
;         for (int ai = 0; ai < 2; ++ai)
; #pragma unroll
;             for (int m = 0; m < 4; ++m) { const int rl = rl0 + ai * 128 + m * 16; float* rowp = out + (size_t)(u.pm * 256 + rl) * DM + col0;
;                 const float r2 = tab[ui * 256 + rl];
; #pragma unroll
;                 for (int bj = 0; bj < 2; ++bj) { const u32x4 x = xv[ai][m][bj];
;                     const f32x4 x0 = {bf_lo(x.x), bf_hi(x.x), bf_lo(x.y), bf_hi(x.y)}, x1 = {bf_lo(x.z), bf_hi(x.z), bf_lo(x.w), bf_hi(x.w)};
;                     *(f32x4*)(rowp + bj * 128) = acc[ai][bj][m][0] * r2 + x0; *(f32x4*)(rowp + bj * 128 + 4) = acc[ai][bj][m][1] * r2 + x1; } }
	v_pk_fma_f32 v[62:63], v[62:63], v[66:67], v[70:71] op_sel_hi:[1,0,1]
	v_pk_fma_f32 v[60:61], v[60:61], v[66:67], v[68:69] op_sel_hi:[1,0,1]
	global_store_dwordx4 v[64:65], v[60:63], off
	v_pk_fma_f32 v[58:59], v[58:59], v[66:67], v[74:75] op_sel_hi:[1,0,1]
	v_pk_fma_f32 v[56:57], v[56:57], v[66:67], v[72:73] op_sel_hi:[1,0,1]
	v_lshlrev_b32_e32 v60, 16, v154
	v_and_b32_e32 v61, 0xffff0000, v154
	v_lshlrev_b32_e32 v62, 16, v155
	v_and_b32_e32 v63, 0xffff0000, v155
	global_store_dwordx4 v[64:65], v[56:59], off offset:16
	v_pk_fma_f32 v[46:47], v[46:47], v[66:67], v[62:63] op_sel_hi:[1,0,1]
	v_pk_fma_f32 v[44:45], v[44:45], v[66:67], v[60:61] op_sel_hi:[1,0,1]
	v_lshlrev_b32_e32 v56, 16, v152
	v_and_b32_e32 v57, 0xffff0000, v152
	v_lshlrev_b32_e32 v58, 16, v153
	v_and_b32_e32 v59, 0xffff0000, v153
	v_pk_fma_f32 v[54:55], v[54:55], v[66:67], v[58:59] op_sel_hi:[1,0,1]
	v_pk_fma_f32 v[52:53], v[52:53], v[66:67], v[56:57] op_sel_hi:[1,0,1]
	global_store_dwordx4 v[64:65], v[44:47], off offset:528
	global_store_dwordx4 v[64:65], v[52:55], off offset:512
	v_lshlrev_b32_e32 v56, 16, v151
	v_lshlrev_b64 v[44:45], 12, v[182:183]
	v_lshl_add_u64 v[44:45], s[26:27], 0, v[44:45]
	v_lshlrev_b32_e32 v54, 16, v150
	v_and_b32_e32 v55, 0xffff0000, v150
	v_and_b32_e32 v57, 0xffff0000, v151
	v_mov_b32_e32 v58, v67
	v_lshl_add_u64 v[52:53], v[44:45], 0, v[176:177]
	v_pk_fma_f32 v[42:43], v[42:43], v[58:59], v[56:57] op_sel_hi:[1,0,1]
	v_pk_fma_f32 v[40:41], v[40:41], v[58:59], v[54:55] op_sel_hi:[1,0,1]
	v_lshlrev_b32_e32 v44, 16, v148
	v_and_b32_e32 v45, 0xffff0000, v148
	v_lshlrev_b32_e32 v46, 16, v149
	v_and_b32_e32 v47, 0xffff0000, v149
	global_store_dwordx4 v[52:53], v[40:43], off offset:16
	v_pk_fma_f32 v[46:47], v[50:51], v[58:59], v[46:47] op_sel_hi:[1,0,1]
	v_pk_fma_f32 v[44:45], v[48:49], v[58:59], v[44:45] op_sel_hi:[1,0,1]
	v_lshlrev_b32_e32 v40, 16, v144
	v_and_b32_e32 v41, 0xffff0000, v144
	v_lshlrev_b32_e32 v42, 16, v145
	v_and_b32_e32 v43, 0xffff0000, v145
	v_pk_fma_f32 v[38:39], v[38:39], v[58:59], v[42:43] op_sel_hi:[1,0,1]
	v_pk_fma_f32 v[36:37], v[36:37], v[58:59], v[40:41] op_sel_hi:[1,0,1]
	global_store_dwordx4 v[52:53], v[44:47], off
	global_store_dwordx4 v[52:53], v[36:39], off offset:512
	ds_read2_b32 v[38:39], v196 offset0:160 offset1:176
	v_lshlrev_b32_e32 v44, 16, v146
	v_and_b32_e32 v45, 0xffff0000, v146
	v_lshlrev_b32_e32 v46, 16, v147
	v_and_b32_e32 v47, 0xffff0000, v147
	v_pk_fma_f32 v[30:31], v[30:31], v[58:59], v[46:47] op_sel_hi:[1,0,1]
	v_pk_fma_f32 v[28:29], v[28:29], v[58:59], v[44:45] op_sel_hi:[1,0,1]
	global_store_dwordx4 v[52:53], v[28:31], off offset:528
	v_lshlrev_b32_e32 v40, 16, v142
	v_and_b32_e32 v41, 0xffff0000, v142
	v_lshlrev_b64 v[28:29], 12, v[180:181]
	v_lshl_add_u64 v[28:29], s[26:27], 0, v[28:29]
	v_lshl_add_u64 v[36:37], v[28:29], 0, v[176:177]
	v_lshlrev_b32_e32 v28, 16, v140
	v_and_b32_e32 v29, 0xffff0000, v140
	v_lshlrev_b32_e32 v30, 16, v141
	v_and_b32_e32 v31, 0xffff0000, v141
	s_waitcnt lgkmcnt(0)
	v_pk_fma_f32 v[30:31], v[34:35], v[38:39], v[30:31] op_sel_hi:[1,0,1]
	v_pk_fma_f32 v[28:29], v[32:33], v[38:39], v[28:29] op_sel_hi:[1,0,1]
	v_lshlrev_b32_e32 v42, 16, v143
	v_and_b32_e32 v43, 0xffff0000, v143
	global_store_dwordx4 v[36:37], v[28:31], off
	v_pk_fma_f32 v[26:27], v[26:27], v[38:39], v[42:43] op_sel_hi:[1,0,1]
	v_pk_fma_f32 v[24:25], v[24:25], v[38:39], v[40:41] op_sel_hi:[1,0,1]
	v_lshlrev_b32_e32 v28, 16, v138
	v_and_b32_e32 v29, 0xffff0000, v138
	v_lshlrev_b32_e32 v30, 16, v139
	v_and_b32_e32 v31, 0xffff0000, v139
	v_pk_fma_f32 v[14:15], v[14:15], v[38:39], v[30:31] op_sel_hi:[1,0,1]
	v_pk_fma_f32 v[12:13], v[12:13], v[38:39], v[28:29] op_sel_hi:[1,0,1]
	global_store_dwordx4 v[36:37], v[24:27], off offset:16
	global_store_dwordx4 v[36:37], v[12:15], off offset:528
	s_nop 0
	v_lshlrev_b32_e32 v24, 16, v136
	v_and_b32_e32 v25, 0xffff0000, v136
	v_lshlrev_b32_e32 v26, 16, v137
	v_and_b32_e32 v27, 0xffff0000, v137
	v_lshlrev_b64 v[12:13], 12, v[178:179]
	v_pk_fma_f32 v[22:23], v[22:23], v[38:39], v[26:27] op_sel_hi:[1,0,1]
	v_pk_fma_f32 v[20:21], v[20:21], v[38:39], v[24:25] op_sel_hi:[1,0,1]
	v_lshl_add_u64 v[12:13], s[26:27], 0, v[12:13]
	global_store_dwordx4 v[36:37], v[20:23], off offset:512
	v_lshlrev_b32_e32 v14, 16, v133
	v_and_b32_e32 v15, 0xffff0000, v133
	v_lshl_add_u64 v[20:21], v[12:13], 0, v[176:177]
	v_lshlrev_b32_e32 v12, 16, v132
	v_and_b32_e32 v13, 0xffff0000, v132
	v_lshlrev_b32_e32 v22, 16, v134
	v_and_b32_e32 v23, 0xffff0000, v134
	v_lshlrev_b32_e32 v24, 16, v135
	v_and_b32_e32 v25, 0xffff0000, v135
	v_mov_b32_e32 v26, v39
	v_pk_fma_f32 v[14:15], v[18:19], v[26:27], v[14:15] op_sel_hi:[1,0,1]
	v_pk_fma_f32 v[12:13], v[16:17], v[26:27], v[12:13] op_sel_hi:[1,0,1]
	v_pk_fma_f32 v[10:11], v[10:11], v[26:27], v[24:25] op_sel_hi:[1,0,1]
	v_pk_fma_f32 v[8:9], v[8:9], v[26:27], v[22:23] op_sel_hi:[1,0,1]
	global_store_dwordx4 v[20:21], v[12:15], off
	global_store_dwordx4 v[20:21], v[8:11], off offset:16
	s_nop 0
	v_lshlrev_b32_e32 v12, 16, v130
	v_lshlrev_b32_e32 v8, 16, v128
	v_and_b32_e32 v9, 0xffff0000, v128
	v_lshlrev_b32_e32 v10, 16, v129
	v_and_b32_e32 v11, 0xffff0000, v129
	v_and_b32_e32 v13, 0xffff0000, v130
	v_lshlrev_b32_e32 v14, 16, v131
	v_and_b32_e32 v15, 0xffff0000, v131
	v_pk_fma_f32 v[6:7], v[6:7], v[26:27], v[10:11] op_sel_hi:[1,0,1]
	v_pk_fma_f32 v[4:5], v[4:5], v[26:27], v[8:9] op_sel_hi:[1,0,1]
	v_pk_fma_f32 v[2:3], v[2:3], v[26:27], v[14:15] op_sel_hi:[1,0,1]
	v_pk_fma_f32 v[0:1], v[0:1], v[26:27], v[12:13] op_sel_hi:[1,0,1]
	global_store_dwordx4 v[20:21], v[4:7], off offset:512
	global_store_dwordx4 v[20:21], v[0:3], off offset:528
	s_cbranch_vccz .LBB0_517
	s_waitcnt vmcnt(0)
	s_setprio 0
	s_cmpk_gt_u32 s33, 0xff
	s_cbranch_scc1 .LBB0_526
	s_barrier
